# baseline (speedup 1.0000x reference)
; #define LDA(dst, b, h)                                                                                     \
;   _Pragma("unroll") for (int m = 0; m < 4; ++m) _Pragma("unroll") for (int k = 0; k < 2; ++k) dst[m][k] = \
;       *reinterpret_cast<const bf16x8*>(shmc + aL + (((b) * 2 + (h)) * 16384 + (m * 2 + k) * 1024))
; #define LDB(dst, b, h)                                                                                     \
;   _Pragma("unroll") for (int n = 0; n < 2; ++n) _Pragma("unroll") for (int k = 0; k < 2; ++k) dst[n][k] = \
;       *reinterpret_cast<const bf16x8*>(shmc + bL + (((b) * 2 + (h)) * 16384 + (n * 2 + k) * 1024))
; #define OPAQ asm volatile("" : "+v"(aL), "+v"(bL))
; #define WAIT_V(n) asm volatile("s_waitcnt vmcnt(" #n ")" ::: "memory")
; #define WAIT_L(n) asm volatile("s_waitcnt lgkmcnt(" #n ")" ::: "memory")
; #define BAR __builtin_amdgcn_s_barrier()
; #define SCHED __builtin_amdgcn_sched_barrier(0)
; template <int EPI>
; __device__ __forceinline__ void phase_gemm(const Params& p, const GemmDesc& d, char* shmc) {
;     ...
;       OPAQ;
;       LDB(B0, 0, 0); SCHED; LDA(At, 0, 0); STAGE_A(SA(1, 1), 1, t + 1);
;       WAIT_L(8); BAR; WAIT_L(0); MMA(0, 0, At, B0); BAR; SCHED;
;       LDB(B1, 0, 1); STAGE_B(SB(0, 0), 0, t + 2);
;       BAR; WAIT_L(0); MMA(0, 1, At, B1); BAR;
;       LDA(At, 0, 1); STAGE_A(SA(0, 0), 0, t + 2);
;       BAR; WAIT_L(0); MMA(1, 0, At, B0); BAR; SCHED;
;       STAGE_B(SB(0, 1), 1, t + 2);
;       WAIT_V(6); BAR; MMA(1, 1, At, B1); BAR;
.LBB0_296:
	s_nop 0
	v_add_u32_e32 v162, 0, v205
	v_add_u32_e32 v175, 0, v204
	s_setprio 0
	ds_read_b128 v[138:141], v162
	ds_read_b128 v[142:145], v162 offset:1024
	ds_read_b128 v[146:149], v162 offset:2048
	ds_read_b128 v[150:153], v162 offset:3072
	ds_read_b128 v[208:211], v162 offset:16384
	ds_read_b128 v[212:215], v162 offset:17408
	ds_read_b128 v[216:219], v162 offset:18432
	ds_read_b128 v[220:223], v162 offset:19456
	ds_read_b128 v[154:157], v175
	ds_read_b128 v[158:161], v175 offset:1024
	ds_read_b128 v[178:181], v175 offset:2048
	ds_read_b128 v[182:185], v175 offset:3072
	ds_read_b128 v[186:189], v175 offset:4096
	ds_read_b128 v[190:193], v175 offset:5120
	ds_read_b128 v[194:197], v175 offset:6144
	ds_read_b128 v[198:201], v175 offset:7168
	s_mov_b32 m0, s93
	s_nop 0
	global_load_lds_dwordx4 v202, s[98:99]
	s_mov_b32 m0, s94
	s_nop 0
	global_load_lds_dwordx4 v203, s[98:99]
	s_waitcnt vmcnt(8) lgkmcnt(0)
	s_setprio 1
	s_barrier
	v_mfma_f32_16x16x32_bf16 v[2:5], v[154:157], v[138:141], v[2:5]
	v_mfma_f32_16x16x32_bf16 v[6:9], v[154:157], v[146:149], v[6:9]
	v_mfma_f32_16x16x32_bf16 v[10:13], v[178:181], v[138:141], v[10:13]
	v_mfma_f32_16x16x32_bf16 v[18:21], v[178:181], v[146:149], v[18:21]
	v_mfma_f32_16x16x32_bf16 v[30:33], v[186:189], v[138:141], v[30:33]
	v_mfma_f32_16x16x32_bf16 v[42:45], v[186:189], v[146:149], v[42:45]
	v_mfma_f32_16x16x32_bf16 v[54:57], v[194:197], v[138:141], v[54:57]
	v_mfma_f32_16x16x32_bf16 v[66:69], v[194:197], v[146:149], v[66:69]
	v_mfma_f32_16x16x32_bf16 v[2:5], v[158:161], v[142:145], v[2:5]
	v_mfma_f32_16x16x32_bf16 v[6:9], v[158:161], v[150:153], v[6:9]
	v_mfma_f32_16x16x32_bf16 v[10:13], v[182:185], v[142:145], v[10:13]
	v_mfma_f32_16x16x32_bf16 v[18:21], v[182:185], v[150:153], v[18:21]
	v_mfma_f32_16x16x32_bf16 v[30:33], v[190:193], v[142:145], v[30:33]
	v_mfma_f32_16x16x32_bf16 v[42:45], v[190:193], v[150:153], v[42:45]
	v_mfma_f32_16x16x32_bf16 v[54:57], v[198:201], v[142:145], v[54:57]
	v_mfma_f32_16x16x32_bf16 v[66:69], v[198:201], v[150:153], v[66:69]
	v_mfma_f32_16x16x32_bf16 v[14:17], v[154:157], v[208:211], v[14:17]
	v_mfma_f32_16x16x32_bf16 v[22:25], v[154:157], v[216:219], v[22:25]
	v_mfma_f32_16x16x32_bf16 v[34:37], v[178:181], v[208:211], v[34:37]
	v_mfma_f32_16x16x32_bf16 v[46:49], v[178:181], v[216:219], v[46:49]
	v_mfma_f32_16x16x32_bf16 v[58:61], v[186:189], v[208:211], v[58:61]
	v_mfma_f32_16x16x32_bf16 v[70:73], v[186:189], v[216:219], v[70:73]
	v_mfma_f32_16x16x32_bf16 v[78:81], v[194:197], v[208:211], v[78:81]
	v_mfma_f32_16x16x32_bf16 v[86:89], v[194:197], v[216:219], v[86:89]
	v_mfma_f32_16x16x32_bf16 v[14:17], v[158:161], v[212:215], v[14:17]
	v_mfma_f32_16x16x32_bf16 v[22:25], v[158:161], v[220:223], v[22:25]
	v_mfma_f32_16x16x32_bf16 v[34:37], v[182:185], v[212:215], v[34:37]
	v_mfma_f32_16x16x32_bf16 v[46:49], v[182:185], v[220:223], v[46:49]
	v_mfma_f32_16x16x32_bf16 v[58:61], v[190:193], v[212:215], v[58:61]
	v_mfma_f32_16x16x32_bf16 v[70:73], v[190:193], v[220:223], v[70:73]
	v_mfma_f32_16x16x32_bf16 v[78:81], v[198:201], v[212:215], v[78:81]
	v_mfma_f32_16x16x32_bf16 v[86:89], v[198:201], v[220:223], v[86:89]
	s_barrier
	s_setprio 0
	ds_read_b128 v[154:157], v175 offset:16384
	ds_read_b128 v[158:161], v175 offset:17408
	ds_read_b128 v[178:181], v175 offset:18432
	ds_read_b128 v[182:185], v175 offset:19456
	ds_read_b128 v[186:189], v175 offset:20480
	ds_read_b128 v[190:193], v175 offset:21504
	ds_read_b128 v[194:197], v175 offset:22528
	ds_read_b128 v[198:201], v175 offset:23552
	s_mov_b32 m0, s80
	s_nop 0
	global_load_lds_dwordx4 v224, s[100:101]
	s_mov_b32 m0, s81
	s_nop 0
	global_load_lds_dwordx4 v225, s[100:101]
	s_mov_b32 m0, s77
	s_nop 0
	global_load_lds_dwordx4 v226, s[98:99]
	s_mov_b32 m0, s82
	s_nop 0
	global_load_lds_dwordx4 v227, s[98:99]
	s_mov_b32 m0, s83
	s_nop 0
	global_load_lds_dwordx4 v228, s[100:101]
	s_mov_b32 m0, s84
	s_nop 0
	global_load_lds_dwordx4 v229, s[100:101]
	s_waitcnt vmcnt(8) lgkmcnt(0)
	s_setprio 1
	s_barrier
	v_mfma_f32_16x16x32_bf16 v[26:29], v[154:157], v[138:141], v[26:29]
	v_mfma_f32_16x16x32_bf16 v[38:41], v[154:157], v[146:149], v[38:41]
	v_mfma_f32_16x16x32_bf16 v[50:53], v[178:181], v[138:141], v[50:53]
	v_mfma_f32_16x16x32_bf16 v[62:65], v[178:181], v[146:149], v[62:65]
	v_mfma_f32_16x16x32_bf16 v[74:77], v[186:189], v[138:141], v[74:77]
	v_mfma_f32_16x16x32_bf16 v[82:85], v[186:189], v[146:149], v[82:85]
	v_mfma_f32_16x16x32_bf16 v[90:93], v[194:197], v[138:141], v[90:93]
	v_mfma_f32_16x16x32_bf16 v[94:97], v[194:197], v[146:149], v[94:97]
	v_mfma_f32_16x16x32_bf16 v[26:29], v[158:161], v[142:145], v[26:29]
	v_mfma_f32_16x16x32_bf16 v[38:41], v[158:161], v[150:153], v[38:41]
	v_mfma_f32_16x16x32_bf16 v[50:53], v[182:185], v[142:145], v[50:53]
	v_mfma_f32_16x16x32_bf16 v[62:65], v[182:185], v[150:153], v[62:65]
	v_mfma_f32_16x16x32_bf16 v[74:77], v[190:193], v[142:145], v[74:77]
	v_mfma_f32_16x16x32_bf16 v[82:85], v[190:193], v[150:153], v[82:85]
	v_mfma_f32_16x16x32_bf16 v[90:93], v[198:201], v[142:145], v[90:93]
	v_mfma_f32_16x16x32_bf16 v[94:97], v[198:201], v[150:153], v[94:97]
	v_mfma_f32_16x16x32_bf16 v[98:101], v[154:157], v[208:211], v[98:101]
	v_mfma_f32_16x16x32_bf16 v[102:105], v[154:157], v[216:219], v[102:105]
	v_mfma_f32_16x16x32_bf16 v[106:109], v[178:181], v[208:211], v[106:109]
	v_mfma_f32_16x16x32_bf16 v[110:113], v[178:181], v[216:219], v[110:113]
	v_mfma_f32_16x16x32_bf16 v[114:117], v[186:189], v[208:211], v[114:117]
	v_mfma_f32_16x16x32_bf16 v[118:121], v[186:189], v[216:219], v[118:121]
	v_mfma_f32_16x16x32_bf16 v[122:125], v[194:197], v[208:211], v[122:125]
	v_mfma_f32_16x16x32_bf16 v[126:129], v[194:197], v[216:219], v[126:129]
	v_mfma_f32_16x16x32_bf16 v[98:101], v[158:161], v[212:215], v[98:101]
	v_mfma_f32_16x16x32_bf16 v[102:105], v[158:161], v[220:223], v[102:105]
	v_mfma_f32_16x16x32_bf16 v[106:109], v[182:185], v[212:215], v[106:109]
	v_mfma_f32_16x16x32_bf16 v[110:113], v[182:185], v[220:223], v[110:113]
	v_mfma_f32_16x16x32_bf16 v[114:117], v[190:193], v[212:215], v[114:117]
	v_mfma_f32_16x16x32_bf16 v[118:121], v[190:193], v[220:223], v[118:121]
	v_mfma_f32_16x16x32_bf16 v[122:125], v[198:201], v[212:215], v[122:125]
	v_mfma_f32_16x16x32_bf16 v[126:129], v[198:201], v[220:223], v[126:129]
	s_barrier
; #define LDA(dst, b, h)                                                                                     \
;   _Pragma("unroll") for (int m = 0; m < 4; ++m) _Pragma("unroll") for (int k = 0; k < 2; ++k) dst[m][k] = \
;       *reinterpret_cast<const bf16x8*>(shmc + aL + (((b) * 2 + (h)) * 16384 + (m * 2 + k) * 1024))
; #define LDB(dst, b, h)                                                                                     \
;   _Pragma("unroll") for (int n = 0; n < 2; ++n) _Pragma("unroll") for (int k = 0; k < 2; ++k) dst[n][k] = \
;       *reinterpret_cast<const bf16x8*>(shmc + bL + (((b) * 2 + (h)) * 16384 + (n * 2 + k) * 1024))
; #define WAIT_V(n) asm volatile("s_waitcnt vmcnt(" #n ")" ::: "memory")
; #define WAIT_L(n) asm volatile("s_waitcnt lgkmcnt(" #n ")" ::: "memory")
; #define BAR __builtin_amdgcn_s_barrier()
; #define SCHED __builtin_amdgcn_sched_barrier(0)
; template <int EPI>
; __device__ __forceinline__ void phase_gemm(const Params& p, const GemmDesc& d, char* shmc) {
;     ...
;       LDB(B0, 1, 0); SCHED; LDA(At, 1, 0); STAGE_A(SA(0, 1), 1, t + 2);
;       WAIT_L(8); BAR; WAIT_L(0); MMA(0, 0, At, B0); BAR; SCHED;
;       LDB(B1, 1, 1); STAGE_B(SB(1, 0), 0, t + 3);
;       BAR; WAIT_L(0); MMA(0, 1, At, B1); BAR;
;       LDA(At, 1, 1); STAGE_A(SA(1, 0), 0, t + 3);
;       BAR; WAIT_L(0); MMA(1, 0, At, B0); BAR; SCHED;
;       STAGE_B(SB(1, 1), 1, t + 3);
;       WAIT_V(6); BAR; MMA(1, 1, At, B1); BAR;
;     }
	s_setprio 0
	ds_read_b128 v[138:141], v162 offset:32768
	ds_read_b128 v[142:145], v162 offset:33792
	ds_read_b128 v[146:149], v162 offset:34816
	ds_read_b128 v[150:153], v162 offset:35840
	ds_read_b128 v[208:211], v162 offset:49152
	ds_read_b128 v[212:215], v162 offset:50176
	ds_read_b128 v[216:219], v162 offset:51200
	ds_read_b128 v[220:223], v162 offset:52224
	ds_read_b128 v[154:157], v175 offset:32768
	ds_read_b128 v[158:161], v175 offset:33792
	ds_read_b128 v[178:181], v175 offset:34816
	ds_read_b128 v[182:185], v175 offset:35840
	ds_read_b128 v[186:189], v175 offset:36864
	ds_read_b128 v[190:193], v175 offset:37888
	ds_read_b128 v[194:197], v175 offset:38912
	ds_read_b128 v[198:201], v175 offset:39936
	s_mov_b32 m0, s85
	s_nop 0
	global_load_lds_dwordx4 v230, s[98:99]
	s_mov_b32 m0, s86
	s_nop 0
	global_load_lds_dwordx4 v231, s[98:99]
	s_waitcnt vmcnt(8) lgkmcnt(0)
	s_setprio 1
	s_barrier
	v_mfma_f32_16x16x32_bf16 v[2:5], v[154:157], v[138:141], v[2:5]
	v_mfma_f32_16x16x32_bf16 v[6:9], v[154:157], v[146:149], v[6:9]
	v_mfma_f32_16x16x32_bf16 v[10:13], v[178:181], v[138:141], v[10:13]
	v_mfma_f32_16x16x32_bf16 v[18:21], v[178:181], v[146:149], v[18:21]
	v_mfma_f32_16x16x32_bf16 v[30:33], v[186:189], v[138:141], v[30:33]
	v_mfma_f32_16x16x32_bf16 v[42:45], v[186:189], v[146:149], v[42:45]
	v_mfma_f32_16x16x32_bf16 v[54:57], v[194:197], v[138:141], v[54:57]
	v_mfma_f32_16x16x32_bf16 v[66:69], v[194:197], v[146:149], v[66:69]
	v_mfma_f32_16x16x32_bf16 v[2:5], v[158:161], v[142:145], v[2:5]
	v_mfma_f32_16x16x32_bf16 v[6:9], v[158:161], v[150:153], v[6:9]
	v_mfma_f32_16x16x32_bf16 v[10:13], v[182:185], v[142:145], v[10:13]
	v_mfma_f32_16x16x32_bf16 v[18:21], v[182:185], v[150:153], v[18:21]
	v_mfma_f32_16x16x32_bf16 v[30:33], v[190:193], v[142:145], v[30:33]
	v_mfma_f32_16x16x32_bf16 v[42:45], v[190:193], v[150:153], v[42:45]
	v_mfma_f32_16x16x32_bf16 v[54:57], v[198:201], v[142:145], v[54:57]
	v_mfma_f32_16x16x32_bf16 v[66:69], v[198:201], v[150:153], v[66:69]
	v_mfma_f32_16x16x32_bf16 v[14:17], v[154:157], v[208:211], v[14:17]
	v_mfma_f32_16x16x32_bf16 v[22:25], v[154:157], v[216:219], v[22:25]
	v_mfma_f32_16x16x32_bf16 v[34:37], v[178:181], v[208:211], v[34:37]
	v_mfma_f32_16x16x32_bf16 v[46:49], v[178:181], v[216:219], v[46:49]
	v_mfma_f32_16x16x32_bf16 v[58:61], v[186:189], v[208:211], v[58:61]
	v_mfma_f32_16x16x32_bf16 v[70:73], v[186:189], v[216:219], v[70:73]
	v_mfma_f32_16x16x32_bf16 v[78:81], v[194:197], v[208:211], v[78:81]
	v_mfma_f32_16x16x32_bf16 v[86:89], v[194:197], v[216:219], v[86:89]
	v_mfma_f32_16x16x32_bf16 v[14:17], v[158:161], v[212:215], v[14:17]
	v_mfma_f32_16x16x32_bf16 v[22:25], v[158:161], v[220:223], v[22:25]
	v_mfma_f32_16x16x32_bf16 v[34:37], v[182:185], v[212:215], v[34:37]
	v_mfma_f32_16x16x32_bf16 v[46:49], v[182:185], v[220:223], v[46:49]
	v_mfma_f32_16x16x32_bf16 v[58:61], v[190:193], v[212:215], v[58:61]
	v_mfma_f32_16x16x32_bf16 v[70:73], v[190:193], v[220:223], v[70:73]
	v_mfma_f32_16x16x32_bf16 v[78:81], v[198:201], v[212:215], v[78:81]
	v_mfma_f32_16x16x32_bf16 v[86:89], v[198:201], v[220:223], v[86:89]
	s_barrier
	s_setprio 0
	ds_read_b128 v[154:157], v175 offset:49152
	ds_read_b128 v[158:161], v175 offset:50176
	ds_read_b128 v[178:181], v175 offset:51200
	ds_read_b128 v[182:185], v175 offset:52224
	ds_read_b128 v[186:189], v175 offset:53248
	ds_read_b128 v[190:193], v175 offset:54272
	ds_read_b128 v[194:197], v175 offset:55296
	ds_read_b128 v[198:201], v175 offset:56320
	s_mov_b32 m0, s87
	s_nop 0
	global_load_lds_dwordx4 v232, s[100:101]
	s_mov_b32 m0, s88
	s_nop 0
	global_load_lds_dwordx4 v233, s[100:101]
	s_mov_b32 m0, s89
	s_nop 0
	global_load_lds_dwordx4 v234, s[98:99]
	s_mov_b32 m0, s90
	s_nop 0
	global_load_lds_dwordx4 v235, s[98:99]
	s_mov_b32 m0, s91
	s_nop 0
	global_load_lds_dwordx4 v236, s[100:101]
	s_mov_b32 m0, s92
	s_nop 0
	global_load_lds_dwordx4 v237, s[100:101]
	s_add_i32 s35, s35, 2
	s_add_u32 s10, s10, 0x100
	s_addc_u32 s11, s11, 0
	s_add_u32 s98, s98, 0x100
	s_addc_u32 s99, s99, 0
	s_add_u32 s100, s100, 0x100
	s_addc_u32 s101, s101, 0
	s_cmp_gt_u32 s35, 27
	s_waitcnt vmcnt(8) lgkmcnt(0)
	s_setprio 1
	s_barrier
	v_mfma_f32_16x16x32_bf16 v[26:29], v[154:157], v[138:141], v[26:29]
	v_mfma_f32_16x16x32_bf16 v[38:41], v[154:157], v[146:149], v[38:41]
	v_mfma_f32_16x16x32_bf16 v[50:53], v[178:181], v[138:141], v[50:53]
	v_mfma_f32_16x16x32_bf16 v[62:65], v[178:181], v[146:149], v[62:65]
	v_mfma_f32_16x16x32_bf16 v[74:77], v[186:189], v[138:141], v[74:77]
	v_mfma_f32_16x16x32_bf16 v[82:85], v[186:189], v[146:149], v[82:85]
	v_mfma_f32_16x16x32_bf16 v[90:93], v[194:197], v[138:141], v[90:93]
	v_mfma_f32_16x16x32_bf16 v[94:97], v[194:197], v[146:149], v[94:97]
	v_mfma_f32_16x16x32_bf16 v[26:29], v[158:161], v[142:145], v[26:29]
	v_mfma_f32_16x16x32_bf16 v[38:41], v[158:161], v[150:153], v[38:41]
	v_mfma_f32_16x16x32_bf16 v[50:53], v[182:185], v[142:145], v[50:53]
	v_mfma_f32_16x16x32_bf16 v[62:65], v[182:185], v[150:153], v[62:65]
	v_mfma_f32_16x16x32_bf16 v[74:77], v[190:193], v[142:145], v[74:77]
	v_mfma_f32_16x16x32_bf16 v[82:85], v[190:193], v[150:153], v[82:85]
	v_mfma_f32_16x16x32_bf16 v[90:93], v[198:201], v[142:145], v[90:93]
	v_mfma_f32_16x16x32_bf16 v[94:97], v[198:201], v[150:153], v[94:97]
	v_mfma_f32_16x16x32_bf16 v[98:101], v[154:157], v[208:211], v[98:101]
	v_mfma_f32_16x16x32_bf16 v[102:105], v[154:157], v[216:219], v[102:105]
	v_mfma_f32_16x16x32_bf16 v[106:109], v[178:181], v[208:211], v[106:109]
	v_mfma_f32_16x16x32_bf16 v[110:113], v[178:181], v[216:219], v[110:113]
	v_mfma_f32_16x16x32_bf16 v[114:117], v[186:189], v[208:211], v[114:117]
	v_mfma_f32_16x16x32_bf16 v[118:121], v[186:189], v[216:219], v[118:121]
	v_mfma_f32_16x16x32_bf16 v[122:125], v[194:197], v[208:211], v[122:125]
	v_mfma_f32_16x16x32_bf16 v[126:129], v[194:197], v[216:219], v[126:129]
	v_mfma_f32_16x16x32_bf16 v[98:101], v[158:161], v[212:215], v[98:101]
	v_mfma_f32_16x16x32_bf16 v[102:105], v[158:161], v[220:223], v[102:105]
	v_mfma_f32_16x16x32_bf16 v[106:109], v[182:185], v[212:215], v[106:109]
	v_mfma_f32_16x16x32_bf16 v[110:113], v[182:185], v[220:223], v[110:113]
	v_mfma_f32_16x16x32_bf16 v[114:117], v[190:193], v[212:215], v[114:117]
	v_mfma_f32_16x16x32_bf16 v[118:121], v[190:193], v[220:223], v[118:121]
	v_mfma_f32_16x16x32_bf16 v[122:125], v[198:201], v[212:215], v[122:125]
	v_mfma_f32_16x16x32_bf16 v[126:129], v[198:201], v[220:223], v[126:129]
	s_barrier
; #define LDA(dst, b, h)                                                                                     \
;   _Pragma("unroll") for (int m = 0; m < 4; ++m) _Pragma("unroll") for (int k = 0; k < 2; ++k) dst[m][k] = \
;       *reinterpret_cast<const bf16x8*>(shmc + aL + (((b) * 2 + (h)) * 16384 + (m * 2 + k) * 1024))
; #define LDB(dst, b, h)                                                                                     \
;   _Pragma("unroll") for (int n = 0; n < 2; ++n) _Pragma("unroll") for (int k = 0; k < 2; ++k) dst[n][k] = \
;       *reinterpret_cast<const bf16x8*>(shmc + bL + (((b) * 2 + (h)) * 16384 + (n * 2 + k) * 1024))
; #define OPAQ asm volatile("" : "+v"(aL), "+v"(bL))
; #define WAIT_V(n) asm volatile("s_waitcnt vmcnt(" #n ")" ::: "memory")
; #define WAIT_L(n) asm volatile("s_waitcnt lgkmcnt(" #n ")" ::: "memory")
; #define BAR __builtin_amdgcn_s_barrier()
; template <int EPI>
; __device__ __forceinline__ void phase_gemm(const Params& p, const GemmDesc& d, char* shmc) {
;     ...
;     {
;       OPAQ;
;       LDB(B0, 0, 0); LDA(At, 0, 0); STAGE_A(SA(1, 1), 1, nt - 1);
;       BAR; WAIT_L(0); MMA(0, 0, At, B0); BAR;
;       LDB(B1, 0, 1); BAR; WAIT_L(0); MMA(0, 1, At, B1); BAR;
;       LDA(At, 0, 1); WAIT_V(4); BAR; WAIT_L(0); MMA(1, 0, At, B0); MMA(1, 1, At, B1); BAR;
;     }
	s_cbranch_scc0 .LBB0_296
	s_setprio 0
	s_add_u32 s8, s8, 0x80f80
	s_addc_u32 s9, s9, 0
	v_add_u32_e32 v162, 0, v205
	v_add_u32_e32 v175, 0, v204
	s_mov_b32 m0, s93
	ds_read_b128 v[130:133], v162
	ds_read_b128 v[134:137], v162 offset:1024
	ds_read_b128 v[138:141], v162 offset:2048
	ds_read_b128 v[142:145], v162 offset:3072
	ds_read_b128 v[146:149], v175
	ds_read_b128 v[150:153], v175 offset:1024
	ds_read_b128 v[154:157], v175 offset:2048
	ds_read_b128 v[158:161], v175 offset:3072
	ds_read_b128 v[178:181], v175 offset:4096
	ds_read_b128 v[182:185], v175 offset:5120
	ds_read_b128 v[186:189], v175 offset:6144
	ds_read_b128 v[190:193], v175 offset:7168
	global_load_lds_dwordx4 v174, s[8:9]
	s_mov_b32 m0, s94
	s_nop 0
	global_load_lds_dwordx4 v176, s[8:9]
	s_waitcnt vmcnt(8)
	s_barrier
	s_waitcnt lgkmcnt(0)
	s_setprio 1
	s_waitcnt lgkmcnt(0)
	v_mfma_f32_16x16x32_bf16 v[2:5], v[146:149], v[130:133], v[2:5]
	v_mfma_f32_16x16x32_bf16 v[6:9], v[146:149], v[138:141], v[6:9]
	v_mfma_f32_16x16x32_bf16 v[10:13], v[154:157], v[130:133], v[10:13]
	v_mfma_f32_16x16x32_bf16 v[18:21], v[154:157], v[138:141], v[18:21]
	v_mfma_f32_16x16x32_bf16 v[66:69], v[186:189], v[138:141], v[66:69]
	v_mfma_f32_16x16x32_bf16 v[2:5], v[150:153], v[134:137], v[2:5]
	v_mfma_f32_16x16x32_bf16 v[6:9], v[150:153], v[142:145], v[6:9]
	v_mfma_f32_16x16x32_bf16 v[10:13], v[158:161], v[134:137], v[10:13]
	v_mfma_f32_16x16x32_bf16 v[18:21], v[158:161], v[142:145], v[18:21]
	v_mfma_f32_16x16x32_bf16 v[30:33], v[178:181], v[130:133], v[30:33]
	v_mfma_f32_16x16x32_bf16 v[42:45], v[178:181], v[138:141], v[42:45]
	v_mfma_f32_16x16x32_bf16 v[54:57], v[186:189], v[130:133], v[54:57]
	v_mfma_f32_16x16x32_bf16 v[66:69], v[190:193], v[142:145], v[66:69]
	v_mfma_f32_16x16x32_bf16 v[30:33], v[182:185], v[134:137], v[30:33]
	v_mfma_f32_16x16x32_bf16 v[42:45], v[182:185], v[142:145], v[42:45]
	v_mfma_f32_16x16x32_bf16 v[54:57], v[190:193], v[134:137], v[54:57]
	s_setprio 0
	s_barrier
	ds_read_b128 v[194:197], v162 offset:16384
	ds_read_b128 v[198:201], v162 offset:17408
	ds_read_b128 v[208:211], v162 offset:18432
	ds_read_b128 v[212:215], v162 offset:19456
	s_barrier
	s_waitcnt lgkmcnt(0)
	s_setprio 1
	s_waitcnt lgkmcnt(0)
	v_mfma_f32_16x16x32_bf16 v[14:17], v[146:149], v[194:197], v[14:17]
	v_mfma_f32_16x16x32_bf16 v[22:25], v[146:149], v[208:211], v[22:25]
	v_mfma_f32_16x16x32_bf16 v[58:61], v[178:181], v[194:197], v[58:61]
	v_mfma_f32_16x16x32_bf16 v[14:17], v[150:153], v[198:201], v[14:17]
	v_mfma_f32_16x16x32_bf16 v[22:25], v[150:153], v[212:215], v[22:25]
	v_mfma_f32_16x16x32_bf16 v[150:153], v[182:185], v[198:201], v[58:61]
	v_mfma_f32_16x16x32_bf16 v[58:61], v[178:181], v[208:211], v[70:73]
	v_mfma_f32_16x16x32_bf16 v[34:37], v[154:157], v[194:197], v[34:37]
	v_mfma_f32_16x16x32_bf16 v[46:49], v[154:157], v[208:211], v[46:49]
	v_mfma_f32_16x16x32_bf16 v[154:157], v[182:185], v[212:215], v[58:61]
	v_mfma_f32_16x16x32_bf16 v[58:61], v[186:189], v[194:197], v[78:81]
	v_mfma_f32_16x16x32_bf16 v[78:81], v[190:193], v[198:201], v[58:61]
	v_mfma_f32_16x16x32_bf16 v[58:61], v[186:189], v[208:211], v[86:89]
	v_mfma_f32_16x16x32_bf16 v[86:89], v[190:193], v[212:215], v[58:61]
	v_mfma_f32_16x16x32_bf16 v[34:37], v[158:161], v[198:201], v[34:37]
	v_mfma_f32_16x16x32_bf16 v[46:49], v[158:161], v[212:215], v[46:49]
	s_setprio 0
	s_barrier
	s_nop 2
	ds_read_b128 v[58:61], v175 offset:16384
	ds_read_b128 v[70:73], v175 offset:17408
	ds_read_b128 v[146:149], v175 offset:18432
	ds_read_b128 v[158:161], v175 offset:19456
	ds_read_b128 v[178:181], v175 offset:20480
	ds_read_b128 v[182:185], v175 offset:21504
	ds_read_b128 v[186:189], v175 offset:22528
	ds_read_b128 v[190:193], v175 offset:23552
	s_waitcnt vmcnt(4)
	s_barrier
	s_waitcnt lgkmcnt(0)
	s_setprio 1
	s_waitcnt lgkmcnt(0)
	v_mfma_f32_16x16x32_bf16 v[74:77], v[178:181], v[130:133], v[74:77]
	v_mfma_f32_16x16x32_bf16 v[216:219], v[182:185], v[134:137], v[74:77]
	v_mfma_f32_16x16x32_bf16 v[74:77], v[178:181], v[138:141], v[82:85]
	v_mfma_f32_16x16x32_bf16 v[26:29], v[58:61], v[130:133], v[26:29]
	v_mfma_f32_16x16x32_bf16 v[82:85], v[182:185], v[142:145], v[74:77]
	v_mfma_f32_16x16x32_bf16 v[74:77], v[186:189], v[130:133], v[90:93]
	v_mfma_f32_16x16x32_bf16 v[26:29], v[70:73], v[134:137], v[26:29]
	v_mfma_f32_16x16x32_bf16 v[38:41], v[58:61], v[138:141], v[38:41]
	v_mfma_f32_16x16x32_bf16 v[50:53], v[146:149], v[130:133], v[50:53]
	v_mfma_f32_16x16x32_bf16 v[62:65], v[146:149], v[138:141], v[62:65]
	v_mfma_f32_16x16x32_bf16 v[90:93], v[190:193], v[134:137], v[74:77]
	v_mfma_f32_16x16x32_bf16 v[74:77], v[186:189], v[138:141], v[94:97]
	v_mfma_f32_16x16x32_bf16 v[38:41], v[70:73], v[142:145], v[38:41]
	v_mfma_f32_16x16x32_bf16 v[50:53], v[158:161], v[134:137], v[50:53]
	v_mfma_f32_16x16x32_bf16 v[62:65], v[158:161], v[142:145], v[62:65]
	v_mfma_f32_16x16x32_bf16 v[220:223], v[190:193], v[142:145], v[74:77]
	s_setprio 0
	s_setprio 1
	v_mfma_f32_16x16x32_bf16 v[74:77], v[58:61], v[194:197], v[98:101]
	v_mfma_f32_16x16x32_bf16 v[58:61], v[58:61], v[208:211], v[102:105]
	v_mfma_f32_16x16x32_bf16 v[228:231], v[70:73], v[212:215], v[58:61]
	v_mfma_f32_16x16x32_bf16 v[58:61], v[146:149], v[194:197], v[106:109]
	v_mfma_f32_16x16x32_bf16 v[232:235], v[158:161], v[198:201], v[58:61]
	v_mfma_f32_16x16x32_bf16 v[58:61], v[146:149], v[208:211], v[110:113]
	v_mfma_f32_16x16x32_bf16 v[236:239], v[158:161], v[212:215], v[58:61]
	v_mfma_f32_16x16x32_bf16 v[58:61], v[178:181], v[194:197], v[114:117]
	v_mfma_f32_16x16x32_bf16 v[240:243], v[182:185], v[198:201], v[58:61]
	v_mfma_f32_16x16x32_bf16 v[58:61], v[178:181], v[208:211], v[118:121]
	v_mfma_f32_16x16x32_bf16 v[178:181], v[182:185], v[212:215], v[58:61]
	v_mfma_f32_16x16x32_bf16 v[58:61], v[186:189], v[194:197], v[122:125]
	v_mfma_f32_16x16x32_bf16 v[182:185], v[190:193], v[198:201], v[58:61]
	v_mfma_f32_16x16x32_bf16 v[58:61], v[186:189], v[208:211], v[126:129]
	v_mfma_f32_16x16x32_bf16 v[224:227], v[70:73], v[198:201], v[74:77]
	v_mfma_f32_16x16x32_bf16 v[186:189], v[190:193], v[212:215], v[58:61]
	s_setprio 0
	s_barrier
; #define LDA(dst, b, h)                                                                                     \
;   _Pragma("unroll") for (int m = 0; m < 4; ++m) _Pragma("unroll") for (int k = 0; k < 2; ++k) dst[m][k] = \
;       *reinterpret_cast<const bf16x8*>(shmc + aL + (((b) * 2 + (h)) * 16384 + (m * 2 + k) * 1024))
; #define LDB(dst, b, h)                                                                                     \
;   _Pragma("unroll") for (int n = 0; n < 2; ++n) _Pragma("unroll") for (int k = 0; k < 2; ++k) dst[n][k] = \
;       *reinterpret_cast<const bf16x8*>(shmc + bL + (((b) * 2 + (h)) * 16384 + (n * 2 + k) * 1024))
; #define WAIT_V(n) asm volatile("s_waitcnt vmcnt(" #n ")" ::: "memory")
; #define WAIT_L(n) asm volatile("s_waitcnt lgkmcnt(" #n ")" ::: "memory")
; #define BAR __builtin_amdgcn_s_barrier()
; template <int EPI>
; __device__ __forceinline__ void phase_gemm(const Params& p, const GemmDesc& d, char* shmc) {
;     ...
;     {
;       LDB(B0, 1, 0); LDA(At, 1, 0); WAIT_V(2); BAR; WAIT_L(0); MMA(0, 0, At, B0); BAR;
;       LDB(B1, 1, 1); WAIT_V(0); BAR; WAIT_L(0); MMA(0, 1, At, B1); BAR;
;       LDA(At, 1, 1); BAR; WAIT_L(0); MMA(1, 0, At, B0); MMA(1, 1, At, B1); BAR;
;     }
;     if (wr == 0) BAR;
	ds_read_b128 v[98:101], v162 offset:32768
	ds_read_b128 v[106:109], v162 offset:33792
	ds_read_b128 v[190:193], v162 offset:34816
	ds_read_b128 v[194:197], v162 offset:35840
	ds_read_b128 v[58:61], v175 offset:32768
	ds_read_b128 v[70:73], v175 offset:33792
	ds_read_b128 v[114:117], v175 offset:34816
	ds_read_b128 v[122:125], v175 offset:35840
	ds_read_b128 v[130:133], v175 offset:36864
	ds_read_b128 v[138:141], v175 offset:37888
	ds_read_b128 v[198:201], v175 offset:38912
	ds_read_b128 v[208:211], v175 offset:39936
	s_waitcnt vmcnt(2)
	s_barrier
	s_waitcnt lgkmcnt(0)
	s_setprio 1
	s_waitcnt lgkmcnt(0)
	v_mfma_f32_16x16x32_bf16 v[2:5], v[58:61], v[98:101], v[2:5]
	v_mfma_f32_16x16x32_bf16 v[158:161], v[70:73], v[106:109], v[2:5]
	v_mfma_f32_16x16x32_bf16 v[2:5], v[58:61], v[190:193], v[6:9]
	v_mfma_f32_16x16x32_bf16 v[146:149], v[70:73], v[194:197], v[2:5]
	v_mfma_f32_16x16x32_bf16 v[2:5], v[114:117], v[98:101], v[10:13]
	v_mfma_f32_16x16x32_bf16 v[142:145], v[122:125], v[106:109], v[2:5]
	v_mfma_f32_16x16x32_bf16 v[2:5], v[114:117], v[190:193], v[18:21]
	v_mfma_f32_16x16x32_bf16 v[134:137], v[122:125], v[194:197], v[2:5]
	v_mfma_f32_16x16x32_bf16 v[2:5], v[130:133], v[98:101], v[30:33]
	v_mfma_f32_16x16x32_bf16 v[126:129], v[138:141], v[106:109], v[2:5]
	v_mfma_f32_16x16x32_bf16 v[2:5], v[130:133], v[190:193], v[42:45]
	v_mfma_f32_16x16x32_bf16 v[118:121], v[138:141], v[194:197], v[2:5]
	v_mfma_f32_16x16x32_bf16 v[2:5], v[198:201], v[98:101], v[54:57]
	v_mfma_f32_16x16x32_bf16 v[110:113], v[208:211], v[106:109], v[2:5]
	v_mfma_f32_16x16x32_bf16 v[2:5], v[198:201], v[190:193], v[66:69]
	v_mfma_f32_16x16x32_bf16 v[102:105], v[208:211], v[194:197], v[2:5]
	s_setprio 0
	s_barrier
	ds_read_b128 v[30:33], v162 offset:49152
	ds_read_b128 v[42:45], v162 offset:50176
	ds_read_b128 v[54:57], v162 offset:51200
	ds_read_b128 v[212:215], v162 offset:52224
	s_waitcnt vmcnt(0)
	s_barrier
	s_waitcnt lgkmcnt(0)
	s_setprio 1
	s_waitcnt lgkmcnt(0)
	v_mfma_f32_16x16x32_bf16 v[2:5], v[58:61], v[30:33], v[14:17]
	v_mfma_f32_16x16x32_bf16 v[94:97], v[70:73], v[42:45], v[2:5]
	v_mfma_f32_16x16x32_bf16 v[2:5], v[58:61], v[54:57], v[22:25]
	v_mfma_f32_16x16x32_bf16 v[58:61], v[70:73], v[212:215], v[2:5]
	v_mfma_f32_16x16x32_bf16 v[2:5], v[114:117], v[30:33], v[34:37]
	v_mfma_f32_16x16x32_bf16 v[74:77], v[122:125], v[42:45], v[2:5]
	v_mfma_f32_16x16x32_bf16 v[2:5], v[114:117], v[54:57], v[46:49]
	v_mfma_f32_16x16x32_bf16 v[10:13], v[122:125], v[212:215], v[2:5]
	v_mfma_f32_16x16x32_bf16 v[2:5], v[130:133], v[30:33], v[150:153]
	v_mfma_f32_16x16x32_bf16 v[70:73], v[138:141], v[42:45], v[2:5]
	v_mfma_f32_16x16x32_bf16 v[2:5], v[130:133], v[54:57], v[154:157]
	v_mfma_f32_16x16x32_bf16 v[6:9], v[138:141], v[212:215], v[2:5]
	v_mfma_f32_16x16x32_bf16 v[2:5], v[198:201], v[30:33], v[78:81]
	v_mfma_f32_16x16x32_bf16 v[66:69], v[208:211], v[42:45], v[2:5]
	v_mfma_f32_16x16x32_bf16 v[2:5], v[198:201], v[54:57], v[86:89]
	v_mfma_f32_16x16x32_bf16 v[2:5], v[208:211], v[212:215], v[2:5]
	s_setprio 0
	s_barrier
	ds_read_b128 v[14:17], v175 offset:49152
	ds_read_b128 v[18:21], v175 offset:50176
	ds_read_b128 v[22:25], v175 offset:51200
	ds_read_b128 v[34:37], v175 offset:52224
	ds_read_b128 v[46:49], v175 offset:53248
	ds_read_b128 v[78:81], v175 offset:54272
	ds_read_b128 v[198:201], v175 offset:55296
	ds_read_b128 v[208:211], v175 offset:56320
	s_barrier
	s_waitcnt lgkmcnt(0)
	s_setprio 1
	s_waitcnt lgkmcnt(0)
	v_mfma_f32_16x16x32_bf16 v[26:29], v[14:17], v[98:101], v[26:29]
	v_mfma_f32_16x16x32_bf16 v[154:157], v[18:21], v[106:109], v[26:29]
	v_mfma_f32_16x16x32_bf16 v[26:29], v[14:17], v[190:193], v[38:41]
	v_mfma_f32_16x16x32_bf16 v[150:153], v[18:21], v[194:197], v[26:29]
	v_mfma_f32_16x16x32_bf16 v[26:29], v[22:25], v[98:101], v[50:53]
	v_mfma_f32_16x16x32_bf16 v[138:141], v[34:37], v[106:109], v[26:29]
	v_mfma_f32_16x16x32_bf16 v[26:29], v[22:25], v[190:193], v[62:65]
	v_mfma_f32_16x16x32_bf16 v[130:133], v[34:37], v[194:197], v[26:29]
	v_mfma_f32_16x16x32_bf16 v[26:29], v[46:49], v[98:101], v[216:219]
	v_mfma_f32_16x16x32_bf16 v[122:125], v[78:81], v[106:109], v[26:29]
	v_mfma_f32_16x16x32_bf16 v[26:29], v[46:49], v[190:193], v[82:85]
	v_mfma_f32_16x16x32_bf16 v[114:117], v[78:81], v[194:197], v[26:29]
	v_mfma_f32_16x16x32_bf16 v[26:29], v[198:201], v[98:101], v[90:93]
	v_mfma_f32_16x16x32_bf16 v[106:109], v[208:211], v[106:109], v[26:29]
	v_mfma_f32_16x16x32_bf16 v[26:29], v[198:201], v[190:193], v[220:223]
	v_mfma_f32_16x16x32_bf16 v[98:101], v[208:211], v[194:197], v[26:29]
	s_setprio 0
	s_setprio 1
	v_mfma_f32_16x16x32_bf16 v[26:29], v[14:17], v[30:33], v[224:227]
	v_mfma_f32_16x16x32_bf16 v[14:17], v[14:17], v[54:57], v[228:231]
	v_mfma_f32_16x16x32_bf16 v[90:93], v[18:21], v[42:45], v[26:29]
	v_mfma_f32_16x16x32_bf16 v[26:29], v[18:21], v[212:215], v[14:17]
	v_mfma_f32_16x16x32_bf16 v[14:17], v[22:25], v[30:33], v[232:235]
	v_mfma_f32_16x16x32_bf16 v[86:89], v[34:37], v[42:45], v[14:17]
	v_mfma_f32_16x16x32_bf16 v[14:17], v[22:25], v[54:57], v[236:239]
	v_mfma_f32_16x16x32_bf16 v[22:25], v[34:37], v[212:215], v[14:17]
	v_mfma_f32_16x16x32_bf16 v[14:17], v[46:49], v[30:33], v[240:243]
	v_mfma_f32_16x16x32_bf16 v[82:85], v[78:81], v[42:45], v[14:17]
	v_mfma_f32_16x16x32_bf16 v[14:17], v[46:49], v[54:57], v[178:181]
	v_mfma_f32_16x16x32_bf16 v[18:21], v[78:81], v[212:215], v[14:17]
	v_mfma_f32_16x16x32_bf16 v[14:17], v[198:201], v[30:33], v[182:185]
	v_mfma_f32_16x16x32_bf16 v[78:81], v[208:211], v[42:45], v[14:17]
	v_mfma_f32_16x16x32_bf16 v[14:17], v[198:201], v[54:57], v[186:189]
	v_mfma_f32_16x16x32_bf16 v[14:17], v[208:211], v[212:215], v[14:17]
	s_setprio 0
	s_barrier
	s_and_saveexec_b64 s[8:9], s[6:7]
	s_cbranch_execz .LBB0_299
	s_barrier

; #define LDA(dst, b, h)                                                                                     \
;   _Pragma("unroll") for (int m = 0; m < 4; ++m) _Pragma("unroll") for (int k = 0; k < 2; ++k) dst[m][k] = \
;       *reinterpret_cast<const bf16x8*>(shmc + aL + (((b) * 2 + (h)) * 16384 + (m * 2 + k) * 1024))
; #define LDB(dst, b, h)                                                                                     \
;   _Pragma("unroll") for (int n = 0; n < 2; ++n) _Pragma("unroll") for (int k = 0; k < 2; ++k) dst[n][k] = \
;       *reinterpret_cast<const bf16x8*>(shmc + bL + (((b) * 2 + (h)) * 16384 + (n * 2 + k) * 1024))
; #define OPAQ asm volatile("" : "+v"(aL), "+v"(bL))
; #define WAIT_V(n) asm volatile("s_waitcnt vmcnt(" #n ")" ::: "memory")
; #define WAIT_L(n) asm volatile("s_waitcnt lgkmcnt(" #n ")" ::: "memory")
; #define BAR __builtin_amdgcn_s_barrier()
; #define SCHED __builtin_amdgcn_sched_barrier(0)
; template <int EPI>
; __device__ __forceinline__ void phase_gemm(const Params& p, const GemmDesc& d, char* shmc) {
;     ...
;       OPAQ;
;       LDB(B0, 0, 0); SCHED; LDA(At, 0, 0); STAGE_A(SA(1, 1), 1, t + 1);
;       WAIT_L(8); BAR; WAIT_L(0); MMA(0, 0, At, B0); BAR; SCHED;
;       LDB(B1, 0, 1); STAGE_B(SB(0, 0), 0, t + 2);
;       BAR; WAIT_L(0); MMA(0, 1, At, B1); BAR;
;       LDA(At, 0, 1); STAGE_A(SA(0, 0), 0, t + 2);
;       BAR; WAIT_L(0); MMA(1, 0, At, B0); BAR; SCHED;
;       STAGE_B(SB(0, 1), 1, t + 2);
;       WAIT_V(6); BAR; MMA(1, 1, At, B1); BAR;
.LBB0_455:
	s_nop 0
	v_add_u32_e32 v130, 0, v153
	v_add_u32_e32 v141, 0, v152
	s_setprio 0
	ds_read_b128 v[156:159], v130
	ds_read_b128 v[160:163], v130 offset:1024
	ds_read_b128 v[164:167], v130 offset:2048
	ds_read_b128 v[168:171], v130 offset:3072
	ds_read_b128 v[204:207], v130 offset:16384
	ds_read_b128 v[208:211], v130 offset:17408
	ds_read_b128 v[212:215], v130 offset:18432
	ds_read_b128 v[216:219], v130 offset:19456
	ds_read_b128 v[172:175], v141
	ds_read_b128 v[176:179], v141 offset:1024
	ds_read_b128 v[180:183], v141 offset:2048
	ds_read_b128 v[184:187], v141 offset:3072
	ds_read_b128 v[188:191], v141 offset:4096
	ds_read_b128 v[192:195], v141 offset:5120
	ds_read_b128 v[196:199], v141 offset:6144
	ds_read_b128 v[200:203], v141 offset:7168
	s_mov_b32 m0, s70
	s_nop 0
	global_load_lds_dwordx4 v220, s[98:99]
	s_mov_b32 m0, s71
	s_nop 0
	global_load_lds_dwordx4 v221, s[98:99]
	s_waitcnt vmcnt(8) lgkmcnt(0)
	s_setprio 1
	s_barrier
	v_mfma_f32_16x16x32_bf16 v[126:129], v[156:159], v[172:175], v[126:129]
	v_mfma_f32_16x16x32_bf16 v[122:125], v[164:167], v[172:175], v[122:125]
	v_mfma_f32_16x16x32_bf16 v[118:121], v[156:159], v[180:183], v[118:121]
	v_mfma_f32_16x16x32_bf16 v[114:117], v[164:167], v[180:183], v[114:117]
	v_mfma_f32_16x16x32_bf16 v[110:113], v[156:159], v[188:191], v[110:113]
	v_mfma_f32_16x16x32_bf16 v[106:109], v[164:167], v[188:191], v[106:109]
	v_mfma_f32_16x16x32_bf16 v[102:105], v[156:159], v[196:199], v[102:105]
	v_mfma_f32_16x16x32_bf16 v[98:101], v[164:167], v[196:199], v[98:101]
	v_mfma_f32_16x16x32_bf16 v[126:129], v[160:163], v[176:179], v[126:129]
	v_mfma_f32_16x16x32_bf16 v[122:125], v[168:171], v[176:179], v[122:125]
	v_mfma_f32_16x16x32_bf16 v[118:121], v[160:163], v[184:187], v[118:121]
	v_mfma_f32_16x16x32_bf16 v[114:117], v[168:171], v[184:187], v[114:117]
	v_mfma_f32_16x16x32_bf16 v[110:113], v[160:163], v[192:195], v[110:113]
	v_mfma_f32_16x16x32_bf16 v[106:109], v[168:171], v[192:195], v[106:109]
	v_mfma_f32_16x16x32_bf16 v[102:105], v[160:163], v[200:203], v[102:105]
	v_mfma_f32_16x16x32_bf16 v[98:101], v[168:171], v[200:203], v[98:101]
	v_mfma_f32_16x16x32_bf16 v[86:89], v[204:207], v[172:175], v[86:89]
	v_mfma_f32_16x16x32_bf16 v[70:73], v[212:215], v[172:175], v[70:73]
	v_mfma_f32_16x16x32_bf16 v[54:57], v[204:207], v[180:183], v[54:57]
	v_mfma_f32_16x16x32_bf16 v[50:53], v[212:215], v[180:183], v[50:53]
	v_mfma_f32_16x16x32_bf16 v[46:49], v[204:207], v[188:191], v[46:49]
	v_mfma_f32_16x16x32_bf16 v[42:45], v[212:215], v[188:191], v[42:45]
	v_mfma_f32_16x16x32_bf16 v[38:41], v[204:207], v[196:199], v[38:41]
	v_mfma_f32_16x16x32_bf16 v[34:37], v[212:215], v[196:199], v[34:37]
	v_mfma_f32_16x16x32_bf16 v[86:89], v[208:211], v[176:179], v[86:89]
	v_mfma_f32_16x16x32_bf16 v[70:73], v[216:219], v[176:179], v[70:73]
	v_mfma_f32_16x16x32_bf16 v[54:57], v[208:211], v[184:187], v[54:57]
	v_mfma_f32_16x16x32_bf16 v[50:53], v[216:219], v[184:187], v[50:53]
	v_mfma_f32_16x16x32_bf16 v[46:49], v[208:211], v[192:195], v[46:49]
	v_mfma_f32_16x16x32_bf16 v[42:45], v[216:219], v[192:195], v[42:45]
	v_mfma_f32_16x16x32_bf16 v[38:41], v[208:211], v[200:203], v[38:41]
	v_mfma_f32_16x16x32_bf16 v[34:37], v[216:219], v[200:203], v[34:37]
	s_barrier
	s_setprio 0
	ds_read_b128 v[172:175], v141 offset:16384
	ds_read_b128 v[176:179], v141 offset:17408
	ds_read_b128 v[180:183], v141 offset:18432
	ds_read_b128 v[184:187], v141 offset:19456
	ds_read_b128 v[188:191], v141 offset:20480
	ds_read_b128 v[192:195], v141 offset:21504
	ds_read_b128 v[196:199], v141 offset:22528
	ds_read_b128 v[200:203], v141 offset:23552
	s_mov_b32 m0, s33
	s_nop 0
	global_load_lds_dwordx4 v222, s[100:101]
	s_mov_b32 m0, s34
	s_nop 0
	global_load_lds_dwordx4 v223, s[100:101]
	s_mov_b32 m0, s14
	s_nop 0
	global_load_lds_dwordx4 v224, s[98:99]
	s_mov_b32 m0, s35
	s_nop 0
	global_load_lds_dwordx4 v225, s[98:99]
	s_mov_b32 m0, s58
	s_nop 0
	global_load_lds_dwordx4 v226, s[100:101]
	s_mov_b32 m0, s59
	s_nop 0
	global_load_lds_dwordx4 v227, s[100:101]
	s_waitcnt vmcnt(8) lgkmcnt(0)
	s_setprio 1
	s_barrier
	v_mfma_f32_16x16x32_bf16 v[30:33], v[156:159], v[172:175], v[30:33]
	v_mfma_f32_16x16x32_bf16 v[26:29], v[164:167], v[172:175], v[26:29]
	v_mfma_f32_16x16x32_bf16 v[22:25], v[156:159], v[180:183], v[22:25]
	v_mfma_f32_16x16x32_bf16 v[18:21], v[164:167], v[180:183], v[18:21]
	v_mfma_f32_16x16x32_bf16 v[14:17], v[156:159], v[188:191], v[14:17]
	v_mfma_f32_16x16x32_bf16 v[10:13], v[164:167], v[188:191], v[10:13]
	v_mfma_f32_16x16x32_bf16 v[6:9], v[156:159], v[196:199], v[6:9]
	v_mfma_f32_16x16x32_bf16 v[2:5], v[164:167], v[196:199], v[2:5]
	v_mfma_f32_16x16x32_bf16 v[30:33], v[160:163], v[176:179], v[30:33]
	v_mfma_f32_16x16x32_bf16 v[26:29], v[168:171], v[176:179], v[26:29]
	v_mfma_f32_16x16x32_bf16 v[22:25], v[160:163], v[184:187], v[22:25]
	v_mfma_f32_16x16x32_bf16 v[18:21], v[168:171], v[184:187], v[18:21]
	v_mfma_f32_16x16x32_bf16 v[14:17], v[160:163], v[192:195], v[14:17]
	v_mfma_f32_16x16x32_bf16 v[10:13], v[168:171], v[192:195], v[10:13]
	v_mfma_f32_16x16x32_bf16 v[6:9], v[160:163], v[200:203], v[6:9]
	v_mfma_f32_16x16x32_bf16 v[2:5], v[168:171], v[200:203], v[2:5]
	v_mfma_f32_16x16x32_bf16 v[58:61], v[204:207], v[172:175], v[58:61]
	v_mfma_f32_16x16x32_bf16 v[62:65], v[212:215], v[172:175], v[62:65]
	v_mfma_f32_16x16x32_bf16 v[66:69], v[204:207], v[180:183], v[66:69]
	v_mfma_f32_16x16x32_bf16 v[74:77], v[212:215], v[180:183], v[74:77]
	v_mfma_f32_16x16x32_bf16 v[78:81], v[204:207], v[188:191], v[78:81]
	v_mfma_f32_16x16x32_bf16 v[82:85], v[212:215], v[188:191], v[82:85]
	v_mfma_f32_16x16x32_bf16 v[90:93], v[204:207], v[196:199], v[90:93]
	v_mfma_f32_16x16x32_bf16 v[94:97], v[212:215], v[196:199], v[94:97]
	v_mfma_f32_16x16x32_bf16 v[58:61], v[208:211], v[176:179], v[58:61]
	v_mfma_f32_16x16x32_bf16 v[62:65], v[216:219], v[176:179], v[62:65]
	v_mfma_f32_16x16x32_bf16 v[66:69], v[208:211], v[184:187], v[66:69]
	v_mfma_f32_16x16x32_bf16 v[74:77], v[216:219], v[184:187], v[74:77]
	v_mfma_f32_16x16x32_bf16 v[78:81], v[208:211], v[192:195], v[78:81]
	v_mfma_f32_16x16x32_bf16 v[82:85], v[216:219], v[192:195], v[82:85]
	v_mfma_f32_16x16x32_bf16 v[90:93], v[208:211], v[200:203], v[90:93]
	v_mfma_f32_16x16x32_bf16 v[94:97], v[216:219], v[200:203], v[94:97]
	s_barrier
; #define LDA(dst, b, h)                                                                                     \
;   _Pragma("unroll") for (int m = 0; m < 4; ++m) _Pragma("unroll") for (int k = 0; k < 2; ++k) dst[m][k] = \
;       *reinterpret_cast<const bf16x8*>(shmc + aL + (((b) * 2 + (h)) * 16384 + (m * 2 + k) * 1024))
; #define LDB(dst, b, h)                                                                                     \
;   _Pragma("unroll") for (int n = 0; n < 2; ++n) _Pragma("unroll") for (int k = 0; k < 2; ++k) dst[n][k] = \
;       *reinterpret_cast<const bf16x8*>(shmc + bL + (((b) * 2 + (h)) * 16384 + (n * 2 + k) * 1024))
; #define WAIT_V(n) asm volatile("s_waitcnt vmcnt(" #n ")" ::: "memory")
; #define WAIT_L(n) asm volatile("s_waitcnt lgkmcnt(" #n ")" ::: "memory")
; #define BAR __builtin_amdgcn_s_barrier()
; #define SCHED __builtin_amdgcn_sched_barrier(0)
; template <int EPI>
; __device__ __forceinline__ void phase_gemm(const Params& p, const GemmDesc& d, char* shmc) {
;     ...
;       LDB(B0, 1, 0); SCHED; LDA(At, 1, 0); STAGE_A(SA(0, 1), 1, t + 2);
;       WAIT_L(8); BAR; WAIT_L(0); MMA(0, 0, At, B0); BAR; SCHED;
;       LDB(B1, 1, 1); STAGE_B(SB(1, 0), 0, t + 3);
;       BAR; WAIT_L(0); MMA(0, 1, At, B1); BAR;
;       LDA(At, 1, 1); STAGE_A(SA(1, 0), 0, t + 3);
;       BAR; WAIT_L(0); MMA(1, 0, At, B0); BAR; SCHED;
;       STAGE_B(SB(1, 1), 1, t + 3);
;       WAIT_V(6); BAR; MMA(1, 1, At, B1); BAR;
;     }
	s_setprio 0
	ds_read_b128 v[156:159], v130 offset:32768
	ds_read_b128 v[160:163], v130 offset:33792
	ds_read_b128 v[164:167], v130 offset:34816
	ds_read_b128 v[168:171], v130 offset:35840
	ds_read_b128 v[204:207], v130 offset:49152
	ds_read_b128 v[208:211], v130 offset:50176
	ds_read_b128 v[212:215], v130 offset:51200
	ds_read_b128 v[216:219], v130 offset:52224
	ds_read_b128 v[172:175], v141 offset:32768
	ds_read_b128 v[176:179], v141 offset:33792
	ds_read_b128 v[180:183], v141 offset:34816
	ds_read_b128 v[184:187], v141 offset:35840
	ds_read_b128 v[188:191], v141 offset:36864
	ds_read_b128 v[192:195], v141 offset:37888
	ds_read_b128 v[196:199], v141 offset:38912
	ds_read_b128 v[200:203], v141 offset:39936
	s_mov_b32 m0, s60
	s_nop 0
	global_load_lds_dwordx4 v228, s[98:99]
	s_mov_b32 m0, s61
	s_nop 0
	global_load_lds_dwordx4 v229, s[98:99]
	s_waitcnt vmcnt(8) lgkmcnt(0)
	s_setprio 1
	s_barrier
	v_mfma_f32_16x16x32_bf16 v[126:129], v[156:159], v[172:175], v[126:129]
	v_mfma_f32_16x16x32_bf16 v[122:125], v[164:167], v[172:175], v[122:125]
	v_mfma_f32_16x16x32_bf16 v[118:121], v[156:159], v[180:183], v[118:121]
	v_mfma_f32_16x16x32_bf16 v[114:117], v[164:167], v[180:183], v[114:117]
	v_mfma_f32_16x16x32_bf16 v[110:113], v[156:159], v[188:191], v[110:113]
	v_mfma_f32_16x16x32_bf16 v[106:109], v[164:167], v[188:191], v[106:109]
	v_mfma_f32_16x16x32_bf16 v[102:105], v[156:159], v[196:199], v[102:105]
	v_mfma_f32_16x16x32_bf16 v[98:101], v[164:167], v[196:199], v[98:101]
	v_mfma_f32_16x16x32_bf16 v[126:129], v[160:163], v[176:179], v[126:129]
	v_mfma_f32_16x16x32_bf16 v[122:125], v[168:171], v[176:179], v[122:125]
	v_mfma_f32_16x16x32_bf16 v[118:121], v[160:163], v[184:187], v[118:121]
	v_mfma_f32_16x16x32_bf16 v[114:117], v[168:171], v[184:187], v[114:117]
	v_mfma_f32_16x16x32_bf16 v[110:113], v[160:163], v[192:195], v[110:113]
	v_mfma_f32_16x16x32_bf16 v[106:109], v[168:171], v[192:195], v[106:109]
	v_mfma_f32_16x16x32_bf16 v[102:105], v[160:163], v[200:203], v[102:105]
	v_mfma_f32_16x16x32_bf16 v[98:101], v[168:171], v[200:203], v[98:101]
	v_mfma_f32_16x16x32_bf16 v[86:89], v[204:207], v[172:175], v[86:89]
	v_mfma_f32_16x16x32_bf16 v[70:73], v[212:215], v[172:175], v[70:73]
	v_mfma_f32_16x16x32_bf16 v[54:57], v[204:207], v[180:183], v[54:57]
	v_mfma_f32_16x16x32_bf16 v[50:53], v[212:215], v[180:183], v[50:53]
	v_mfma_f32_16x16x32_bf16 v[46:49], v[204:207], v[188:191], v[46:49]
	v_mfma_f32_16x16x32_bf16 v[42:45], v[212:215], v[188:191], v[42:45]
	v_mfma_f32_16x16x32_bf16 v[38:41], v[204:207], v[196:199], v[38:41]
	v_mfma_f32_16x16x32_bf16 v[34:37], v[212:215], v[196:199], v[34:37]
	v_mfma_f32_16x16x32_bf16 v[86:89], v[208:211], v[176:179], v[86:89]
	v_mfma_f32_16x16x32_bf16 v[70:73], v[216:219], v[176:179], v[70:73]
	v_mfma_f32_16x16x32_bf16 v[54:57], v[208:211], v[184:187], v[54:57]
	v_mfma_f32_16x16x32_bf16 v[50:53], v[216:219], v[184:187], v[50:53]
	v_mfma_f32_16x16x32_bf16 v[46:49], v[208:211], v[192:195], v[46:49]
	v_mfma_f32_16x16x32_bf16 v[42:45], v[216:219], v[192:195], v[42:45]
	v_mfma_f32_16x16x32_bf16 v[38:41], v[208:211], v[200:203], v[38:41]
	v_mfma_f32_16x16x32_bf16 v[34:37], v[216:219], v[200:203], v[34:37]
	s_barrier
	s_setprio 0
	ds_read_b128 v[172:175], v141 offset:49152
	ds_read_b128 v[176:179], v141 offset:50176
	ds_read_b128 v[180:183], v141 offset:51200
	ds_read_b128 v[184:187], v141 offset:52224
	ds_read_b128 v[188:191], v141 offset:53248
	ds_read_b128 v[192:195], v141 offset:54272
	ds_read_b128 v[196:199], v141 offset:55296
	ds_read_b128 v[200:203], v141 offset:56320
	s_mov_b32 m0, s62
	s_nop 0
	global_load_lds_dwordx4 v232, s[100:101]
	s_mov_b32 m0, s63
	s_nop 0
	global_load_lds_dwordx4 v233, s[100:101]
	s_mov_b32 m0, s64
	s_nop 0
	global_load_lds_dwordx4 v234, s[98:99]
	s_mov_b32 m0, s65
	s_nop 0
	global_load_lds_dwordx4 v235, s[98:99]
	s_mov_b32 m0, s68
	s_nop 0
	global_load_lds_dwordx4 v236, s[100:101]
	s_mov_b32 m0, s69
	s_nop 0
	global_load_lds_dwordx4 v237, s[100:101]
	s_add_i32 s54, s54, 2
	s_add_u32 s52, s52, 0x100
	s_addc_u32 s53, s53, 0
	s_add_u32 s98, s98, 0x100
	s_addc_u32 s99, s99, 0
	s_add_u32 s100, s100, 0x100
	s_addc_u32 s101, s101, 0
	s_cmpk_gt_u32 s54, 0x53
	s_waitcnt vmcnt(8) lgkmcnt(0)
	s_setprio 1
	s_barrier
	v_mfma_f32_16x16x32_bf16 v[30:33], v[156:159], v[172:175], v[30:33]
	v_mfma_f32_16x16x32_bf16 v[26:29], v[164:167], v[172:175], v[26:29]
	v_mfma_f32_16x16x32_bf16 v[22:25], v[156:159], v[180:183], v[22:25]
	v_mfma_f32_16x16x32_bf16 v[18:21], v[164:167], v[180:183], v[18:21]
	v_mfma_f32_16x16x32_bf16 v[14:17], v[156:159], v[188:191], v[14:17]
	v_mfma_f32_16x16x32_bf16 v[10:13], v[164:167], v[188:191], v[10:13]
	v_mfma_f32_16x16x32_bf16 v[6:9], v[156:159], v[196:199], v[6:9]
	v_mfma_f32_16x16x32_bf16 v[2:5], v[164:167], v[196:199], v[2:5]
	v_mfma_f32_16x16x32_bf16 v[30:33], v[160:163], v[176:179], v[30:33]
	v_mfma_f32_16x16x32_bf16 v[26:29], v[168:171], v[176:179], v[26:29]
	v_mfma_f32_16x16x32_bf16 v[22:25], v[160:163], v[184:187], v[22:25]
	v_mfma_f32_16x16x32_bf16 v[18:21], v[168:171], v[184:187], v[18:21]
	v_mfma_f32_16x16x32_bf16 v[14:17], v[160:163], v[192:195], v[14:17]
	v_mfma_f32_16x16x32_bf16 v[10:13], v[168:171], v[192:195], v[10:13]
	v_mfma_f32_16x16x32_bf16 v[6:9], v[160:163], v[200:203], v[6:9]
	v_mfma_f32_16x16x32_bf16 v[2:5], v[168:171], v[200:203], v[2:5]
	v_mfma_f32_16x16x32_bf16 v[58:61], v[204:207], v[172:175], v[58:61]
	v_mfma_f32_16x16x32_bf16 v[62:65], v[212:215], v[172:175], v[62:65]
	v_mfma_f32_16x16x32_bf16 v[66:69], v[204:207], v[180:183], v[66:69]
	v_mfma_f32_16x16x32_bf16 v[74:77], v[212:215], v[180:183], v[74:77]
	v_mfma_f32_16x16x32_bf16 v[78:81], v[204:207], v[188:191], v[78:81]
	v_mfma_f32_16x16x32_bf16 v[82:85], v[212:215], v[188:191], v[82:85]
	v_mfma_f32_16x16x32_bf16 v[90:93], v[204:207], v[196:199], v[90:93]
	v_mfma_f32_16x16x32_bf16 v[94:97], v[212:215], v[196:199], v[94:97]
	v_mfma_f32_16x16x32_bf16 v[58:61], v[208:211], v[176:179], v[58:61]
	v_mfma_f32_16x16x32_bf16 v[62:65], v[216:219], v[176:179], v[62:65]
	v_mfma_f32_16x16x32_bf16 v[66:69], v[208:211], v[184:187], v[66:69]
	v_mfma_f32_16x16x32_bf16 v[74:77], v[216:219], v[184:187], v[74:77]
	v_mfma_f32_16x16x32_bf16 v[78:81], v[208:211], v[192:195], v[78:81]
	v_mfma_f32_16x16x32_bf16 v[82:85], v[216:219], v[192:195], v[82:85]
	v_mfma_f32_16x16x32_bf16 v[90:93], v[208:211], v[200:203], v[90:93]
	v_mfma_f32_16x16x32_bf16 v[94:97], v[216:219], v[200:203], v[94:97]
	s_barrier
; #define LDA(dst, b, h)                                                                                     \
;   _Pragma("unroll") for (int m = 0; m < 4; ++m) _Pragma("unroll") for (int k = 0; k < 2; ++k) dst[m][k] = \
;       *reinterpret_cast<const bf16x8*>(shmc + aL + (((b) * 2 + (h)) * 16384 + (m * 2 + k) * 1024))
; #define LDB(dst, b, h)                                                                                     \
;   _Pragma("unroll") for (int n = 0; n < 2; ++n) _Pragma("unroll") for (int k = 0; k < 2; ++k) dst[n][k] = \
;       *reinterpret_cast<const bf16x8*>(shmc + bL + (((b) * 2 + (h)) * 16384 + (n * 2 + k) * 1024))
; #define OPAQ asm volatile("" : "+v"(aL), "+v"(bL))
; #define WAIT_V(n) asm volatile("s_waitcnt vmcnt(" #n ")" ::: "memory")
; #define WAIT_L(n) asm volatile("s_waitcnt lgkmcnt(" #n ")" ::: "memory")
; #define BAR __builtin_amdgcn_s_barrier()
; template <int EPI>
; __device__ __forceinline__ void phase_gemm(const Params& p, const GemmDesc& d, char* shmc) {
;     ...
;     {
;       OPAQ;
;       LDB(B0, 0, 0); LDA(At, 0, 0); STAGE_A(SA(1, 1), 1, nt - 1);
;       BAR; WAIT_L(0); MMA(0, 0, At, B0); BAR;
;       LDB(B1, 0, 1); BAR; WAIT_L(0); MMA(0, 1, At, B1); BAR;
;       LDA(At, 0, 1); WAIT_V(4); BAR; WAIT_L(0); MMA(1, 0, At, B0); MMA(1, 1, At, B1); BAR;
;     }
	s_cbranch_scc0 .LBB0_455
	s_setprio 0
	s_add_u32 s48, s48, 0x162b80
	s_addc_u32 s49, s49, 0
	v_add_u32_e32 v130, 0, v153
	v_add_u32_e32 v141, 0, v152
	s_mov_b32 m0, s70
	ds_read_b128 v[144:147], v130
	ds_read_b128 v[148:151], v130 offset:1024
	ds_read_b128 v[156:159], v130 offset:2048
	ds_read_b128 v[160:163], v130 offset:3072
	ds_read_b128 v[164:167], v141
	ds_read_b128 v[168:171], v141 offset:1024
	ds_read_b128 v[172:175], v141 offset:2048
	ds_read_b128 v[176:179], v141 offset:3072
	ds_read_b128 v[180:183], v141 offset:4096
	ds_read_b128 v[184:187], v141 offset:5120
	ds_read_b128 v[188:191], v141 offset:6144
	ds_read_b128 v[192:195], v141 offset:7168
	global_load_lds_dwordx4 v140, s[48:49]
	s_mov_b32 m0, s71
	s_nop 0
	global_load_lds_dwordx4 v142, s[48:49]
	s_waitcnt vmcnt(8)
	s_barrier
	s_waitcnt lgkmcnt(0)
	s_setprio 1
	s_waitcnt lgkmcnt(0)
	v_mfma_f32_16x16x32_bf16 v[126:129], v[144:147], v[164:167], v[126:129]
	v_mfma_f32_16x16x32_bf16 v[122:125], v[156:159], v[164:167], v[122:125]
	v_mfma_f32_16x16x32_bf16 v[114:117], v[156:159], v[172:175], v[114:117]
	v_mfma_f32_16x16x32_bf16 v[110:113], v[144:147], v[180:183], v[110:113]
	v_mfma_f32_16x16x32_bf16 v[102:105], v[144:147], v[188:191], v[102:105]
	v_mfma_f32_16x16x32_bf16 v[126:129], v[148:151], v[168:171], v[126:129]
	v_mfma_f32_16x16x32_bf16 v[122:125], v[160:163], v[168:171], v[122:125]
	v_mfma_f32_16x16x32_bf16 v[118:121], v[144:147], v[172:175], v[118:121]
	v_mfma_f32_16x16x32_bf16 v[114:117], v[160:163], v[176:179], v[114:117]
	v_mfma_f32_16x16x32_bf16 v[110:113], v[148:151], v[184:187], v[110:113]
	v_mfma_f32_16x16x32_bf16 v[106:109], v[156:159], v[180:183], v[106:109]
	v_mfma_f32_16x16x32_bf16 v[102:105], v[148:151], v[192:195], v[102:105]
	v_mfma_f32_16x16x32_bf16 v[98:101], v[156:159], v[188:191], v[98:101]
	v_mfma_f32_16x16x32_bf16 v[196:199], v[148:151], v[176:179], v[118:121]
	v_mfma_f32_16x16x32_bf16 v[200:203], v[160:163], v[184:187], v[106:109]
	v_mfma_f32_16x16x32_bf16 v[204:207], v[160:163], v[192:195], v[98:101]
	s_setprio 0
	s_barrier
	s_nop 2
	ds_read_b128 v[98:101], v130 offset:16384
	ds_read_b128 v[106:109], v130 offset:17408
	ds_read_b128 v[118:121], v130 offset:18432
	ds_read_b128 v[208:211], v130 offset:19456
	s_barrier
	s_waitcnt lgkmcnt(0)
	s_setprio 1
	s_waitcnt lgkmcnt(0)
	v_mfma_f32_16x16x32_bf16 v[86:89], v[98:101], v[164:167], v[86:89]
	v_mfma_f32_16x16x32_bf16 v[70:73], v[118:121], v[164:167], v[70:73]
	v_mfma_f32_16x16x32_bf16 v[54:57], v[98:101], v[172:175], v[54:57]
	v_mfma_f32_16x16x32_bf16 v[50:53], v[118:121], v[172:175], v[50:53]
	v_mfma_f32_16x16x32_bf16 v[46:49], v[98:101], v[180:183], v[46:49]
	v_mfma_f32_16x16x32_bf16 v[42:45], v[118:121], v[180:183], v[42:45]
	v_mfma_f32_16x16x32_bf16 v[38:41], v[98:101], v[188:191], v[38:41]
	v_mfma_f32_16x16x32_bf16 v[34:37], v[118:121], v[188:191], v[34:37]
	v_mfma_f32_16x16x32_bf16 v[86:89], v[106:109], v[168:171], v[86:89]
	v_mfma_f32_16x16x32_bf16 v[70:73], v[208:211], v[168:171], v[70:73]
	v_mfma_f32_16x16x32_bf16 v[54:57], v[106:109], v[176:179], v[54:57]
	v_mfma_f32_16x16x32_bf16 v[50:53], v[208:211], v[176:179], v[50:53]
	v_mfma_f32_16x16x32_bf16 v[46:49], v[106:109], v[184:187], v[46:49]
	v_mfma_f32_16x16x32_bf16 v[42:45], v[208:211], v[184:187], v[42:45]
	v_mfma_f32_16x16x32_bf16 v[38:41], v[106:109], v[192:195], v[38:41]
	v_mfma_f32_16x16x32_bf16 v[34:37], v[208:211], v[192:195], v[34:37]
	s_setprio 0
	s_barrier
	ds_read_b128 v[164:167], v141 offset:16384
	ds_read_b128 v[168:171], v141 offset:17408
	ds_read_b128 v[172:175], v141 offset:18432
	ds_read_b128 v[176:179], v141 offset:19456
	ds_read_b128 v[180:183], v141 offset:20480
	ds_read_b128 v[184:187], v141 offset:21504
	ds_read_b128 v[188:191], v141 offset:22528
	ds_read_b128 v[192:195], v141 offset:23552
	s_waitcnt vmcnt(4)
	s_barrier
	s_waitcnt lgkmcnt(0)
	s_setprio 1
	s_waitcnt lgkmcnt(0)
	v_mfma_f32_16x16x32_bf16 v[30:33], v[144:147], v[164:167], v[30:33]
	v_mfma_f32_16x16x32_bf16 v[26:29], v[156:159], v[164:167], v[26:29]
	v_mfma_f32_16x16x32_bf16 v[22:25], v[144:147], v[172:175], v[22:25]
	v_mfma_f32_16x16x32_bf16 v[18:21], v[156:159], v[172:175], v[18:21]
	v_mfma_f32_16x16x32_bf16 v[14:17], v[144:147], v[180:183], v[14:17]
	v_mfma_f32_16x16x32_bf16 v[10:13], v[156:159], v[180:183], v[10:13]
	v_mfma_f32_16x16x32_bf16 v[6:9], v[144:147], v[188:191], v[6:9]
	v_mfma_f32_16x16x32_bf16 v[2:5], v[156:159], v[188:191], v[2:5]
	v_mfma_f32_16x16x32_bf16 v[30:33], v[148:151], v[168:171], v[30:33]
	v_mfma_f32_16x16x32_bf16 v[26:29], v[160:163], v[168:171], v[26:29]
	v_mfma_f32_16x16x32_bf16 v[22:25], v[148:151], v[176:179], v[22:25]
	v_mfma_f32_16x16x32_bf16 v[18:21], v[160:163], v[176:179], v[18:21]
	v_mfma_f32_16x16x32_bf16 v[14:17], v[148:151], v[184:187], v[14:17]
	v_mfma_f32_16x16x32_bf16 v[10:13], v[160:163], v[184:187], v[10:13]
	v_mfma_f32_16x16x32_bf16 v[6:9], v[148:151], v[192:195], v[6:9]
	v_mfma_f32_16x16x32_bf16 v[2:5], v[160:163], v[192:195], v[2:5]
	s_setprio 0
	s_setprio 1
	v_mfma_f32_16x16x32_bf16 v[62:65], v[118:121], v[164:167], v[62:65]
	v_mfma_f32_16x16x32_bf16 v[144:147], v[208:211], v[168:171], v[62:65]
	v_mfma_f32_16x16x32_bf16 v[62:65], v[98:101], v[172:175], v[66:69]
	v_mfma_f32_16x16x32_bf16 v[148:151], v[106:109], v[176:179], v[62:65]
	v_mfma_f32_16x16x32_bf16 v[62:65], v[118:121], v[172:175], v[74:77]
	v_mfma_f32_16x16x32_bf16 v[156:159], v[208:211], v[176:179], v[62:65]
	v_mfma_f32_16x16x32_bf16 v[62:65], v[98:101], v[180:183], v[78:81]
	v_mfma_f32_16x16x32_bf16 v[160:163], v[106:109], v[184:187], v[62:65]
	v_mfma_f32_16x16x32_bf16 v[62:65], v[118:121], v[180:183], v[82:85]
	v_mfma_f32_16x16x32_bf16 v[58:61], v[98:101], v[164:167], v[58:61]
	v_mfma_f32_16x16x32_bf16 v[164:167], v[208:211], v[184:187], v[62:65]
	v_mfma_f32_16x16x32_bf16 v[62:65], v[98:101], v[188:191], v[90:93]
	v_mfma_f32_16x16x32_bf16 v[58:61], v[106:109], v[168:171], v[58:61]
	v_mfma_f32_16x16x32_bf16 v[168:171], v[106:109], v[192:195], v[62:65]
	v_mfma_f32_16x16x32_bf16 v[62:65], v[118:121], v[188:191], v[94:97]
	v_mfma_f32_16x16x32_bf16 v[172:175], v[208:211], v[192:195], v[62:65]
	s_setprio 0
	s_barrier
; #define LDA(dst, b, h)                                                                                     \
;   _Pragma("unroll") for (int m = 0; m < 4; ++m) _Pragma("unroll") for (int k = 0; k < 2; ++k) dst[m][k] = \
;       *reinterpret_cast<const bf16x8*>(shmc + aL + (((b) * 2 + (h)) * 16384 + (m * 2 + k) * 1024))
; #define LDB(dst, b, h)                                                                                     \
;   _Pragma("unroll") for (int n = 0; n < 2; ++n) _Pragma("unroll") for (int k = 0; k < 2; ++k) dst[n][k] = \
;       *reinterpret_cast<const bf16x8*>(shmc + bL + (((b) * 2 + (h)) * 16384 + (n * 2 + k) * 1024))
; #define WAIT_V(n) asm volatile("s_waitcnt vmcnt(" #n ")" ::: "memory")
; #define WAIT_L(n) asm volatile("s_waitcnt lgkmcnt(" #n ")" ::: "memory")
; #define BAR __builtin_amdgcn_s_barrier()
; template <int EPI>
; __device__ __forceinline__ void phase_gemm(const Params& p, const GemmDesc& d, char* shmc) {
;     ...
;     {
;       LDB(B0, 1, 0); LDA(At, 1, 0); WAIT_V(2); BAR; WAIT_L(0); MMA(0, 0, At, B0); BAR;
;       LDB(B1, 1, 1); WAIT_V(0); BAR; WAIT_L(0); MMA(0, 1, At, B1); BAR;
;       LDA(At, 1, 1); BAR; WAIT_L(0); MMA(1, 0, At, B0); MMA(1, 1, At, B1); BAR;
;     }
;     if (wr == 0) BAR;
	ds_read_b128 v[176:179], v130 offset:32768
	ds_read_b128 v[180:183], v130 offset:33792
	ds_read_b128 v[184:187], v130 offset:34816
	ds_read_b128 v[188:191], v130 offset:35840
	s_nop 0
	ds_read_b128 v[62:65], v141 offset:32768
	ds_read_b128 v[78:81], v141 offset:33792
	ds_read_b128 v[94:97], v141 offset:34816
	ds_read_b128 v[192:195], v141 offset:35840
	ds_read_b128 v[208:211], v141 offset:36864
	ds_read_b128 v[212:215], v141 offset:37888
	ds_read_b128 v[216:219], v141 offset:38912
	ds_read_b128 v[220:223], v141 offset:39936
	s_waitcnt vmcnt(2)
	s_barrier
	s_waitcnt lgkmcnt(0)
	s_setprio 1
	s_waitcnt lgkmcnt(0)
	v_mfma_f32_16x16x32_bf16 v[66:69], v[176:179], v[62:65], v[126:129]
	v_mfma_f32_16x16x32_bf16 v[126:129], v[180:183], v[78:81], v[66:69]
	v_mfma_f32_16x16x32_bf16 v[66:69], v[184:187], v[62:65], v[122:125]
	v_mfma_f32_16x16x32_bf16 v[118:121], v[188:191], v[78:81], v[66:69]
	v_mfma_f32_16x16x32_bf16 v[66:69], v[176:179], v[94:97], v[196:199]
	v_mfma_f32_16x16x32_bf16 v[106:109], v[180:183], v[192:195], v[66:69]
	v_mfma_f32_16x16x32_bf16 v[66:69], v[184:187], v[94:97], v[114:117]
	v_mfma_f32_16x16x32_bf16 v[98:101], v[188:191], v[192:195], v[66:69]
	v_mfma_f32_16x16x32_bf16 v[66:69], v[176:179], v[208:211], v[110:113]
	v_mfma_f32_16x16x32_bf16 v[90:93], v[180:183], v[212:215], v[66:69]
	v_mfma_f32_16x16x32_bf16 v[66:69], v[184:187], v[208:211], v[200:203]
	v_mfma_f32_16x16x32_bf16 v[82:85], v[188:191], v[212:215], v[66:69]
	v_mfma_f32_16x16x32_bf16 v[66:69], v[176:179], v[216:219], v[102:105]
	v_mfma_f32_16x16x32_bf16 v[74:77], v[180:183], v[220:223], v[66:69]
	v_mfma_f32_16x16x32_bf16 v[66:69], v[184:187], v[216:219], v[204:207]
	v_mfma_f32_16x16x32_bf16 v[66:69], v[188:191], v[220:223], v[66:69]
	s_setprio 0
	s_barrier
	ds_read_b128 v[196:199], v130 offset:49152
	ds_read_b128 v[200:203], v130 offset:50176
	ds_read_b128 v[204:207], v130 offset:51200
	ds_read_b128 v[224:227], v130 offset:52224
	s_waitcnt vmcnt(0)
	s_barrier
	s_waitcnt lgkmcnt(0)
	s_setprio 1
	s_waitcnt lgkmcnt(0)
	v_mfma_f32_16x16x32_bf16 v[86:89], v[196:199], v[62:65], v[86:89]
	v_mfma_f32_16x16x32_bf16 v[62:65], v[204:207], v[62:65], v[70:73]
	v_mfma_f32_16x16x32_bf16 v[54:57], v[196:199], v[94:97], v[54:57]
	v_mfma_f32_16x16x32_bf16 v[50:53], v[204:207], v[94:97], v[50:53]
	v_mfma_f32_16x16x32_bf16 v[46:49], v[196:199], v[208:211], v[46:49]
	v_mfma_f32_16x16x32_bf16 v[42:45], v[204:207], v[208:211], v[42:45]
	v_mfma_f32_16x16x32_bf16 v[38:41], v[196:199], v[216:219], v[38:41]
	v_mfma_f32_16x16x32_bf16 v[34:37], v[204:207], v[216:219], v[34:37]
	v_mfma_f32_16x16x32_bf16 v[122:125], v[200:203], v[78:81], v[86:89]
	v_mfma_f32_16x16x32_bf16 v[114:117], v[224:227], v[78:81], v[62:65]
	v_mfma_f32_16x16x32_bf16 v[110:113], v[200:203], v[192:195], v[54:57]
	v_mfma_f32_16x16x32_bf16 v[102:105], v[224:227], v[192:195], v[50:53]
	v_mfma_f32_16x16x32_bf16 v[94:97], v[200:203], v[212:215], v[46:49]
	v_mfma_f32_16x16x32_bf16 v[86:89], v[224:227], v[212:215], v[42:45]
	v_mfma_f32_16x16x32_bf16 v[78:81], v[200:203], v[220:223], v[38:41]
	v_mfma_f32_16x16x32_bf16 v[70:73], v[224:227], v[220:223], v[34:37]
	s_setprio 0
	s_barrier
	s_nop 0
	ds_read_b128 v[34:37], v141 offset:49152
	ds_read_b128 v[42:45], v141 offset:50176
	ds_read_b128 v[192:195], v141 offset:51200
	ds_read_b128 v[208:211], v141 offset:52224
	ds_read_b128 v[212:215], v141 offset:53248
	ds_read_b128 v[216:219], v141 offset:54272
	ds_read_b128 v[220:223], v141 offset:55296
	ds_read_b128 v[228:231], v141 offset:56320
	s_barrier
	s_waitcnt lgkmcnt(0)
	s_setprio 1
	s_waitcnt lgkmcnt(0)
	v_mfma_f32_16x16x32_bf16 v[30:33], v[176:179], v[34:37], v[30:33]
	v_mfma_f32_16x16x32_bf16 v[26:29], v[184:187], v[34:37], v[26:29]
	v_mfma_f32_16x16x32_bf16 v[22:25], v[176:179], v[192:195], v[22:25]
	v_mfma_f32_16x16x32_bf16 v[18:21], v[184:187], v[192:195], v[18:21]
	v_mfma_f32_16x16x32_bf16 v[14:17], v[176:179], v[212:215], v[14:17]
	v_mfma_f32_16x16x32_bf16 v[10:13], v[184:187], v[212:215], v[10:13]
	v_mfma_f32_16x16x32_bf16 v[6:9], v[176:179], v[220:223], v[6:9]
	v_mfma_f32_16x16x32_bf16 v[2:5], v[184:187], v[220:223], v[2:5]
	v_mfma_f32_16x16x32_bf16 v[62:65], v[180:183], v[42:45], v[30:33]
	v_mfma_f32_16x16x32_bf16 v[54:57], v[188:191], v[42:45], v[26:29]
	v_mfma_f32_16x16x32_bf16 v[46:49], v[180:183], v[208:211], v[22:25]
	v_mfma_f32_16x16x32_bf16 v[38:41], v[188:191], v[208:211], v[18:21]
	v_mfma_f32_16x16x32_bf16 v[30:33], v[180:183], v[216:219], v[14:17]
	v_mfma_f32_16x16x32_bf16 v[22:25], v[188:191], v[216:219], v[10:13]
	v_mfma_f32_16x16x32_bf16 v[14:17], v[180:183], v[228:231], v[6:9]
	v_mfma_f32_16x16x32_bf16 v[6:9], v[188:191], v[228:231], v[2:5]
	s_setprio 0
	s_setprio 1
	v_mfma_f32_16x16x32_bf16 v[2:5], v[196:199], v[34:37], v[58:61]
	v_mfma_f32_16x16x32_bf16 v[58:61], v[200:203], v[42:45], v[2:5]
	v_mfma_f32_16x16x32_bf16 v[2:5], v[204:207], v[34:37], v[144:147]
	v_mfma_f32_16x16x32_bf16 v[50:53], v[224:227], v[42:45], v[2:5]
	v_mfma_f32_16x16x32_bf16 v[2:5], v[196:199], v[192:195], v[148:151]
	v_mfma_f32_16x16x32_bf16 v[42:45], v[200:203], v[208:211], v[2:5]
	v_mfma_f32_16x16x32_bf16 v[2:5], v[204:207], v[192:195], v[156:159]
	v_mfma_f32_16x16x32_bf16 v[34:37], v[224:227], v[208:211], v[2:5]
	v_mfma_f32_16x16x32_bf16 v[2:5], v[196:199], v[212:215], v[160:163]
	v_mfma_f32_16x16x32_bf16 v[26:29], v[200:203], v[216:219], v[2:5]
	v_mfma_f32_16x16x32_bf16 v[2:5], v[204:207], v[212:215], v[164:167]
	v_mfma_f32_16x16x32_bf16 v[18:21], v[224:227], v[216:219], v[2:5]
	v_mfma_f32_16x16x32_bf16 v[2:5], v[196:199], v[220:223], v[168:171]
	v_mfma_f32_16x16x32_bf16 v[10:13], v[200:203], v[228:231], v[2:5]
	v_mfma_f32_16x16x32_bf16 v[2:5], v[204:207], v[220:223], v[172:175]
	v_mfma_f32_16x16x32_bf16 v[2:5], v[224:227], v[228:231], v[2:5]
	s_setprio 0
	s_barrier
	s_and_saveexec_b64 s[48:49], s[4:5]
	s_cbranch_execz .LBB0_458
	s_barrier

; #define LDA(dst, b, h)                                                                                     \
;   _Pragma("unroll") for (int m = 0; m < 4; ++m) _Pragma("unroll") for (int k = 0; k < 2; ++k) dst[m][k] = \
;       *reinterpret_cast<const bf16x8*>(shmc + aL + (((b) * 2 + (h)) * 16384 + (m * 2 + k) * 1024))
; #define LDB(dst, b, h)                                                                                     \
;   _Pragma("unroll") for (int n = 0; n < 2; ++n) _Pragma("unroll") for (int k = 0; k < 2; ++k) dst[n][k] = \
;       *reinterpret_cast<const bf16x8*>(shmc + bL + (((b) * 2 + (h)) * 16384 + (n * 2 + k) * 1024))
; #define OPAQ asm volatile("" : "+v"(aL), "+v"(bL))
; #define WAIT_V(n) asm volatile("s_waitcnt vmcnt(" #n ")" ::: "memory")
; #define WAIT_L(n) asm volatile("s_waitcnt lgkmcnt(" #n ")" ::: "memory")
; #define BAR __builtin_amdgcn_s_barrier()
; #define SCHED __builtin_amdgcn_sched_barrier(0)
; template <int EPI>
; __device__ __forceinline__ void phase_gemm(const Params& p, const GemmDesc& d, char* shmc) {
;     ...
;       OPAQ;
;       LDB(B0, 0, 0); SCHED; LDA(At, 0, 0); STAGE_A(SA(1, 1), 1, t + 1);
;       WAIT_L(8); BAR; WAIT_L(0); MMA(0, 0, At, B0); BAR; SCHED;
;       LDB(B1, 0, 1); STAGE_B(SB(0, 0), 0, t + 2);
;       BAR; WAIT_L(0); MMA(0, 1, At, B1); BAR;
;       LDA(At, 0, 1); STAGE_A(SA(0, 0), 0, t + 2);
;       BAR; WAIT_L(0); MMA(1, 0, At, B0); BAR; SCHED;
;       STAGE_B(SB(0, 1), 1, t + 2);
;       WAIT_V(6); BAR; MMA(1, 1, At, B1); BAR;
.LBB0_598:
	s_nop 0
	v_add_u32_e32 v175, 0, v179
	v_add_u32_e32 v176, 0, v177
	s_setprio 0
	ds_read_b128 v[138:141], v175
	ds_read_b128 v[142:145], v175 offset:1024
	ds_read_b128 v[146:149], v175 offset:2048
	ds_read_b128 v[150:153], v175 offset:3072
	ds_read_b128 v[206:209], v175 offset:16384
	ds_read_b128 v[210:213], v175 offset:17408
	ds_read_b128 v[214:217], v175 offset:18432
	ds_read_b128 v[218:221], v175 offset:19456
	ds_read_b128 v[154:157], v176
	ds_read_b128 v[158:161], v176 offset:1024
	ds_read_b128 v[182:185], v176 offset:2048
	ds_read_b128 v[186:189], v176 offset:3072
	ds_read_b128 v[190:193], v176 offset:4096
	ds_read_b128 v[194:197], v176 offset:5120
	ds_read_b128 v[198:201], v176 offset:6144
	ds_read_b128 v[202:205], v176 offset:7168
	s_add_i32 s88, s68, 0xc000
	s_mov_b32 m0, s88
	s_nop 0
	global_load_lds_dwordx4 v222, s[98:99]
	s_add_i32 s89, s68, 0xe000
	s_mov_b32 m0, s89
	s_nop 0
	global_load_lds_dwordx4 v223, s[98:99]
	s_waitcnt vmcnt(8) lgkmcnt(0)
	s_setprio 1
	s_barrier
	v_mfma_f32_16x16x32_bf16 v[126:129], v[154:157], v[138:141], v[126:129]
	v_mfma_f32_16x16x32_bf16 v[122:125], v[154:157], v[146:149], v[122:125]
	v_mfma_f32_16x16x32_bf16 v[118:121], v[182:185], v[138:141], v[118:121]
	v_mfma_f32_16x16x32_bf16 v[114:117], v[182:185], v[146:149], v[114:117]
	v_mfma_f32_16x16x32_bf16 v[110:113], v[190:193], v[138:141], v[110:113]
	v_mfma_f32_16x16x32_bf16 v[106:109], v[190:193], v[146:149], v[106:109]
	v_mfma_f32_16x16x32_bf16 v[102:105], v[198:201], v[138:141], v[102:105]
	v_mfma_f32_16x16x32_bf16 v[94:97], v[198:201], v[146:149], v[94:97]
	v_mfma_f32_16x16x32_bf16 v[126:129], v[158:161], v[142:145], v[126:129]
	v_mfma_f32_16x16x32_bf16 v[122:125], v[158:161], v[150:153], v[122:125]
	v_mfma_f32_16x16x32_bf16 v[118:121], v[186:189], v[142:145], v[118:121]
	v_mfma_f32_16x16x32_bf16 v[114:117], v[186:189], v[150:153], v[114:117]
	v_mfma_f32_16x16x32_bf16 v[110:113], v[194:197], v[142:145], v[110:113]
	v_mfma_f32_16x16x32_bf16 v[106:109], v[194:197], v[150:153], v[106:109]
	v_mfma_f32_16x16x32_bf16 v[102:105], v[202:205], v[142:145], v[102:105]
	v_mfma_f32_16x16x32_bf16 v[94:97], v[202:205], v[150:153], v[94:97]
	v_mfma_f32_16x16x32_bf16 v[50:53], v[154:157], v[206:209], v[50:53]
	v_mfma_f32_16x16x32_bf16 v[42:45], v[154:157], v[214:217], v[42:45]
	v_mfma_f32_16x16x32_bf16 v[38:41], v[182:185], v[206:209], v[38:41]
	v_mfma_f32_16x16x32_bf16 v[34:37], v[182:185], v[214:217], v[34:37]
	v_mfma_f32_16x16x32_bf16 v[30:33], v[190:193], v[206:209], v[30:33]
	v_mfma_f32_16x16x32_bf16 v[26:29], v[190:193], v[214:217], v[26:29]
	v_mfma_f32_16x16x32_bf16 v[22:25], v[198:201], v[206:209], v[22:25]
	v_mfma_f32_16x16x32_bf16 v[18:21], v[198:201], v[214:217], v[18:21]
	v_mfma_f32_16x16x32_bf16 v[50:53], v[158:161], v[210:213], v[50:53]
	v_mfma_f32_16x16x32_bf16 v[42:45], v[158:161], v[218:221], v[42:45]
	v_mfma_f32_16x16x32_bf16 v[38:41], v[186:189], v[210:213], v[38:41]
	v_mfma_f32_16x16x32_bf16 v[34:37], v[186:189], v[218:221], v[34:37]
	v_mfma_f32_16x16x32_bf16 v[30:33], v[194:197], v[210:213], v[30:33]
	v_mfma_f32_16x16x32_bf16 v[26:29], v[194:197], v[218:221], v[26:29]
	v_mfma_f32_16x16x32_bf16 v[22:25], v[202:205], v[210:213], v[22:25]
	v_mfma_f32_16x16x32_bf16 v[18:21], v[202:205], v[218:221], v[18:21]
	s_barrier
	s_setprio 0
	ds_read_b128 v[154:157], v176 offset:16384
	ds_read_b128 v[158:161], v176 offset:17408
	ds_read_b128 v[182:185], v176 offset:18432
	ds_read_b128 v[186:189], v176 offset:19456
	ds_read_b128 v[190:193], v176 offset:20480
	ds_read_b128 v[194:197], v176 offset:21504
	ds_read_b128 v[198:201], v176 offset:22528
	ds_read_b128 v[202:205], v176 offset:23552
	s_mov_b32 m0, s69
	s_nop 0
	global_load_lds_dwordx4 v224, s[100:101]
	s_mov_b32 m0, s70
	s_nop 0
	global_load_lds_dwordx4 v225, s[100:101]
	s_mov_b32 m0, s68
	s_nop 0
	global_load_lds_dwordx4 v226, s[98:99]
	s_mov_b32 m0, s71
	s_nop 0
	global_load_lds_dwordx4 v227, s[98:99]
	s_mov_b32 m0, s76
	s_nop 0
	global_load_lds_dwordx4 v228, s[100:101]
	s_mov_b32 m0, s77
	s_nop 0
	global_load_lds_dwordx4 v229, s[100:101]
	s_waitcnt vmcnt(8) lgkmcnt(0)
	s_setprio 1
	s_barrier
	v_mfma_f32_16x16x32_bf16 v[14:17], v[154:157], v[138:141], v[14:17]
	v_mfma_f32_16x16x32_bf16 v[10:13], v[154:157], v[146:149], v[10:13]
	v_mfma_f32_16x16x32_bf16 v[6:9], v[182:185], v[138:141], v[6:9]
	v_mfma_f32_16x16x32_bf16 v[2:5], v[182:185], v[146:149], v[2:5]
	v_mfma_f32_16x16x32_bf16 v[46:49], v[190:193], v[138:141], v[46:49]
	v_mfma_f32_16x16x32_bf16 v[54:57], v[190:193], v[146:149], v[54:57]
	v_mfma_f32_16x16x32_bf16 v[58:61], v[198:201], v[138:141], v[58:61]
	v_mfma_f32_16x16x32_bf16 v[62:65], v[198:201], v[146:149], v[62:65]
	v_mfma_f32_16x16x32_bf16 v[14:17], v[158:161], v[142:145], v[14:17]
	v_mfma_f32_16x16x32_bf16 v[10:13], v[158:161], v[150:153], v[10:13]
	v_mfma_f32_16x16x32_bf16 v[6:9], v[186:189], v[142:145], v[6:9]
	v_mfma_f32_16x16x32_bf16 v[2:5], v[186:189], v[150:153], v[2:5]
	v_mfma_f32_16x16x32_bf16 v[46:49], v[194:197], v[142:145], v[46:49]
	v_mfma_f32_16x16x32_bf16 v[54:57], v[194:197], v[150:153], v[54:57]
	v_mfma_f32_16x16x32_bf16 v[58:61], v[202:205], v[142:145], v[58:61]
	v_mfma_f32_16x16x32_bf16 v[62:65], v[202:205], v[150:153], v[62:65]
	v_mfma_f32_16x16x32_bf16 v[66:69], v[154:157], v[206:209], v[66:69]
	v_mfma_f32_16x16x32_bf16 v[70:73], v[154:157], v[214:217], v[70:73]
	v_mfma_f32_16x16x32_bf16 v[74:77], v[182:185], v[206:209], v[74:77]
	v_mfma_f32_16x16x32_bf16 v[78:81], v[182:185], v[214:217], v[78:81]
	v_mfma_f32_16x16x32_bf16 v[82:85], v[190:193], v[206:209], v[82:85]
	v_mfma_f32_16x16x32_bf16 v[86:89], v[190:193], v[214:217], v[86:89]
	v_mfma_f32_16x16x32_bf16 v[90:93], v[198:201], v[206:209], v[90:93]
	v_mfma_f32_16x16x32_bf16 v[98:101], v[198:201], v[214:217], v[98:101]
	v_mfma_f32_16x16x32_bf16 v[66:69], v[158:161], v[210:213], v[66:69]
	v_mfma_f32_16x16x32_bf16 v[70:73], v[158:161], v[218:221], v[70:73]
	v_mfma_f32_16x16x32_bf16 v[74:77], v[186:189], v[210:213], v[74:77]
	v_mfma_f32_16x16x32_bf16 v[78:81], v[186:189], v[218:221], v[78:81]
	v_mfma_f32_16x16x32_bf16 v[82:85], v[194:197], v[210:213], v[82:85]
	v_mfma_f32_16x16x32_bf16 v[86:89], v[194:197], v[218:221], v[86:89]
	v_mfma_f32_16x16x32_bf16 v[90:93], v[202:205], v[210:213], v[90:93]
	v_mfma_f32_16x16x32_bf16 v[98:101], v[202:205], v[218:221], v[98:101]
	s_barrier
; #define LDA(dst, b, h)                                                                                     \
;   _Pragma("unroll") for (int m = 0; m < 4; ++m) _Pragma("unroll") for (int k = 0; k < 2; ++k) dst[m][k] = \
;       *reinterpret_cast<const bf16x8*>(shmc + aL + (((b) * 2 + (h)) * 16384 + (m * 2 + k) * 1024))
; #define LDB(dst, b, h)                                                                                     \
;   _Pragma("unroll") for (int n = 0; n < 2; ++n) _Pragma("unroll") for (int k = 0; k < 2; ++k) dst[n][k] = \
;       *reinterpret_cast<const bf16x8*>(shmc + bL + (((b) * 2 + (h)) * 16384 + (n * 2 + k) * 1024))
; #define WAIT_V(n) asm volatile("s_waitcnt vmcnt(" #n ")" ::: "memory")
; #define WAIT_L(n) asm volatile("s_waitcnt lgkmcnt(" #n ")" ::: "memory")
; #define BAR __builtin_amdgcn_s_barrier()
; #define SCHED __builtin_amdgcn_sched_barrier(0)
; template <int EPI>
; __device__ __forceinline__ void phase_gemm(const Params& p, const GemmDesc& d, char* shmc) {
;     ...
;       LDB(B0, 1, 0); SCHED; LDA(At, 1, 0); STAGE_A(SA(0, 1), 1, t + 2);
;       WAIT_L(8); BAR; WAIT_L(0); MMA(0, 0, At, B0); BAR; SCHED;
;       LDB(B1, 1, 1); STAGE_B(SB(1, 0), 0, t + 3);
;       BAR; WAIT_L(0); MMA(0, 1, At, B1); BAR;
;       LDA(At, 1, 1); STAGE_A(SA(1, 0), 0, t + 3);
;       BAR; WAIT_L(0); MMA(1, 0, At, B0); BAR; SCHED;
;       STAGE_B(SB(1, 1), 1, t + 3);
;       WAIT_V(6); BAR; MMA(1, 1, At, B1); BAR;
;     }
	s_setprio 0
	ds_read_b128 v[138:141], v175 offset:32768
	ds_read_b128 v[142:145], v175 offset:33792
	ds_read_b128 v[146:149], v175 offset:34816
	ds_read_b128 v[150:153], v175 offset:35840
	ds_read_b128 v[206:209], v175 offset:49152
	ds_read_b128 v[210:213], v175 offset:50176
	ds_read_b128 v[214:217], v175 offset:51200
	ds_read_b128 v[218:221], v175 offset:52224
	ds_read_b128 v[154:157], v176 offset:32768
	ds_read_b128 v[158:161], v176 offset:33792
	ds_read_b128 v[182:185], v176 offset:34816
	ds_read_b128 v[186:189], v176 offset:35840
	ds_read_b128 v[190:193], v176 offset:36864
	ds_read_b128 v[194:197], v176 offset:37888
	ds_read_b128 v[198:201], v176 offset:38912
	ds_read_b128 v[202:205], v176 offset:39936
	s_mov_b32 m0, s80
	s_nop 0
	global_load_lds_dwordx4 v230, s[98:99]
	s_mov_b32 m0, s81
	s_nop 0
	global_load_lds_dwordx4 v231, s[98:99]
	s_waitcnt vmcnt(8) lgkmcnt(0)
	s_setprio 1
	s_barrier
	v_mfma_f32_16x16x32_bf16 v[126:129], v[154:157], v[138:141], v[126:129]
	v_mfma_f32_16x16x32_bf16 v[122:125], v[154:157], v[146:149], v[122:125]
	v_mfma_f32_16x16x32_bf16 v[118:121], v[182:185], v[138:141], v[118:121]
	v_mfma_f32_16x16x32_bf16 v[114:117], v[182:185], v[146:149], v[114:117]
	v_mfma_f32_16x16x32_bf16 v[110:113], v[190:193], v[138:141], v[110:113]
	v_mfma_f32_16x16x32_bf16 v[106:109], v[190:193], v[146:149], v[106:109]
	v_mfma_f32_16x16x32_bf16 v[102:105], v[198:201], v[138:141], v[102:105]
	v_mfma_f32_16x16x32_bf16 v[94:97], v[198:201], v[146:149], v[94:97]
	v_mfma_f32_16x16x32_bf16 v[126:129], v[158:161], v[142:145], v[126:129]
	v_mfma_f32_16x16x32_bf16 v[122:125], v[158:161], v[150:153], v[122:125]
	v_mfma_f32_16x16x32_bf16 v[118:121], v[186:189], v[142:145], v[118:121]
	v_mfma_f32_16x16x32_bf16 v[114:117], v[186:189], v[150:153], v[114:117]
	v_mfma_f32_16x16x32_bf16 v[110:113], v[194:197], v[142:145], v[110:113]
	v_mfma_f32_16x16x32_bf16 v[106:109], v[194:197], v[150:153], v[106:109]
	v_mfma_f32_16x16x32_bf16 v[102:105], v[202:205], v[142:145], v[102:105]
	v_mfma_f32_16x16x32_bf16 v[94:97], v[202:205], v[150:153], v[94:97]
	v_mfma_f32_16x16x32_bf16 v[50:53], v[154:157], v[206:209], v[50:53]
	v_mfma_f32_16x16x32_bf16 v[42:45], v[154:157], v[214:217], v[42:45]
	v_mfma_f32_16x16x32_bf16 v[38:41], v[182:185], v[206:209], v[38:41]
	v_mfma_f32_16x16x32_bf16 v[34:37], v[182:185], v[214:217], v[34:37]
	v_mfma_f32_16x16x32_bf16 v[30:33], v[190:193], v[206:209], v[30:33]
	v_mfma_f32_16x16x32_bf16 v[26:29], v[190:193], v[214:217], v[26:29]
	v_mfma_f32_16x16x32_bf16 v[22:25], v[198:201], v[206:209], v[22:25]
	v_mfma_f32_16x16x32_bf16 v[18:21], v[198:201], v[214:217], v[18:21]
	v_mfma_f32_16x16x32_bf16 v[50:53], v[158:161], v[210:213], v[50:53]
	v_mfma_f32_16x16x32_bf16 v[42:45], v[158:161], v[218:221], v[42:45]
	v_mfma_f32_16x16x32_bf16 v[38:41], v[186:189], v[210:213], v[38:41]
	v_mfma_f32_16x16x32_bf16 v[34:37], v[186:189], v[218:221], v[34:37]
	v_mfma_f32_16x16x32_bf16 v[30:33], v[194:197], v[210:213], v[30:33]
	v_mfma_f32_16x16x32_bf16 v[26:29], v[194:197], v[218:221], v[26:29]
	v_mfma_f32_16x16x32_bf16 v[22:25], v[202:205], v[210:213], v[22:25]
	v_mfma_f32_16x16x32_bf16 v[18:21], v[202:205], v[218:221], v[18:21]
	s_barrier
	s_setprio 0
	ds_read_b128 v[154:157], v176 offset:49152
	ds_read_b128 v[158:161], v176 offset:50176
	ds_read_b128 v[182:185], v176 offset:51200
	ds_read_b128 v[186:189], v176 offset:52224
	ds_read_b128 v[190:193], v176 offset:53248
	ds_read_b128 v[194:197], v176 offset:54272
	ds_read_b128 v[198:201], v176 offset:55296
	ds_read_b128 v[202:205], v176 offset:56320
	s_mov_b32 m0, s61
	s_nop 0
	global_load_lds_dwordx4 v232, s[100:101]
	s_mov_b32 m0, s78
	s_nop 0
	global_load_lds_dwordx4 v233, s[100:101]
	s_mov_b32 m0, s79
	s_nop 0
	global_load_lds_dwordx4 v234, s[98:99]
	s_mov_b32 m0, s86
	s_nop 0
	global_load_lds_dwordx4 v235, s[98:99]
	s_mov_b32 m0, s64
	s_nop 0
	global_load_lds_dwordx4 v236, s[100:101]
	s_mov_b32 m0, s65
	s_nop 0
	global_load_lds_dwordx4 v237, s[100:101]
	s_add_i32 s87, s87, 2
	s_add_u32 s62, s62, 0x100
	s_addc_u32 s63, s63, 0
	s_add_u32 s98, s98, 0x100
	s_addc_u32 s99, s99, 0
	s_add_u32 s100, s100, 0x100
	s_addc_u32 s101, s101, 0
	s_cmp_gt_u32 s87, 27
	s_waitcnt vmcnt(8) lgkmcnt(0)
	s_setprio 1
	s_barrier
	v_mfma_f32_16x16x32_bf16 v[14:17], v[154:157], v[138:141], v[14:17]
	v_mfma_f32_16x16x32_bf16 v[10:13], v[154:157], v[146:149], v[10:13]
	v_mfma_f32_16x16x32_bf16 v[6:9], v[182:185], v[138:141], v[6:9]
	v_mfma_f32_16x16x32_bf16 v[2:5], v[182:185], v[146:149], v[2:5]
	v_mfma_f32_16x16x32_bf16 v[46:49], v[190:193], v[138:141], v[46:49]
	v_mfma_f32_16x16x32_bf16 v[54:57], v[190:193], v[146:149], v[54:57]
	v_mfma_f32_16x16x32_bf16 v[58:61], v[198:201], v[138:141], v[58:61]
	v_mfma_f32_16x16x32_bf16 v[62:65], v[198:201], v[146:149], v[62:65]
	v_mfma_f32_16x16x32_bf16 v[14:17], v[158:161], v[142:145], v[14:17]
	v_mfma_f32_16x16x32_bf16 v[10:13], v[158:161], v[150:153], v[10:13]
	v_mfma_f32_16x16x32_bf16 v[6:9], v[186:189], v[142:145], v[6:9]
	v_mfma_f32_16x16x32_bf16 v[2:5], v[186:189], v[150:153], v[2:5]
	v_mfma_f32_16x16x32_bf16 v[46:49], v[194:197], v[142:145], v[46:49]
	v_mfma_f32_16x16x32_bf16 v[54:57], v[194:197], v[150:153], v[54:57]
	v_mfma_f32_16x16x32_bf16 v[58:61], v[202:205], v[142:145], v[58:61]
	v_mfma_f32_16x16x32_bf16 v[62:65], v[202:205], v[150:153], v[62:65]
	v_mfma_f32_16x16x32_bf16 v[66:69], v[154:157], v[206:209], v[66:69]
	v_mfma_f32_16x16x32_bf16 v[70:73], v[154:157], v[214:217], v[70:73]
	v_mfma_f32_16x16x32_bf16 v[74:77], v[182:185], v[206:209], v[74:77]
	v_mfma_f32_16x16x32_bf16 v[78:81], v[182:185], v[214:217], v[78:81]
	v_mfma_f32_16x16x32_bf16 v[82:85], v[190:193], v[206:209], v[82:85]
	v_mfma_f32_16x16x32_bf16 v[86:89], v[190:193], v[214:217], v[86:89]
	v_mfma_f32_16x16x32_bf16 v[90:93], v[198:201], v[206:209], v[90:93]
	v_mfma_f32_16x16x32_bf16 v[98:101], v[198:201], v[214:217], v[98:101]
	v_mfma_f32_16x16x32_bf16 v[66:69], v[158:161], v[210:213], v[66:69]
	v_mfma_f32_16x16x32_bf16 v[70:73], v[158:161], v[218:221], v[70:73]
	v_mfma_f32_16x16x32_bf16 v[74:77], v[186:189], v[210:213], v[74:77]
	v_mfma_f32_16x16x32_bf16 v[78:81], v[186:189], v[218:221], v[78:81]
	v_mfma_f32_16x16x32_bf16 v[82:85], v[194:197], v[210:213], v[82:85]
	v_mfma_f32_16x16x32_bf16 v[86:89], v[194:197], v[218:221], v[86:89]
	v_mfma_f32_16x16x32_bf16 v[90:93], v[202:205], v[210:213], v[90:93]
	v_mfma_f32_16x16x32_bf16 v[98:101], v[202:205], v[218:221], v[98:101]
	s_barrier
; #define LDA(dst, b, h)                                                                                     \
;   _Pragma("unroll") for (int m = 0; m < 4; ++m) _Pragma("unroll") for (int k = 0; k < 2; ++k) dst[m][k] = \
;       *reinterpret_cast<const bf16x8*>(shmc + aL + (((b) * 2 + (h)) * 16384 + (m * 2 + k) * 1024))
; #define LDB(dst, b, h)                                                                                     \
;   _Pragma("unroll") for (int n = 0; n < 2; ++n) _Pragma("unroll") for (int k = 0; k < 2; ++k) dst[n][k] = \
;       *reinterpret_cast<const bf16x8*>(shmc + bL + (((b) * 2 + (h)) * 16384 + (n * 2 + k) * 1024))
; #define OPAQ asm volatile("" : "+v"(aL), "+v"(bL))
; #define WAIT_V(n) asm volatile("s_waitcnt vmcnt(" #n ")" ::: "memory")
; #define WAIT_L(n) asm volatile("s_waitcnt lgkmcnt(" #n ")" ::: "memory")
; #define BAR __builtin_amdgcn_s_barrier()
; template <int EPI>
; __device__ __forceinline__ void phase_gemm(const Params& p, const GemmDesc& d, char* shmc) {
;     ...
;     {
;       OPAQ;
;       LDB(B0, 0, 0); LDA(At, 0, 0); STAGE_A(SA(1, 1), 1, nt - 1);
;       BAR; WAIT_L(0); MMA(0, 0, At, B0); BAR;
;       LDB(B1, 0, 1); BAR; WAIT_L(0); MMA(0, 1, At, B1); BAR;
;       LDA(At, 0, 1); WAIT_V(4); BAR; WAIT_L(0); MMA(1, 0, At, B0); MMA(1, 1, At, B1); BAR;
;     }
	s_cbranch_scc0 .LBB0_598
	s_setprio 0
	s_add_u32 s8, s8, 0x80f80
	s_addc_u32 s9, s9, 0
	v_add_u32_e32 v175, 0, v179
	v_add_u32_e32 v176, 0, v177
	s_mov_b32 m0, s88
	ds_read_b128 v[130:133], v175
	ds_read_b128 v[134:137], v175 offset:1024
	ds_read_b128 v[138:141], v175 offset:2048
	ds_read_b128 v[142:145], v175 offset:3072
	ds_read_b128 v[146:149], v176
	ds_read_b128 v[150:153], v176 offset:1024
	ds_read_b128 v[154:157], v176 offset:2048
	ds_read_b128 v[158:161], v176 offset:3072
	ds_read_b128 v[182:185], v176 offset:4096
	ds_read_b128 v[186:189], v176 offset:5120
	ds_read_b128 v[190:193], v176 offset:6144
	ds_read_b128 v[194:197], v176 offset:7168
	global_load_lds_dwordx4 v162, s[8:9]
	s_mov_b32 m0, s89
	s_nop 0
	global_load_lds_dwordx4 v174, s[8:9]
	s_waitcnt vmcnt(8)
	s_barrier
	s_waitcnt lgkmcnt(0)
	s_setprio 1
	s_waitcnt lgkmcnt(0)
	v_mfma_f32_16x16x32_bf16 v[126:129], v[146:149], v[130:133], v[126:129]
	v_mfma_f32_16x16x32_bf16 v[122:125], v[146:149], v[138:141], v[122:125]
	v_mfma_f32_16x16x32_bf16 v[114:117], v[154:157], v[138:141], v[114:117]
	v_mfma_f32_16x16x32_bf16 v[110:113], v[182:185], v[130:133], v[110:113]
	v_mfma_f32_16x16x32_bf16 v[126:129], v[150:153], v[134:137], v[126:129]
	v_mfma_f32_16x16x32_bf16 v[122:125], v[150:153], v[142:145], v[122:125]
	v_mfma_f32_16x16x32_bf16 v[118:121], v[154:157], v[130:133], v[118:121]
	v_mfma_f32_16x16x32_bf16 v[114:117], v[158:161], v[142:145], v[114:117]
	v_mfma_f32_16x16x32_bf16 v[110:113], v[186:189], v[134:137], v[110:113]
	v_mfma_f32_16x16x32_bf16 v[106:109], v[182:185], v[138:141], v[106:109]
	v_mfma_f32_16x16x32_bf16 v[102:105], v[190:193], v[130:133], v[102:105]
	v_mfma_f32_16x16x32_bf16 v[94:97], v[190:193], v[138:141], v[94:97]
	v_mfma_f32_16x16x32_bf16 v[118:121], v[158:161], v[134:137], v[118:121]
	v_mfma_f32_16x16x32_bf16 v[106:109], v[186:189], v[142:145], v[106:109]
	v_mfma_f32_16x16x32_bf16 v[102:105], v[194:197], v[134:137], v[102:105]
	v_mfma_f32_16x16x32_bf16 v[94:97], v[194:197], v[142:145], v[94:97]
	s_setprio 0
	s_barrier
	ds_read_b128 v[198:201], v175 offset:16384
	ds_read_b128 v[202:205], v175 offset:17408
	ds_read_b128 v[206:209], v175 offset:18432
	ds_read_b128 v[210:213], v175 offset:19456
	s_barrier
	s_waitcnt lgkmcnt(0)
	s_setprio 1
	s_waitcnt lgkmcnt(0)
	v_mfma_f32_16x16x32_bf16 v[50:53], v[146:149], v[198:201], v[50:53]
	v_mfma_f32_16x16x32_bf16 v[42:45], v[146:149], v[206:209], v[42:45]
	v_mfma_f32_16x16x32_bf16 v[38:41], v[154:157], v[198:201], v[38:41]
	v_mfma_f32_16x16x32_bf16 v[30:33], v[182:185], v[198:201], v[30:33]
	v_mfma_f32_16x16x32_bf16 v[22:25], v[190:193], v[198:201], v[22:25]
	v_mfma_f32_16x16x32_bf16 v[50:53], v[150:153], v[202:205], v[50:53]
	v_mfma_f32_16x16x32_bf16 v[42:45], v[150:153], v[210:213], v[42:45]
	v_mfma_f32_16x16x32_bf16 v[38:41], v[158:161], v[202:205], v[38:41]
	v_mfma_f32_16x16x32_bf16 v[34:37], v[154:157], v[206:209], v[34:37]
	v_mfma_f32_16x16x32_bf16 v[30:33], v[186:189], v[202:205], v[30:33]
	v_mfma_f32_16x16x32_bf16 v[26:29], v[182:185], v[206:209], v[26:29]
	v_mfma_f32_16x16x32_bf16 v[22:25], v[194:197], v[202:205], v[22:25]
	v_mfma_f32_16x16x32_bf16 v[18:21], v[190:193], v[206:209], v[18:21]
	v_mfma_f32_16x16x32_bf16 v[34:37], v[158:161], v[210:213], v[34:37]
	v_mfma_f32_16x16x32_bf16 v[26:29], v[186:189], v[210:213], v[26:29]
	v_mfma_f32_16x16x32_bf16 v[18:21], v[194:197], v[210:213], v[18:21]
	s_setprio 0
	s_barrier
	ds_read_b128 v[146:149], v176 offset:16384
	ds_read_b128 v[150:153], v176 offset:17408
	ds_read_b128 v[154:157], v176 offset:18432
	ds_read_b128 v[158:161], v176 offset:19456
	ds_read_b128 v[182:185], v176 offset:20480
	ds_read_b128 v[186:189], v176 offset:21504
	ds_read_b128 v[190:193], v176 offset:22528
	ds_read_b128 v[194:197], v176 offset:23552
	s_waitcnt vmcnt(4)
	s_barrier
	s_waitcnt lgkmcnt(0)
	s_setprio 1
	s_waitcnt lgkmcnt(0)
	v_mfma_f32_16x16x32_bf16 v[14:17], v[146:149], v[130:133], v[14:17]
	v_mfma_f32_16x16x32_bf16 v[6:9], v[154:157], v[130:133], v[6:9]
	v_mfma_f32_16x16x32_bf16 v[2:5], v[154:157], v[138:141], v[2:5]
	v_mfma_f32_16x16x32_bf16 v[46:49], v[182:185], v[130:133], v[46:49]
	v_mfma_f32_16x16x32_bf16 v[54:57], v[182:185], v[138:141], v[54:57]
	v_mfma_f32_16x16x32_bf16 v[58:61], v[190:193], v[130:133], v[58:61]
	v_mfma_f32_16x16x32_bf16 v[14:17], v[150:153], v[134:137], v[14:17]
	v_mfma_f32_16x16x32_bf16 v[10:13], v[146:149], v[138:141], v[10:13]
	v_mfma_f32_16x16x32_bf16 v[6:9], v[158:161], v[134:137], v[6:9]
	v_mfma_f32_16x16x32_bf16 v[2:5], v[158:161], v[142:145], v[2:5]
	v_mfma_f32_16x16x32_bf16 v[46:49], v[186:189], v[134:137], v[46:49]
	v_mfma_f32_16x16x32_bf16 v[54:57], v[186:189], v[142:145], v[54:57]
	v_mfma_f32_16x16x32_bf16 v[214:217], v[194:197], v[134:137], v[58:61]
	v_mfma_f32_16x16x32_bf16 v[58:61], v[190:193], v[138:141], v[62:65]
	v_mfma_f32_16x16x32_bf16 v[10:13], v[150:153], v[142:145], v[10:13]
	v_mfma_f32_16x16x32_bf16 v[218:221], v[194:197], v[142:145], v[58:61]
	s_setprio 0
	s_setprio 1
	v_mfma_f32_16x16x32_bf16 v[58:61], v[146:149], v[198:201], v[66:69]
	v_mfma_f32_16x16x32_bf16 v[222:225], v[150:153], v[202:205], v[58:61]
	v_mfma_f32_16x16x32_bf16 v[58:61], v[146:149], v[206:209], v[70:73]
	v_mfma_f32_16x16x32_bf16 v[226:229], v[150:153], v[210:213], v[58:61]
	v_mfma_f32_16x16x32_bf16 v[58:61], v[154:157], v[198:201], v[74:77]
	v_mfma_f32_16x16x32_bf16 v[230:233], v[158:161], v[202:205], v[58:61]
	v_mfma_f32_16x16x32_bf16 v[58:61], v[154:157], v[206:209], v[78:81]
	v_mfma_f32_16x16x32_bf16 v[234:237], v[158:161], v[210:213], v[58:61]
	v_mfma_f32_16x16x32_bf16 v[58:61], v[182:185], v[198:201], v[82:85]
	v_mfma_f32_16x16x32_bf16 v[238:241], v[186:189], v[202:205], v[58:61]
	v_mfma_f32_16x16x32_bf16 v[58:61], v[182:185], v[206:209], v[86:89]
	v_mfma_f32_16x16x32_bf16 v[182:185], v[186:189], v[210:213], v[58:61]
	v_mfma_f32_16x16x32_bf16 v[58:61], v[190:193], v[198:201], v[90:93]
	v_mfma_f32_16x16x32_bf16 v[186:189], v[194:197], v[202:205], v[58:61]
	v_mfma_f32_16x16x32_bf16 v[58:61], v[190:193], v[206:209], v[98:101]
	v_mfma_f32_16x16x32_bf16 v[190:193], v[194:197], v[210:213], v[58:61]
	s_setprio 0
	s_barrier
; #define LDA(dst, b, h)                                                                                     \
;   _Pragma("unroll") for (int m = 0; m < 4; ++m) _Pragma("unroll") for (int k = 0; k < 2; ++k) dst[m][k] = \
;       *reinterpret_cast<const bf16x8*>(shmc + aL + (((b) * 2 + (h)) * 16384 + (m * 2 + k) * 1024))
; #define LDB(dst, b, h)                                                                                     \
;   _Pragma("unroll") for (int n = 0; n < 2; ++n) _Pragma("unroll") for (int k = 0; k < 2; ++k) dst[n][k] = \
;       *reinterpret_cast<const bf16x8*>(shmc + bL + (((b) * 2 + (h)) * 16384 + (n * 2 + k) * 1024))
; #define WAIT_V(n) asm volatile("s_waitcnt vmcnt(" #n ")" ::: "memory")
; #define WAIT_L(n) asm volatile("s_waitcnt lgkmcnt(" #n ")" ::: "memory")
; #define BAR __builtin_amdgcn_s_barrier()
; template <int EPI>
; __device__ __forceinline__ void phase_gemm(const Params& p, const GemmDesc& d, char* shmc) {
;     ...
;     {
;       LDB(B0, 1, 0); LDA(At, 1, 0); WAIT_V(2); BAR; WAIT_L(0); MMA(0, 0, At, B0); BAR;
;       LDB(B1, 1, 1); WAIT_V(0); BAR; WAIT_L(0); MMA(0, 1, At, B1); BAR;
;       LDA(At, 1, 1); BAR; WAIT_L(0); MMA(1, 0, At, B0); MMA(1, 1, At, B1); BAR;
;     }
;     if (wr == 0) BAR;
	ds_read_b128 v[66:69], v175 offset:32768
	ds_read_b128 v[194:197], v175 offset:33792
	ds_read_b128 v[198:201], v175 offset:34816
	ds_read_b128 v[202:205], v175 offset:35840
	s_nop 0
	ds_read_b128 v[58:61], v176 offset:32768
	ds_read_b128 v[62:65], v176 offset:33792
	ds_read_b128 v[70:73], v176 offset:34816
	ds_read_b128 v[74:77], v176 offset:35840
	ds_read_b128 v[78:81], v176 offset:36864
	ds_read_b128 v[82:85], v176 offset:37888
	ds_read_b128 v[206:209], v176 offset:38912
	ds_read_b128 v[210:213], v176 offset:39936
	s_waitcnt vmcnt(2)
	s_barrier
	s_waitcnt lgkmcnt(0)
	s_setprio 1
	s_waitcnt lgkmcnt(0)
	v_mfma_f32_16x16x32_bf16 v[86:89], v[58:61], v[66:69], v[126:129]
	v_mfma_f32_16x16x32_bf16 v[158:161], v[62:65], v[194:197], v[86:89]
	v_mfma_f32_16x16x32_bf16 v[86:89], v[58:61], v[198:201], v[122:125]
	v_mfma_f32_16x16x32_bf16 v[142:145], v[62:65], v[202:205], v[86:89]
	v_mfma_f32_16x16x32_bf16 v[86:89], v[70:73], v[66:69], v[118:121]
	v_mfma_f32_16x16x32_bf16 v[154:157], v[74:77], v[194:197], v[86:89]
	v_mfma_f32_16x16x32_bf16 v[86:89], v[70:73], v[198:201], v[114:117]
	v_mfma_f32_16x16x32_bf16 v[138:141], v[74:77], v[202:205], v[86:89]
	v_mfma_f32_16x16x32_bf16 v[86:89], v[78:81], v[66:69], v[110:113]
	v_mfma_f32_16x16x32_bf16 v[150:153], v[82:85], v[194:197], v[86:89]
	v_mfma_f32_16x16x32_bf16 v[86:89], v[78:81], v[198:201], v[106:109]
	v_mfma_f32_16x16x32_bf16 v[134:137], v[82:85], v[202:205], v[86:89]
	v_mfma_f32_16x16x32_bf16 v[86:89], v[206:209], v[66:69], v[102:105]
	v_mfma_f32_16x16x32_bf16 v[146:149], v[210:213], v[194:197], v[86:89]
	v_mfma_f32_16x16x32_bf16 v[86:89], v[206:209], v[198:201], v[94:97]
	v_mfma_f32_16x16x32_bf16 v[130:133], v[210:213], v[202:205], v[86:89]
	s_setprio 0
	s_barrier
	ds_read_b128 v[94:97], v175 offset:49152
	ds_read_b128 v[102:105], v175 offset:50176
	ds_read_b128 v[106:109], v175 offset:51200
	ds_read_b128 v[118:121], v175 offset:52224
	s_waitcnt vmcnt(0)
	s_barrier
	s_waitcnt lgkmcnt(0)
	s_setprio 1
	s_waitcnt lgkmcnt(0)
	v_mfma_f32_16x16x32_bf16 v[50:53], v[58:61], v[94:97], v[50:53]
	v_mfma_f32_16x16x32_bf16 v[42:45], v[58:61], v[106:109], v[42:45]
	v_mfma_f32_16x16x32_bf16 v[38:41], v[70:73], v[94:97], v[38:41]
	v_mfma_f32_16x16x32_bf16 v[34:37], v[70:73], v[106:109], v[34:37]
	v_mfma_f32_16x16x32_bf16 v[30:33], v[78:81], v[94:97], v[30:33]
	v_mfma_f32_16x16x32_bf16 v[26:29], v[78:81], v[106:109], v[26:29]
	v_mfma_f32_16x16x32_bf16 v[22:25], v[206:209], v[94:97], v[22:25]
	v_mfma_f32_16x16x32_bf16 v[18:21], v[206:209], v[106:109], v[18:21]
	v_mfma_f32_16x16x32_bf16 v[126:129], v[62:65], v[102:105], v[50:53]
	v_mfma_f32_16x16x32_bf16 v[98:101], v[62:65], v[118:121], v[42:45]
	v_mfma_f32_16x16x32_bf16 v[122:125], v[74:77], v[102:105], v[38:41]
	v_mfma_f32_16x16x32_bf16 v[90:93], v[74:77], v[118:121], v[34:37]
	v_mfma_f32_16x16x32_bf16 v[114:117], v[82:85], v[102:105], v[30:33]
	v_mfma_f32_16x16x32_bf16 v[86:89], v[82:85], v[118:121], v[26:29]
	v_mfma_f32_16x16x32_bf16 v[110:113], v[210:213], v[102:105], v[22:25]
	v_mfma_f32_16x16x32_bf16 v[82:85], v[210:213], v[118:121], v[18:21]
	s_setprio 0
	s_barrier
	s_nop 0
	ds_read_b128 v[18:21], v176 offset:49152
	ds_read_b128 v[22:25], v176 offset:50176
	ds_read_b128 v[26:29], v176 offset:51200
	ds_read_b128 v[30:33], v176 offset:52224
	ds_read_b128 v[34:37], v176 offset:53248
	ds_read_b128 v[206:209], v176 offset:54272
	ds_read_b128 v[210:213], v176 offset:55296
	ds_read_b128 v[242:245], v176 offset:56320
	s_barrier
	s_waitcnt lgkmcnt(0)
	s_setprio 1
	s_waitcnt lgkmcnt(0)
	v_mfma_f32_16x16x32_bf16 v[2:5], v[26:29], v[198:201], v[2:5]
	v_mfma_f32_16x16x32_bf16 v[58:61], v[30:33], v[202:205], v[2:5]
	v_mfma_f32_16x16x32_bf16 v[2:5], v[34:37], v[66:69], v[46:49]
	v_mfma_f32_16x16x32_bf16 v[70:73], v[206:209], v[194:197], v[2:5]
	v_mfma_f32_16x16x32_bf16 v[2:5], v[34:37], v[198:201], v[54:57]
	v_mfma_f32_16x16x32_bf16 v[54:57], v[206:209], v[202:205], v[2:5]
	v_mfma_f32_16x16x32_bf16 v[2:5], v[210:213], v[66:69], v[214:217]
	v_mfma_f32_16x16x32_bf16 v[14:17], v[18:21], v[66:69], v[14:17]
	v_mfma_f32_16x16x32_bf16 v[10:13], v[18:21], v[198:201], v[10:13]
	v_mfma_f32_16x16x32_bf16 v[6:9], v[26:29], v[66:69], v[6:9]
	v_mfma_f32_16x16x32_bf16 v[66:69], v[242:245], v[194:197], v[2:5]
	v_mfma_f32_16x16x32_bf16 v[2:5], v[210:213], v[198:201], v[218:221]
	v_mfma_f32_16x16x32_bf16 v[78:81], v[22:25], v[194:197], v[14:17]
	v_mfma_f32_16x16x32_bf16 v[62:65], v[22:25], v[202:205], v[10:13]
	v_mfma_f32_16x16x32_bf16 v[74:77], v[30:33], v[194:197], v[6:9]
	v_mfma_f32_16x16x32_bf16 v[50:53], v[242:245], v[202:205], v[2:5]
	s_setprio 0
	s_setprio 1
	v_mfma_f32_16x16x32_bf16 v[2:5], v[18:21], v[94:97], v[222:225]
	v_mfma_f32_16x16x32_bf16 v[46:49], v[22:25], v[102:105], v[2:5]
	v_mfma_f32_16x16x32_bf16 v[2:5], v[18:21], v[106:109], v[226:229]
	v_mfma_f32_16x16x32_bf16 v[22:25], v[22:25], v[118:121], v[2:5]
	v_mfma_f32_16x16x32_bf16 v[2:5], v[26:29], v[94:97], v[230:233]
	v_mfma_f32_16x16x32_bf16 v[42:45], v[30:33], v[102:105], v[2:5]
	v_mfma_f32_16x16x32_bf16 v[2:5], v[26:29], v[106:109], v[234:237]
	v_mfma_f32_16x16x32_bf16 v[14:17], v[30:33], v[118:121], v[2:5]
	v_mfma_f32_16x16x32_bf16 v[2:5], v[34:37], v[94:97], v[238:241]
	v_mfma_f32_16x16x32_bf16 v[38:41], v[206:209], v[102:105], v[2:5]
	v_mfma_f32_16x16x32_bf16 v[2:5], v[34:37], v[106:109], v[182:185]
	v_mfma_f32_16x16x32_bf16 v[6:9], v[206:209], v[118:121], v[2:5]
	v_mfma_f32_16x16x32_bf16 v[2:5], v[210:213], v[94:97], v[186:189]
	v_mfma_f32_16x16x32_bf16 v[30:33], v[242:245], v[102:105], v[2:5]
	v_mfma_f32_16x16x32_bf16 v[2:5], v[210:213], v[106:109], v[190:193]
	v_mfma_f32_16x16x32_bf16 v[2:5], v[242:245], v[118:121], v[2:5]
	s_setprio 0
	s_barrier
	s_and_saveexec_b64 s[8:9], s[6:7]
	s_cbranch_execz .LBB0_601
	s_barrier

; #define LDA(dst, b, h)                                                                                     \
;   _Pragma("unroll") for (int m = 0; m < 4; ++m) _Pragma("unroll") for (int k = 0; k < 2; ++k) dst[m][k] = \
;       *reinterpret_cast<const bf16x8*>(shmc + aL + (((b) * 2 + (h)) * 16384 + (m * 2 + k) * 1024))
; #define LDB(dst, b, h)                                                                                     \
;   _Pragma("unroll") for (int n = 0; n < 2; ++n) _Pragma("unroll") for (int k = 0; k < 2; ++k) dst[n][k] = \
;       *reinterpret_cast<const bf16x8*>(shmc + bL + (((b) * 2 + (h)) * 16384 + (n * 2 + k) * 1024))
; #define OPAQ asm volatile("" : "+v"(aL), "+v"(bL))
; #define WAIT_V(n) asm volatile("s_waitcnt vmcnt(" #n ")" ::: "memory")
; #define WAIT_L(n) asm volatile("s_waitcnt lgkmcnt(" #n ")" ::: "memory")
; #define BAR __builtin_amdgcn_s_barrier()
; #define SCHED __builtin_amdgcn_sched_barrier(0)
; template <int EPI>
; __device__ __forceinline__ void phase_gemm(const Params& p, const GemmDesc& d, char* shmc) {
;     ...
;       OPAQ;
;       LDB(B0, 0, 0); SCHED; LDA(At, 0, 0); STAGE_A(SA(1, 1), 1, t + 1);
;       WAIT_L(8); BAR; WAIT_L(0); MMA(0, 0, At, B0); BAR; SCHED;
;       LDB(B1, 0, 1); STAGE_B(SB(0, 0), 0, t + 2);
;       BAR; WAIT_L(0); MMA(0, 1, At, B1); BAR;
;       LDA(At, 0, 1); STAGE_A(SA(0, 0), 0, t + 2);
;       BAR; WAIT_L(0); MMA(1, 0, At, B0); BAR; SCHED;
;       STAGE_B(SB(0, 1), 1, t + 2);
;       WAIT_V(6); BAR; MMA(1, 1, At, B1); BAR;
.LBB0_1010:
	s_nop 0
	v_add_u32_e32 v130, 0, v153
	v_add_u32_e32 v141, 0, v152
	s_setprio 0
	ds_read_b128 v[156:159], v130
	ds_read_b128 v[160:163], v130 offset:1024
	ds_read_b128 v[164:167], v130 offset:2048
	ds_read_b128 v[168:171], v130 offset:3072
	ds_read_b128 v[204:207], v130 offset:16384
	ds_read_b128 v[208:211], v130 offset:17408
	ds_read_b128 v[212:215], v130 offset:18432
	ds_read_b128 v[216:219], v130 offset:19456
	ds_read_b128 v[172:175], v141
	ds_read_b128 v[176:179], v141 offset:1024
	ds_read_b128 v[180:183], v141 offset:2048
	ds_read_b128 v[184:187], v141 offset:3072
	ds_read_b128 v[188:191], v141 offset:4096
	ds_read_b128 v[192:195], v141 offset:5120
	ds_read_b128 v[196:199], v141 offset:6144
	ds_read_b128 v[200:203], v141 offset:7168
	s_mov_b32 m0, s80
	s_nop 0
	global_load_lds_dwordx4 v220, s[98:99]
	s_mov_b32 m0, s81
	s_nop 0
	global_load_lds_dwordx4 v221, s[98:99]
	s_waitcnt vmcnt(8) lgkmcnt(0)
	s_setprio 1
	s_barrier
	v_mfma_f32_16x16x32_bf16 v[126:129], v[156:159], v[172:175], v[126:129]
	v_mfma_f32_16x16x32_bf16 v[122:125], v[164:167], v[172:175], v[122:125]
	v_mfma_f32_16x16x32_bf16 v[118:121], v[156:159], v[180:183], v[118:121]
	v_mfma_f32_16x16x32_bf16 v[114:117], v[164:167], v[180:183], v[114:117]
	v_mfma_f32_16x16x32_bf16 v[110:113], v[156:159], v[188:191], v[110:113]
	v_mfma_f32_16x16x32_bf16 v[106:109], v[164:167], v[188:191], v[106:109]
	v_mfma_f32_16x16x32_bf16 v[102:105], v[156:159], v[196:199], v[102:105]
	v_mfma_f32_16x16x32_bf16 v[98:101], v[164:167], v[196:199], v[98:101]
	v_mfma_f32_16x16x32_bf16 v[126:129], v[160:163], v[176:179], v[126:129]
	v_mfma_f32_16x16x32_bf16 v[122:125], v[168:171], v[176:179], v[122:125]
	v_mfma_f32_16x16x32_bf16 v[118:121], v[160:163], v[184:187], v[118:121]
	v_mfma_f32_16x16x32_bf16 v[114:117], v[168:171], v[184:187], v[114:117]
	v_mfma_f32_16x16x32_bf16 v[110:113], v[160:163], v[192:195], v[110:113]
	v_mfma_f32_16x16x32_bf16 v[106:109], v[168:171], v[192:195], v[106:109]
	v_mfma_f32_16x16x32_bf16 v[102:105], v[160:163], v[200:203], v[102:105]
	v_mfma_f32_16x16x32_bf16 v[98:101], v[168:171], v[200:203], v[98:101]
	v_mfma_f32_16x16x32_bf16 v[86:89], v[204:207], v[172:175], v[86:89]
	v_mfma_f32_16x16x32_bf16 v[70:73], v[212:215], v[172:175], v[70:73]
	v_mfma_f32_16x16x32_bf16 v[54:57], v[204:207], v[180:183], v[54:57]
	v_mfma_f32_16x16x32_bf16 v[50:53], v[212:215], v[180:183], v[50:53]
	v_mfma_f32_16x16x32_bf16 v[46:49], v[204:207], v[188:191], v[46:49]
	v_mfma_f32_16x16x32_bf16 v[42:45], v[212:215], v[188:191], v[42:45]
	v_mfma_f32_16x16x32_bf16 v[38:41], v[204:207], v[196:199], v[38:41]
	v_mfma_f32_16x16x32_bf16 v[34:37], v[212:215], v[196:199], v[34:37]
	v_mfma_f32_16x16x32_bf16 v[86:89], v[208:211], v[176:179], v[86:89]
	v_mfma_f32_16x16x32_bf16 v[70:73], v[216:219], v[176:179], v[70:73]
	v_mfma_f32_16x16x32_bf16 v[54:57], v[208:211], v[184:187], v[54:57]
	v_mfma_f32_16x16x32_bf16 v[50:53], v[216:219], v[184:187], v[50:53]
	v_mfma_f32_16x16x32_bf16 v[46:49], v[208:211], v[192:195], v[46:49]
	v_mfma_f32_16x16x32_bf16 v[42:45], v[216:219], v[192:195], v[42:45]
	v_mfma_f32_16x16x32_bf16 v[38:41], v[208:211], v[200:203], v[38:41]
	v_mfma_f32_16x16x32_bf16 v[34:37], v[216:219], v[200:203], v[34:37]
	s_barrier
	s_setprio 0
	ds_read_b128 v[172:175], v141 offset:16384
	ds_read_b128 v[176:179], v141 offset:17408
	ds_read_b128 v[180:183], v141 offset:18432
	ds_read_b128 v[184:187], v141 offset:19456
	ds_read_b128 v[188:191], v141 offset:20480
	ds_read_b128 v[192:195], v141 offset:21504
	ds_read_b128 v[196:199], v141 offset:22528
	ds_read_b128 v[200:203], v141 offset:23552
	s_mov_b32 m0, s35
	s_nop 0
	global_load_lds_dwordx4 v222, s[100:101]
	s_mov_b32 m0, s64
	s_nop 0
	global_load_lds_dwordx4 v223, s[100:101]
	s_mov_b32 m0, s34
	s_nop 0
	global_load_lds_dwordx4 v224, s[98:99]
	s_mov_b32 m0, s65
	s_nop 0
	global_load_lds_dwordx4 v225, s[98:99]
	s_mov_b32 m0, s66
	s_nop 0
	global_load_lds_dwordx4 v226, s[100:101]
	s_mov_b32 m0, s67
	s_nop 0
	global_load_lds_dwordx4 v227, s[100:101]
	s_waitcnt vmcnt(8) lgkmcnt(0)
	s_setprio 1
	s_barrier
	v_mfma_f32_16x16x32_bf16 v[30:33], v[156:159], v[172:175], v[30:33]
	v_mfma_f32_16x16x32_bf16 v[26:29], v[164:167], v[172:175], v[26:29]
	v_mfma_f32_16x16x32_bf16 v[22:25], v[156:159], v[180:183], v[22:25]
	v_mfma_f32_16x16x32_bf16 v[18:21], v[164:167], v[180:183], v[18:21]
	v_mfma_f32_16x16x32_bf16 v[14:17], v[156:159], v[188:191], v[14:17]
	v_mfma_f32_16x16x32_bf16 v[10:13], v[164:167], v[188:191], v[10:13]
	v_mfma_f32_16x16x32_bf16 v[6:9], v[156:159], v[196:199], v[6:9]
	v_mfma_f32_16x16x32_bf16 v[2:5], v[164:167], v[196:199], v[2:5]
	v_mfma_f32_16x16x32_bf16 v[30:33], v[160:163], v[176:179], v[30:33]
	v_mfma_f32_16x16x32_bf16 v[26:29], v[168:171], v[176:179], v[26:29]
	v_mfma_f32_16x16x32_bf16 v[22:25], v[160:163], v[184:187], v[22:25]
	v_mfma_f32_16x16x32_bf16 v[18:21], v[168:171], v[184:187], v[18:21]
	v_mfma_f32_16x16x32_bf16 v[14:17], v[160:163], v[192:195], v[14:17]
	v_mfma_f32_16x16x32_bf16 v[10:13], v[168:171], v[192:195], v[10:13]
	v_mfma_f32_16x16x32_bf16 v[6:9], v[160:163], v[200:203], v[6:9]
	v_mfma_f32_16x16x32_bf16 v[2:5], v[168:171], v[200:203], v[2:5]
	v_mfma_f32_16x16x32_bf16 v[58:61], v[204:207], v[172:175], v[58:61]
	v_mfma_f32_16x16x32_bf16 v[62:65], v[212:215], v[172:175], v[62:65]
	v_mfma_f32_16x16x32_bf16 v[66:69], v[204:207], v[180:183], v[66:69]
	v_mfma_f32_16x16x32_bf16 v[74:77], v[212:215], v[180:183], v[74:77]
	v_mfma_f32_16x16x32_bf16 v[78:81], v[204:207], v[188:191], v[78:81]
	v_mfma_f32_16x16x32_bf16 v[82:85], v[212:215], v[188:191], v[82:85]
	v_mfma_f32_16x16x32_bf16 v[90:93], v[204:207], v[196:199], v[90:93]
	v_mfma_f32_16x16x32_bf16 v[94:97], v[212:215], v[196:199], v[94:97]
	v_mfma_f32_16x16x32_bf16 v[58:61], v[208:211], v[176:179], v[58:61]
	v_mfma_f32_16x16x32_bf16 v[62:65], v[216:219], v[176:179], v[62:65]
	v_mfma_f32_16x16x32_bf16 v[66:69], v[208:211], v[184:187], v[66:69]
	v_mfma_f32_16x16x32_bf16 v[74:77], v[216:219], v[184:187], v[74:77]
	v_mfma_f32_16x16x32_bf16 v[78:81], v[208:211], v[192:195], v[78:81]
	v_mfma_f32_16x16x32_bf16 v[82:85], v[216:219], v[192:195], v[82:85]
	v_mfma_f32_16x16x32_bf16 v[90:93], v[208:211], v[200:203], v[90:93]
	v_mfma_f32_16x16x32_bf16 v[94:97], v[216:219], v[200:203], v[94:97]
	s_barrier
; #define LDA(dst, b, h)                                                                                     \
;   _Pragma("unroll") for (int m = 0; m < 4; ++m) _Pragma("unroll") for (int k = 0; k < 2; ++k) dst[m][k] = \
;       *reinterpret_cast<const bf16x8*>(shmc + aL + (((b) * 2 + (h)) * 16384 + (m * 2 + k) * 1024))
; #define LDB(dst, b, h)                                                                                     \
;   _Pragma("unroll") for (int n = 0; n < 2; ++n) _Pragma("unroll") for (int k = 0; k < 2; ++k) dst[n][k] = \
;       *reinterpret_cast<const bf16x8*>(shmc + bL + (((b) * 2 + (h)) * 16384 + (n * 2 + k) * 1024))
; #define WAIT_V(n) asm volatile("s_waitcnt vmcnt(" #n ")" ::: "memory")
; #define WAIT_L(n) asm volatile("s_waitcnt lgkmcnt(" #n ")" ::: "memory")
; #define BAR __builtin_amdgcn_s_barrier()
; #define SCHED __builtin_amdgcn_sched_barrier(0)
; template <int EPI>
; __device__ __forceinline__ void phase_gemm(const Params& p, const GemmDesc& d, char* shmc) {
;     ...
;       LDB(B0, 1, 0); SCHED; LDA(At, 1, 0); STAGE_A(SA(0, 1), 1, t + 2);
;       WAIT_L(8); BAR; WAIT_L(0); MMA(0, 0, At, B0); BAR; SCHED;
;       LDB(B1, 1, 1); STAGE_B(SB(1, 0), 0, t + 3);
;       BAR; WAIT_L(0); MMA(0, 1, At, B1); BAR;
;       LDA(At, 1, 1); STAGE_A(SA(1, 0), 0, t + 3);
;       BAR; WAIT_L(0); MMA(1, 0, At, B0); BAR; SCHED;
;       STAGE_B(SB(1, 1), 1, t + 3);
;       WAIT_V(6); BAR; MMA(1, 1, At, B1); BAR;
;     }
	s_setprio 0
	ds_read_b128 v[156:159], v130 offset:32768
	ds_read_b128 v[160:163], v130 offset:33792
	ds_read_b128 v[164:167], v130 offset:34816
	ds_read_b128 v[168:171], v130 offset:35840
	ds_read_b128 v[204:207], v130 offset:49152
	ds_read_b128 v[208:211], v130 offset:50176
	ds_read_b128 v[212:215], v130 offset:51200
	ds_read_b128 v[216:219], v130 offset:52224
	ds_read_b128 v[172:175], v141 offset:32768
	ds_read_b128 v[176:179], v141 offset:33792
	ds_read_b128 v[180:183], v141 offset:34816
	ds_read_b128 v[184:187], v141 offset:35840
	ds_read_b128 v[188:191], v141 offset:36864
	ds_read_b128 v[192:195], v141 offset:37888
	ds_read_b128 v[196:199], v141 offset:38912
	ds_read_b128 v[200:203], v141 offset:39936
	s_mov_b32 m0, s68
	s_nop 0
	global_load_lds_dwordx4 v228, s[98:99]
	s_mov_b32 m0, s69
	s_nop 0
	global_load_lds_dwordx4 v229, s[98:99]
	s_waitcnt vmcnt(8) lgkmcnt(0)
	s_setprio 1
	s_barrier
	v_mfma_f32_16x16x32_bf16 v[126:129], v[156:159], v[172:175], v[126:129]
	v_mfma_f32_16x16x32_bf16 v[122:125], v[164:167], v[172:175], v[122:125]
	v_mfma_f32_16x16x32_bf16 v[118:121], v[156:159], v[180:183], v[118:121]
	v_mfma_f32_16x16x32_bf16 v[114:117], v[164:167], v[180:183], v[114:117]
	v_mfma_f32_16x16x32_bf16 v[110:113], v[156:159], v[188:191], v[110:113]
	v_mfma_f32_16x16x32_bf16 v[106:109], v[164:167], v[188:191], v[106:109]
	v_mfma_f32_16x16x32_bf16 v[102:105], v[156:159], v[196:199], v[102:105]
	v_mfma_f32_16x16x32_bf16 v[98:101], v[164:167], v[196:199], v[98:101]
	v_mfma_f32_16x16x32_bf16 v[126:129], v[160:163], v[176:179], v[126:129]
	v_mfma_f32_16x16x32_bf16 v[122:125], v[168:171], v[176:179], v[122:125]
	v_mfma_f32_16x16x32_bf16 v[118:121], v[160:163], v[184:187], v[118:121]
	v_mfma_f32_16x16x32_bf16 v[114:117], v[168:171], v[184:187], v[114:117]
	v_mfma_f32_16x16x32_bf16 v[110:113], v[160:163], v[192:195], v[110:113]
	v_mfma_f32_16x16x32_bf16 v[106:109], v[168:171], v[192:195], v[106:109]
	v_mfma_f32_16x16x32_bf16 v[102:105], v[160:163], v[200:203], v[102:105]
	v_mfma_f32_16x16x32_bf16 v[98:101], v[168:171], v[200:203], v[98:101]
	v_mfma_f32_16x16x32_bf16 v[86:89], v[204:207], v[172:175], v[86:89]
	v_mfma_f32_16x16x32_bf16 v[70:73], v[212:215], v[172:175], v[70:73]
	v_mfma_f32_16x16x32_bf16 v[54:57], v[204:207], v[180:183], v[54:57]
	v_mfma_f32_16x16x32_bf16 v[50:53], v[212:215], v[180:183], v[50:53]
	v_mfma_f32_16x16x32_bf16 v[46:49], v[204:207], v[188:191], v[46:49]
	v_mfma_f32_16x16x32_bf16 v[42:45], v[212:215], v[188:191], v[42:45]
	v_mfma_f32_16x16x32_bf16 v[38:41], v[204:207], v[196:199], v[38:41]
	v_mfma_f32_16x16x32_bf16 v[34:37], v[212:215], v[196:199], v[34:37]
	v_mfma_f32_16x16x32_bf16 v[86:89], v[208:211], v[176:179], v[86:89]
	v_mfma_f32_16x16x32_bf16 v[70:73], v[216:219], v[176:179], v[70:73]
	v_mfma_f32_16x16x32_bf16 v[54:57], v[208:211], v[184:187], v[54:57]
	v_mfma_f32_16x16x32_bf16 v[50:53], v[216:219], v[184:187], v[50:53]
	v_mfma_f32_16x16x32_bf16 v[46:49], v[208:211], v[192:195], v[46:49]
	v_mfma_f32_16x16x32_bf16 v[42:45], v[216:219], v[192:195], v[42:45]
	v_mfma_f32_16x16x32_bf16 v[38:41], v[208:211], v[200:203], v[38:41]
	v_mfma_f32_16x16x32_bf16 v[34:37], v[216:219], v[200:203], v[34:37]
	s_barrier
	s_setprio 0
	ds_read_b128 v[172:175], v141 offset:49152
	ds_read_b128 v[176:179], v141 offset:50176
	ds_read_b128 v[180:183], v141 offset:51200
	ds_read_b128 v[184:187], v141 offset:52224
	ds_read_b128 v[188:191], v141 offset:53248
	ds_read_b128 v[192:195], v141 offset:54272
	ds_read_b128 v[196:199], v141 offset:55296
	ds_read_b128 v[200:203], v141 offset:56320
	s_mov_b32 m0, s70
	s_nop 0
	global_load_lds_dwordx4 v232, s[100:101]
	s_mov_b32 m0, s71
	s_nop 0
	global_load_lds_dwordx4 v233, s[100:101]
	s_mov_b32 m0, s76
	s_nop 0
	global_load_lds_dwordx4 v234, s[98:99]
	s_mov_b32 m0, s77
	s_nop 0
	global_load_lds_dwordx4 v235, s[98:99]
	s_mov_b32 m0, s78
	s_nop 0
	global_load_lds_dwordx4 v236, s[100:101]
	s_mov_b32 m0, s79
	s_nop 0
	global_load_lds_dwordx4 v237, s[100:101]
	s_add_i32 s53, s53, 2
	s_add_u32 s58, s58, 0x100
	s_addc_u32 s59, s59, 0
	s_add_u32 s98, s98, 0x100
	s_addc_u32 s99, s99, 0
	s_add_u32 s100, s100, 0x100
	s_addc_u32 s101, s101, 0
	s_cmp_gt_u32 s53, 27
	s_waitcnt vmcnt(8) lgkmcnt(0)
	s_setprio 1
	s_barrier
	v_mfma_f32_16x16x32_bf16 v[30:33], v[156:159], v[172:175], v[30:33]
	v_mfma_f32_16x16x32_bf16 v[26:29], v[164:167], v[172:175], v[26:29]
	v_mfma_f32_16x16x32_bf16 v[22:25], v[156:159], v[180:183], v[22:25]
	v_mfma_f32_16x16x32_bf16 v[18:21], v[164:167], v[180:183], v[18:21]
	v_mfma_f32_16x16x32_bf16 v[14:17], v[156:159], v[188:191], v[14:17]
	v_mfma_f32_16x16x32_bf16 v[10:13], v[164:167], v[188:191], v[10:13]
	v_mfma_f32_16x16x32_bf16 v[6:9], v[156:159], v[196:199], v[6:9]
	v_mfma_f32_16x16x32_bf16 v[2:5], v[164:167], v[196:199], v[2:5]
	v_mfma_f32_16x16x32_bf16 v[30:33], v[160:163], v[176:179], v[30:33]
	v_mfma_f32_16x16x32_bf16 v[26:29], v[168:171], v[176:179], v[26:29]
	v_mfma_f32_16x16x32_bf16 v[22:25], v[160:163], v[184:187], v[22:25]
	v_mfma_f32_16x16x32_bf16 v[18:21], v[168:171], v[184:187], v[18:21]
	v_mfma_f32_16x16x32_bf16 v[14:17], v[160:163], v[192:195], v[14:17]
	v_mfma_f32_16x16x32_bf16 v[10:13], v[168:171], v[192:195], v[10:13]
	v_mfma_f32_16x16x32_bf16 v[6:9], v[160:163], v[200:203], v[6:9]
	v_mfma_f32_16x16x32_bf16 v[2:5], v[168:171], v[200:203], v[2:5]
	v_mfma_f32_16x16x32_bf16 v[58:61], v[204:207], v[172:175], v[58:61]
	v_mfma_f32_16x16x32_bf16 v[62:65], v[212:215], v[172:175], v[62:65]
	v_mfma_f32_16x16x32_bf16 v[66:69], v[204:207], v[180:183], v[66:69]
	v_mfma_f32_16x16x32_bf16 v[74:77], v[212:215], v[180:183], v[74:77]
	v_mfma_f32_16x16x32_bf16 v[78:81], v[204:207], v[188:191], v[78:81]
	v_mfma_f32_16x16x32_bf16 v[82:85], v[212:215], v[188:191], v[82:85]
	v_mfma_f32_16x16x32_bf16 v[90:93], v[204:207], v[196:199], v[90:93]
	v_mfma_f32_16x16x32_bf16 v[94:97], v[212:215], v[196:199], v[94:97]
	v_mfma_f32_16x16x32_bf16 v[58:61], v[208:211], v[176:179], v[58:61]
	v_mfma_f32_16x16x32_bf16 v[62:65], v[216:219], v[176:179], v[62:65]
	v_mfma_f32_16x16x32_bf16 v[66:69], v[208:211], v[184:187], v[66:69]
	v_mfma_f32_16x16x32_bf16 v[74:77], v[216:219], v[184:187], v[74:77]
	v_mfma_f32_16x16x32_bf16 v[78:81], v[208:211], v[192:195], v[78:81]
	v_mfma_f32_16x16x32_bf16 v[82:85], v[216:219], v[192:195], v[82:85]
	v_mfma_f32_16x16x32_bf16 v[90:93], v[208:211], v[200:203], v[90:93]
	v_mfma_f32_16x16x32_bf16 v[94:97], v[216:219], v[200:203], v[94:97]
	s_barrier
; #define LDA(dst, b, h)                                                                                     \
;   _Pragma("unroll") for (int m = 0; m < 4; ++m) _Pragma("unroll") for (int k = 0; k < 2; ++k) dst[m][k] = \
;       *reinterpret_cast<const bf16x8*>(shmc + aL + (((b) * 2 + (h)) * 16384 + (m * 2 + k) * 1024))
; #define LDB(dst, b, h)                                                                                     \
;   _Pragma("unroll") for (int n = 0; n < 2; ++n) _Pragma("unroll") for (int k = 0; k < 2; ++k) dst[n][k] = \
;       *reinterpret_cast<const bf16x8*>(shmc + bL + (((b) * 2 + (h)) * 16384 + (n * 2 + k) * 1024))
; #define OPAQ asm volatile("" : "+v"(aL), "+v"(bL))
; #define WAIT_V(n) asm volatile("s_waitcnt vmcnt(" #n ")" ::: "memory")
; #define WAIT_L(n) asm volatile("s_waitcnt lgkmcnt(" #n ")" ::: "memory")
; #define BAR __builtin_amdgcn_s_barrier()
; template <int EPI>
; __device__ __forceinline__ void phase_gemm(const Params& p, const GemmDesc& d, char* shmc) {
;     ...
;     {
;       OPAQ;
;       LDB(B0, 0, 0); LDA(At, 0, 0); STAGE_A(SA(1, 1), 1, nt - 1);
;       BAR; WAIT_L(0); MMA(0, 0, At, B0); BAR;
;       LDB(B1, 0, 1); BAR; WAIT_L(0); MMA(0, 1, At, B1); BAR;
;       LDA(At, 0, 1); WAIT_V(4); BAR; WAIT_L(0); MMA(1, 0, At, B0); MMA(1, 1, At, B1); BAR;
;     }
	s_cbranch_scc0 .LBB0_1010
	s_setprio 0
	s_add_u32 s56, s56, 0x80f80
	s_addc_u32 s57, s57, 0
	v_add_u32_e32 v130, 0, v153
	v_add_u32_e32 v141, 0, v152
	s_mov_b32 m0, s80
	ds_read_b128 v[144:147], v130
	ds_read_b128 v[148:151], v130 offset:1024
	ds_read_b128 v[156:159], v130 offset:2048
	ds_read_b128 v[160:163], v130 offset:3072
	ds_read_b128 v[164:167], v141
	ds_read_b128 v[168:171], v141 offset:1024
	ds_read_b128 v[172:175], v141 offset:2048
	ds_read_b128 v[176:179], v141 offset:3072
	ds_read_b128 v[180:183], v141 offset:4096
	ds_read_b128 v[184:187], v141 offset:5120
	ds_read_b128 v[188:191], v141 offset:6144
	ds_read_b128 v[192:195], v141 offset:7168
	global_load_lds_dwordx4 v140, s[56:57]
	s_mov_b32 m0, s81
	s_nop 0
	global_load_lds_dwordx4 v142, s[56:57]
	s_waitcnt vmcnt(8)
	s_barrier
	s_waitcnt lgkmcnt(0)
	s_setprio 1
	s_waitcnt lgkmcnt(0)
	v_mfma_f32_16x16x32_bf16 v[126:129], v[144:147], v[164:167], v[126:129]
	v_mfma_f32_16x16x32_bf16 v[122:125], v[156:159], v[164:167], v[122:125]
	v_mfma_f32_16x16x32_bf16 v[114:117], v[156:159], v[172:175], v[114:117]
	v_mfma_f32_16x16x32_bf16 v[110:113], v[144:147], v[180:183], v[110:113]
	v_mfma_f32_16x16x32_bf16 v[102:105], v[144:147], v[188:191], v[102:105]
	v_mfma_f32_16x16x32_bf16 v[126:129], v[148:151], v[168:171], v[126:129]
	v_mfma_f32_16x16x32_bf16 v[122:125], v[160:163], v[168:171], v[122:125]
	v_mfma_f32_16x16x32_bf16 v[118:121], v[144:147], v[172:175], v[118:121]
	v_mfma_f32_16x16x32_bf16 v[114:117], v[160:163], v[176:179], v[114:117]
	v_mfma_f32_16x16x32_bf16 v[110:113], v[148:151], v[184:187], v[110:113]
	v_mfma_f32_16x16x32_bf16 v[106:109], v[156:159], v[180:183], v[106:109]
	v_mfma_f32_16x16x32_bf16 v[102:105], v[148:151], v[192:195], v[102:105]
	v_mfma_f32_16x16x32_bf16 v[98:101], v[156:159], v[188:191], v[98:101]
	v_mfma_f32_16x16x32_bf16 v[196:199], v[148:151], v[176:179], v[118:121]
	v_mfma_f32_16x16x32_bf16 v[200:203], v[160:163], v[184:187], v[106:109]
	v_mfma_f32_16x16x32_bf16 v[204:207], v[160:163], v[192:195], v[98:101]
	s_setprio 0
	s_barrier
	s_nop 2
	ds_read_b128 v[98:101], v130 offset:16384
	ds_read_b128 v[106:109], v130 offset:17408
	ds_read_b128 v[118:121], v130 offset:18432
	ds_read_b128 v[208:211], v130 offset:19456
	s_barrier
	s_waitcnt lgkmcnt(0)
	s_setprio 1
	s_waitcnt lgkmcnt(0)
	v_mfma_f32_16x16x32_bf16 v[86:89], v[98:101], v[164:167], v[86:89]
	v_mfma_f32_16x16x32_bf16 v[70:73], v[118:121], v[164:167], v[70:73]
	v_mfma_f32_16x16x32_bf16 v[54:57], v[98:101], v[172:175], v[54:57]
	v_mfma_f32_16x16x32_bf16 v[50:53], v[118:121], v[172:175], v[50:53]
	v_mfma_f32_16x16x32_bf16 v[46:49], v[98:101], v[180:183], v[46:49]
	v_mfma_f32_16x16x32_bf16 v[42:45], v[118:121], v[180:183], v[42:45]
	v_mfma_f32_16x16x32_bf16 v[38:41], v[98:101], v[188:191], v[38:41]
	v_mfma_f32_16x16x32_bf16 v[34:37], v[118:121], v[188:191], v[34:37]
	v_mfma_f32_16x16x32_bf16 v[86:89], v[106:109], v[168:171], v[86:89]
	v_mfma_f32_16x16x32_bf16 v[70:73], v[208:211], v[168:171], v[70:73]
	v_mfma_f32_16x16x32_bf16 v[54:57], v[106:109], v[176:179], v[54:57]
	v_mfma_f32_16x16x32_bf16 v[50:53], v[208:211], v[176:179], v[50:53]
	v_mfma_f32_16x16x32_bf16 v[46:49], v[106:109], v[184:187], v[46:49]
	v_mfma_f32_16x16x32_bf16 v[42:45], v[208:211], v[184:187], v[42:45]
	v_mfma_f32_16x16x32_bf16 v[38:41], v[106:109], v[192:195], v[38:41]
	v_mfma_f32_16x16x32_bf16 v[34:37], v[208:211], v[192:195], v[34:37]
	s_setprio 0
	s_barrier
	ds_read_b128 v[164:167], v141 offset:16384
	ds_read_b128 v[168:171], v141 offset:17408
	ds_read_b128 v[172:175], v141 offset:18432
	ds_read_b128 v[176:179], v141 offset:19456
	ds_read_b128 v[180:183], v141 offset:20480
	ds_read_b128 v[184:187], v141 offset:21504
	ds_read_b128 v[188:191], v141 offset:22528
	ds_read_b128 v[192:195], v141 offset:23552
	s_waitcnt vmcnt(4)
	s_barrier
	s_waitcnt lgkmcnt(0)
	s_setprio 1
	s_waitcnt lgkmcnt(0)
	v_mfma_f32_16x16x32_bf16 v[30:33], v[144:147], v[164:167], v[30:33]
	v_mfma_f32_16x16x32_bf16 v[26:29], v[156:159], v[164:167], v[26:29]
	v_mfma_f32_16x16x32_bf16 v[22:25], v[144:147], v[172:175], v[22:25]
	v_mfma_f32_16x16x32_bf16 v[18:21], v[156:159], v[172:175], v[18:21]
	v_mfma_f32_16x16x32_bf16 v[14:17], v[144:147], v[180:183], v[14:17]
	v_mfma_f32_16x16x32_bf16 v[10:13], v[156:159], v[180:183], v[10:13]
	v_mfma_f32_16x16x32_bf16 v[6:9], v[144:147], v[188:191], v[6:9]
	v_mfma_f32_16x16x32_bf16 v[2:5], v[156:159], v[188:191], v[2:5]
	v_mfma_f32_16x16x32_bf16 v[30:33], v[148:151], v[168:171], v[30:33]
	v_mfma_f32_16x16x32_bf16 v[26:29], v[160:163], v[168:171], v[26:29]
	v_mfma_f32_16x16x32_bf16 v[22:25], v[148:151], v[176:179], v[22:25]
	v_mfma_f32_16x16x32_bf16 v[18:21], v[160:163], v[176:179], v[18:21]
	v_mfma_f32_16x16x32_bf16 v[14:17], v[148:151], v[184:187], v[14:17]
	v_mfma_f32_16x16x32_bf16 v[10:13], v[160:163], v[184:187], v[10:13]
	v_mfma_f32_16x16x32_bf16 v[6:9], v[148:151], v[192:195], v[6:9]
	v_mfma_f32_16x16x32_bf16 v[2:5], v[160:163], v[192:195], v[2:5]
	s_setprio 0
	s_setprio 1
	v_mfma_f32_16x16x32_bf16 v[62:65], v[118:121], v[164:167], v[62:65]
	v_mfma_f32_16x16x32_bf16 v[144:147], v[208:211], v[168:171], v[62:65]
	v_mfma_f32_16x16x32_bf16 v[62:65], v[98:101], v[172:175], v[66:69]
	v_mfma_f32_16x16x32_bf16 v[148:151], v[106:109], v[176:179], v[62:65]
	v_mfma_f32_16x16x32_bf16 v[62:65], v[118:121], v[172:175], v[74:77]
	v_mfma_f32_16x16x32_bf16 v[156:159], v[208:211], v[176:179], v[62:65]
	v_mfma_f32_16x16x32_bf16 v[62:65], v[98:101], v[180:183], v[78:81]
	v_mfma_f32_16x16x32_bf16 v[160:163], v[106:109], v[184:187], v[62:65]
	v_mfma_f32_16x16x32_bf16 v[62:65], v[118:121], v[180:183], v[82:85]
	v_mfma_f32_16x16x32_bf16 v[58:61], v[98:101], v[164:167], v[58:61]
	v_mfma_f32_16x16x32_bf16 v[164:167], v[208:211], v[184:187], v[62:65]
	v_mfma_f32_16x16x32_bf16 v[62:65], v[98:101], v[188:191], v[90:93]
	v_mfma_f32_16x16x32_bf16 v[58:61], v[106:109], v[168:171], v[58:61]
	v_mfma_f32_16x16x32_bf16 v[168:171], v[106:109], v[192:195], v[62:65]
	v_mfma_f32_16x16x32_bf16 v[62:65], v[118:121], v[188:191], v[94:97]
	v_mfma_f32_16x16x32_bf16 v[172:175], v[208:211], v[192:195], v[62:65]
	s_setprio 0
	s_barrier
; #define LDA(dst, b, h)                                                                                     \
;   _Pragma("unroll") for (int m = 0; m < 4; ++m) _Pragma("unroll") for (int k = 0; k < 2; ++k) dst[m][k] = \
;       *reinterpret_cast<const bf16x8*>(shmc + aL + (((b) * 2 + (h)) * 16384 + (m * 2 + k) * 1024))
; #define LDB(dst, b, h)                                                                                     \
;   _Pragma("unroll") for (int n = 0; n < 2; ++n) _Pragma("unroll") for (int k = 0; k < 2; ++k) dst[n][k] = \
;       *reinterpret_cast<const bf16x8*>(shmc + bL + (((b) * 2 + (h)) * 16384 + (n * 2 + k) * 1024))
; #define WAIT_V(n) asm volatile("s_waitcnt vmcnt(" #n ")" ::: "memory")
; #define WAIT_L(n) asm volatile("s_waitcnt lgkmcnt(" #n ")" ::: "memory")
; #define BAR __builtin_amdgcn_s_barrier()
; template <int EPI>
; __device__ __forceinline__ void phase_gemm(const Params& p, const GemmDesc& d, char* shmc) {
;     ...
;     {
;       LDB(B0, 1, 0); LDA(At, 1, 0); WAIT_V(2); BAR; WAIT_L(0); MMA(0, 0, At, B0); BAR;
;       LDB(B1, 1, 1); WAIT_V(0); BAR; WAIT_L(0); MMA(0, 1, At, B1); BAR;
;       LDA(At, 1, 1); BAR; WAIT_L(0); MMA(1, 0, At, B0); MMA(1, 1, At, B1); BAR;
;     }
;     if (wr == 0) BAR;
	ds_read_b128 v[176:179], v130 offset:32768
	ds_read_b128 v[180:183], v130 offset:33792
	ds_read_b128 v[184:187], v130 offset:34816
	ds_read_b128 v[188:191], v130 offset:35840
	s_nop 0
	ds_read_b128 v[62:65], v141 offset:32768
	ds_read_b128 v[78:81], v141 offset:33792
	ds_read_b128 v[94:97], v141 offset:34816
	ds_read_b128 v[192:195], v141 offset:35840
	ds_read_b128 v[208:211], v141 offset:36864
	ds_read_b128 v[212:215], v141 offset:37888
	ds_read_b128 v[216:219], v141 offset:38912
	ds_read_b128 v[220:223], v141 offset:39936
	s_waitcnt vmcnt(2)
	s_barrier
	s_waitcnt lgkmcnt(0)
	s_setprio 1
	s_waitcnt lgkmcnt(0)
	v_mfma_f32_16x16x32_bf16 v[66:69], v[176:179], v[62:65], v[126:129]
	v_mfma_f32_16x16x32_bf16 v[126:129], v[180:183], v[78:81], v[66:69]
	v_mfma_f32_16x16x32_bf16 v[66:69], v[184:187], v[62:65], v[122:125]
	v_mfma_f32_16x16x32_bf16 v[118:121], v[188:191], v[78:81], v[66:69]
	v_mfma_f32_16x16x32_bf16 v[66:69], v[176:179], v[94:97], v[196:199]
	v_mfma_f32_16x16x32_bf16 v[106:109], v[180:183], v[192:195], v[66:69]
	v_mfma_f32_16x16x32_bf16 v[66:69], v[184:187], v[94:97], v[114:117]
	v_mfma_f32_16x16x32_bf16 v[98:101], v[188:191], v[192:195], v[66:69]
	v_mfma_f32_16x16x32_bf16 v[66:69], v[176:179], v[208:211], v[110:113]
	v_mfma_f32_16x16x32_bf16 v[90:93], v[180:183], v[212:215], v[66:69]
	v_mfma_f32_16x16x32_bf16 v[66:69], v[184:187], v[208:211], v[200:203]
	v_mfma_f32_16x16x32_bf16 v[82:85], v[188:191], v[212:215], v[66:69]
	v_mfma_f32_16x16x32_bf16 v[66:69], v[176:179], v[216:219], v[102:105]
	v_mfma_f32_16x16x32_bf16 v[74:77], v[180:183], v[220:223], v[66:69]
	v_mfma_f32_16x16x32_bf16 v[66:69], v[184:187], v[216:219], v[204:207]
	v_mfma_f32_16x16x32_bf16 v[66:69], v[188:191], v[220:223], v[66:69]
	s_setprio 0
	s_barrier
	ds_read_b128 v[196:199], v130 offset:49152
	ds_read_b128 v[200:203], v130 offset:50176
	ds_read_b128 v[204:207], v130 offset:51200
	ds_read_b128 v[224:227], v130 offset:52224
	s_waitcnt vmcnt(0)
	s_barrier
	s_waitcnt lgkmcnt(0)
	s_setprio 1
	s_waitcnt lgkmcnt(0)
	v_mfma_f32_16x16x32_bf16 v[86:89], v[196:199], v[62:65], v[86:89]
	v_mfma_f32_16x16x32_bf16 v[62:65], v[204:207], v[62:65], v[70:73]
	v_mfma_f32_16x16x32_bf16 v[54:57], v[196:199], v[94:97], v[54:57]
	v_mfma_f32_16x16x32_bf16 v[50:53], v[204:207], v[94:97], v[50:53]
	v_mfma_f32_16x16x32_bf16 v[46:49], v[196:199], v[208:211], v[46:49]
	v_mfma_f32_16x16x32_bf16 v[42:45], v[204:207], v[208:211], v[42:45]
	v_mfma_f32_16x16x32_bf16 v[38:41], v[196:199], v[216:219], v[38:41]
	v_mfma_f32_16x16x32_bf16 v[34:37], v[204:207], v[216:219], v[34:37]
	v_mfma_f32_16x16x32_bf16 v[122:125], v[200:203], v[78:81], v[86:89]
	v_mfma_f32_16x16x32_bf16 v[114:117], v[224:227], v[78:81], v[62:65]
	v_mfma_f32_16x16x32_bf16 v[110:113], v[200:203], v[192:195], v[54:57]
	v_mfma_f32_16x16x32_bf16 v[102:105], v[224:227], v[192:195], v[50:53]
	v_mfma_f32_16x16x32_bf16 v[94:97], v[200:203], v[212:215], v[46:49]
	v_mfma_f32_16x16x32_bf16 v[86:89], v[224:227], v[212:215], v[42:45]
	v_mfma_f32_16x16x32_bf16 v[78:81], v[200:203], v[220:223], v[38:41]
	v_mfma_f32_16x16x32_bf16 v[70:73], v[224:227], v[220:223], v[34:37]
	s_setprio 0
	s_barrier
	s_nop 0
	ds_read_b128 v[34:37], v141 offset:49152
	ds_read_b128 v[42:45], v141 offset:50176
	ds_read_b128 v[192:195], v141 offset:51200
	ds_read_b128 v[208:211], v141 offset:52224
	ds_read_b128 v[212:215], v141 offset:53248
	ds_read_b128 v[216:219], v141 offset:54272
	ds_read_b128 v[220:223], v141 offset:55296
	ds_read_b128 v[228:231], v141 offset:56320
	s_barrier
	s_waitcnt lgkmcnt(0)
	s_setprio 1
	s_waitcnt lgkmcnt(0)
	v_mfma_f32_16x16x32_bf16 v[30:33], v[176:179], v[34:37], v[30:33]
	v_mfma_f32_16x16x32_bf16 v[26:29], v[184:187], v[34:37], v[26:29]
	v_mfma_f32_16x16x32_bf16 v[22:25], v[176:179], v[192:195], v[22:25]
	v_mfma_f32_16x16x32_bf16 v[18:21], v[184:187], v[192:195], v[18:21]
	v_mfma_f32_16x16x32_bf16 v[14:17], v[176:179], v[212:215], v[14:17]
	v_mfma_f32_16x16x32_bf16 v[10:13], v[184:187], v[212:215], v[10:13]
	v_mfma_f32_16x16x32_bf16 v[6:9], v[176:179], v[220:223], v[6:9]
	v_mfma_f32_16x16x32_bf16 v[2:5], v[184:187], v[220:223], v[2:5]
	v_mfma_f32_16x16x32_bf16 v[62:65], v[180:183], v[42:45], v[30:33]
	v_mfma_f32_16x16x32_bf16 v[54:57], v[188:191], v[42:45], v[26:29]
	v_mfma_f32_16x16x32_bf16 v[46:49], v[180:183], v[208:211], v[22:25]
	v_mfma_f32_16x16x32_bf16 v[38:41], v[188:191], v[208:211], v[18:21]
	v_mfma_f32_16x16x32_bf16 v[30:33], v[180:183], v[216:219], v[14:17]
	v_mfma_f32_16x16x32_bf16 v[22:25], v[188:191], v[216:219], v[10:13]
	v_mfma_f32_16x16x32_bf16 v[14:17], v[180:183], v[228:231], v[6:9]
	v_mfma_f32_16x16x32_bf16 v[6:9], v[188:191], v[228:231], v[2:5]
	s_setprio 0
	s_setprio 1
	v_mfma_f32_16x16x32_bf16 v[2:5], v[196:199], v[34:37], v[58:61]
	v_mfma_f32_16x16x32_bf16 v[58:61], v[200:203], v[42:45], v[2:5]
	v_mfma_f32_16x16x32_bf16 v[2:5], v[204:207], v[34:37], v[144:147]
	v_mfma_f32_16x16x32_bf16 v[50:53], v[224:227], v[42:45], v[2:5]
	v_mfma_f32_16x16x32_bf16 v[2:5], v[196:199], v[192:195], v[148:151]
	v_mfma_f32_16x16x32_bf16 v[42:45], v[200:203], v[208:211], v[2:5]
	v_mfma_f32_16x16x32_bf16 v[2:5], v[204:207], v[192:195], v[156:159]
	v_mfma_f32_16x16x32_bf16 v[34:37], v[224:227], v[208:211], v[2:5]
	v_mfma_f32_16x16x32_bf16 v[2:5], v[196:199], v[212:215], v[160:163]
	v_mfma_f32_16x16x32_bf16 v[26:29], v[200:203], v[216:219], v[2:5]
	v_mfma_f32_16x16x32_bf16 v[2:5], v[204:207], v[212:215], v[164:167]
	v_mfma_f32_16x16x32_bf16 v[18:21], v[224:227], v[216:219], v[2:5]
	v_mfma_f32_16x16x32_bf16 v[2:5], v[196:199], v[220:223], v[168:171]
	v_mfma_f32_16x16x32_bf16 v[10:13], v[200:203], v[228:231], v[2:5]
	v_mfma_f32_16x16x32_bf16 v[2:5], v[204:207], v[220:223], v[172:175]
	v_mfma_f32_16x16x32_bf16 v[2:5], v[224:227], v[228:231], v[2:5]
	s_setprio 0
	s_barrier
	s_and_saveexec_b64 s[56:57], s[4:5]
	s_cbranch_execz .LBB0_1013
	s_barrier

; #define LDA(dst, b, h)                                                                                     \
;   _Pragma("unroll") for (int m = 0; m < 4; ++m) _Pragma("unroll") for (int k = 0; k < 2; ++k) dst[m][k] = \
;       *reinterpret_cast<const bf16x8*>(shmc + aL + (((b) * 2 + (h)) * 16384 + (m * 2 + k) * 1024))
; #define LDB(dst, b, h)                                                                                     \
;   _Pragma("unroll") for (int n = 0; n < 2; ++n) _Pragma("unroll") for (int k = 0; k < 2; ++k) dst[n][k] = \
;       *reinterpret_cast<const bf16x8*>(shmc + bL + (((b) * 2 + (h)) * 16384 + (n * 2 + k) * 1024))
; #define OPAQ asm volatile("" : "+v"(aL), "+v"(bL))
; #define WAIT_V(n) asm volatile("s_waitcnt vmcnt(" #n ")" ::: "memory")
; #define WAIT_L(n) asm volatile("s_waitcnt lgkmcnt(" #n ")" ::: "memory")
; #define BAR __builtin_amdgcn_s_barrier()
; #define SCHED __builtin_amdgcn_sched_barrier(0)
; template <int EPI>
; __device__ __forceinline__ void phase_gemm(const Params& p, const GemmDesc& d, char* shmc) {
;     ...
;       OPAQ;
;       LDB(B0, 0, 0); SCHED; LDA(At, 0, 0); STAGE_A(SA(1, 1), 1, t + 1);
;       WAIT_L(8); BAR; WAIT_L(0); MMA(0, 0, At, B0); BAR; SCHED;
;       LDB(B1, 0, 1); STAGE_B(SB(0, 0), 0, t + 2);
;       BAR; WAIT_L(0); MMA(0, 1, At, B1); BAR;
;       LDA(At, 0, 1); STAGE_A(SA(0, 0), 0, t + 2);
;       BAR; WAIT_L(0); MMA(1, 0, At, B0); BAR; SCHED;
;       STAGE_B(SB(0, 1), 1, t + 2);
;       WAIT_V(6); BAR; MMA(1, 1, At, B1); BAR;
.LBB0_1153:
	s_nop 0
	v_add_u32_e32 v162, 0, v205
	v_add_u32_e32 v175, 0, v204
	s_setprio 0
	ds_read_b128 v[138:141], v162
	ds_read_b128 v[142:145], v162 offset:1024
	ds_read_b128 v[146:149], v162 offset:2048
	ds_read_b128 v[150:153], v162 offset:3072
	ds_read_b128 v[208:211], v162 offset:16384
	ds_read_b128 v[212:215], v162 offset:17408
	ds_read_b128 v[216:219], v162 offset:18432
	ds_read_b128 v[220:223], v162 offset:19456
	ds_read_b128 v[154:157], v175
	ds_read_b128 v[158:161], v175 offset:1024
	ds_read_b128 v[178:181], v175 offset:2048
	ds_read_b128 v[182:185], v175 offset:3072
	ds_read_b128 v[186:189], v175 offset:4096
	ds_read_b128 v[190:193], v175 offset:5120
	ds_read_b128 v[194:197], v175 offset:6144
	ds_read_b128 v[198:201], v175 offset:7168
	s_add_i32 s59, s64, 0xc000
	s_mov_b32 m0, s59
	s_nop 0
	global_load_lds_dwordx4 v202, s[98:99]
	s_add_i32 s68, s64, 0xe000
	s_mov_b32 m0, s68
	s_nop 0
	global_load_lds_dwordx4 v203, s[98:99]
	s_waitcnt vmcnt(8) lgkmcnt(0)
	s_setprio 1
	s_barrier
	v_mfma_f32_16x16x32_bf16 v[2:5], v[154:157], v[138:141], v[2:5]
	v_mfma_f32_16x16x32_bf16 v[6:9], v[154:157], v[146:149], v[6:9]
	v_mfma_f32_16x16x32_bf16 v[10:13], v[178:181], v[138:141], v[10:13]
	v_mfma_f32_16x16x32_bf16 v[18:21], v[178:181], v[146:149], v[18:21]
	v_mfma_f32_16x16x32_bf16 v[30:33], v[186:189], v[138:141], v[30:33]
	v_mfma_f32_16x16x32_bf16 v[42:45], v[186:189], v[146:149], v[42:45]
	v_mfma_f32_16x16x32_bf16 v[54:57], v[194:197], v[138:141], v[54:57]
	v_mfma_f32_16x16x32_bf16 v[66:69], v[194:197], v[146:149], v[66:69]
	v_mfma_f32_16x16x32_bf16 v[2:5], v[158:161], v[142:145], v[2:5]
	v_mfma_f32_16x16x32_bf16 v[6:9], v[158:161], v[150:153], v[6:9]
	v_mfma_f32_16x16x32_bf16 v[10:13], v[182:185], v[142:145], v[10:13]
	v_mfma_f32_16x16x32_bf16 v[18:21], v[182:185], v[150:153], v[18:21]
	v_mfma_f32_16x16x32_bf16 v[30:33], v[190:193], v[142:145], v[30:33]
	v_mfma_f32_16x16x32_bf16 v[42:45], v[190:193], v[150:153], v[42:45]
	v_mfma_f32_16x16x32_bf16 v[54:57], v[198:201], v[142:145], v[54:57]
	v_mfma_f32_16x16x32_bf16 v[66:69], v[198:201], v[150:153], v[66:69]
	v_mfma_f32_16x16x32_bf16 v[14:17], v[154:157], v[208:211], v[14:17]
	v_mfma_f32_16x16x32_bf16 v[22:25], v[154:157], v[216:219], v[22:25]
	v_mfma_f32_16x16x32_bf16 v[34:37], v[178:181], v[208:211], v[34:37]
	v_mfma_f32_16x16x32_bf16 v[46:49], v[178:181], v[216:219], v[46:49]
	v_mfma_f32_16x16x32_bf16 v[58:61], v[186:189], v[208:211], v[58:61]
	v_mfma_f32_16x16x32_bf16 v[70:73], v[186:189], v[216:219], v[70:73]
	v_mfma_f32_16x16x32_bf16 v[78:81], v[194:197], v[208:211], v[78:81]
	v_mfma_f32_16x16x32_bf16 v[86:89], v[194:197], v[216:219], v[86:89]
	v_mfma_f32_16x16x32_bf16 v[14:17], v[158:161], v[212:215], v[14:17]
	v_mfma_f32_16x16x32_bf16 v[22:25], v[158:161], v[220:223], v[22:25]
	v_mfma_f32_16x16x32_bf16 v[34:37], v[182:185], v[212:215], v[34:37]
	v_mfma_f32_16x16x32_bf16 v[46:49], v[182:185], v[220:223], v[46:49]
	v_mfma_f32_16x16x32_bf16 v[58:61], v[190:193], v[212:215], v[58:61]
	v_mfma_f32_16x16x32_bf16 v[70:73], v[190:193], v[220:223], v[70:73]
	v_mfma_f32_16x16x32_bf16 v[78:81], v[198:201], v[212:215], v[78:81]
	v_mfma_f32_16x16x32_bf16 v[86:89], v[198:201], v[220:223], v[86:89]
	s_barrier
	s_setprio 0
	ds_read_b128 v[154:157], v175 offset:16384
	ds_read_b128 v[158:161], v175 offset:17408
	ds_read_b128 v[178:181], v175 offset:18432
	ds_read_b128 v[182:185], v175 offset:19456
	ds_read_b128 v[186:189], v175 offset:20480
	ds_read_b128 v[190:193], v175 offset:21504
	ds_read_b128 v[194:197], v175 offset:22528
	ds_read_b128 v[198:201], v175 offset:23552
	s_mov_b32 m0, s65
	s_nop 0
	global_load_lds_dwordx4 v224, s[100:101]
	s_mov_b32 m0, s66
	s_nop 0
	global_load_lds_dwordx4 v225, s[100:101]
	s_mov_b32 m0, s64
	s_nop 0
	global_load_lds_dwordx4 v226, s[98:99]
	s_mov_b32 m0, s67
	s_nop 0
	global_load_lds_dwordx4 v227, s[98:99]
	s_mov_b32 m0, s71
	s_nop 0
	global_load_lds_dwordx4 v228, s[100:101]
	s_mov_b32 m0, s76
	s_nop 0
	global_load_lds_dwordx4 v229, s[100:101]
	s_waitcnt vmcnt(8) lgkmcnt(0)
	s_setprio 1
	s_barrier
	v_mfma_f32_16x16x32_bf16 v[26:29], v[154:157], v[138:141], v[26:29]
	v_mfma_f32_16x16x32_bf16 v[38:41], v[154:157], v[146:149], v[38:41]
	v_mfma_f32_16x16x32_bf16 v[50:53], v[178:181], v[138:141], v[50:53]
	v_mfma_f32_16x16x32_bf16 v[62:65], v[178:181], v[146:149], v[62:65]
	v_mfma_f32_16x16x32_bf16 v[74:77], v[186:189], v[138:141], v[74:77]
	v_mfma_f32_16x16x32_bf16 v[82:85], v[186:189], v[146:149], v[82:85]
	v_mfma_f32_16x16x32_bf16 v[90:93], v[194:197], v[138:141], v[90:93]
	v_mfma_f32_16x16x32_bf16 v[94:97], v[194:197], v[146:149], v[94:97]
	v_mfma_f32_16x16x32_bf16 v[26:29], v[158:161], v[142:145], v[26:29]
	v_mfma_f32_16x16x32_bf16 v[38:41], v[158:161], v[150:153], v[38:41]
	v_mfma_f32_16x16x32_bf16 v[50:53], v[182:185], v[142:145], v[50:53]
	v_mfma_f32_16x16x32_bf16 v[62:65], v[182:185], v[150:153], v[62:65]
	v_mfma_f32_16x16x32_bf16 v[74:77], v[190:193], v[142:145], v[74:77]
	v_mfma_f32_16x16x32_bf16 v[82:85], v[190:193], v[150:153], v[82:85]
	v_mfma_f32_16x16x32_bf16 v[90:93], v[198:201], v[142:145], v[90:93]
	v_mfma_f32_16x16x32_bf16 v[94:97], v[198:201], v[150:153], v[94:97]
	v_mfma_f32_16x16x32_bf16 v[98:101], v[154:157], v[208:211], v[98:101]
	v_mfma_f32_16x16x32_bf16 v[102:105], v[154:157], v[216:219], v[102:105]
	v_mfma_f32_16x16x32_bf16 v[106:109], v[178:181], v[208:211], v[106:109]
	v_mfma_f32_16x16x32_bf16 v[110:113], v[178:181], v[216:219], v[110:113]
	v_mfma_f32_16x16x32_bf16 v[114:117], v[186:189], v[208:211], v[114:117]
	v_mfma_f32_16x16x32_bf16 v[118:121], v[186:189], v[216:219], v[118:121]
	v_mfma_f32_16x16x32_bf16 v[122:125], v[194:197], v[208:211], v[122:125]
	v_mfma_f32_16x16x32_bf16 v[126:129], v[194:197], v[216:219], v[126:129]
	v_mfma_f32_16x16x32_bf16 v[98:101], v[158:161], v[212:215], v[98:101]
	v_mfma_f32_16x16x32_bf16 v[102:105], v[158:161], v[220:223], v[102:105]
	v_mfma_f32_16x16x32_bf16 v[106:109], v[182:185], v[212:215], v[106:109]
	v_mfma_f32_16x16x32_bf16 v[110:113], v[182:185], v[220:223], v[110:113]
	v_mfma_f32_16x16x32_bf16 v[114:117], v[190:193], v[212:215], v[114:117]
	v_mfma_f32_16x16x32_bf16 v[118:121], v[190:193], v[220:223], v[118:121]
	v_mfma_f32_16x16x32_bf16 v[122:125], v[198:201], v[212:215], v[122:125]
	v_mfma_f32_16x16x32_bf16 v[126:129], v[198:201], v[220:223], v[126:129]
	s_barrier
; #define LDA(dst, b, h)                                                                                     \
;   _Pragma("unroll") for (int m = 0; m < 4; ++m) _Pragma("unroll") for (int k = 0; k < 2; ++k) dst[m][k] = \
;       *reinterpret_cast<const bf16x8*>(shmc + aL + (((b) * 2 + (h)) * 16384 + (m * 2 + k) * 1024))
; #define LDB(dst, b, h)                                                                                     \
;   _Pragma("unroll") for (int n = 0; n < 2; ++n) _Pragma("unroll") for (int k = 0; k < 2; ++k) dst[n][k] = \
;       *reinterpret_cast<const bf16x8*>(shmc + bL + (((b) * 2 + (h)) * 16384 + (n * 2 + k) * 1024))
; #define WAIT_V(n) asm volatile("s_waitcnt vmcnt(" #n ")" ::: "memory")
; #define WAIT_L(n) asm volatile("s_waitcnt lgkmcnt(" #n ")" ::: "memory")
; #define BAR __builtin_amdgcn_s_barrier()
; #define SCHED __builtin_amdgcn_sched_barrier(0)
; template <int EPI>
; __device__ __forceinline__ void phase_gemm(const Params& p, const GemmDesc& d, char* shmc) {
;     ...
;       LDB(B0, 1, 0); SCHED; LDA(At, 1, 0); STAGE_A(SA(0, 1), 1, t + 2);
;       WAIT_L(8); BAR; WAIT_L(0); MMA(0, 0, At, B0); BAR; SCHED;
;       LDB(B1, 1, 1); STAGE_B(SB(1, 0), 0, t + 3);
;       BAR; WAIT_L(0); MMA(0, 1, At, B1); BAR;
;       LDA(At, 1, 1); STAGE_A(SA(1, 0), 0, t + 3);
;       BAR; WAIT_L(0); MMA(1, 0, At, B0); BAR; SCHED;
;       STAGE_B(SB(1, 1), 1, t + 3);
;       WAIT_V(6); BAR; MMA(1, 1, At, B1); BAR;
;     }
	s_setprio 0
	ds_read_b128 v[138:141], v162 offset:32768
	ds_read_b128 v[142:145], v162 offset:33792
	ds_read_b128 v[146:149], v162 offset:34816
	ds_read_b128 v[150:153], v162 offset:35840
	ds_read_b128 v[208:211], v162 offset:49152
	ds_read_b128 v[212:215], v162 offset:50176
	ds_read_b128 v[216:219], v162 offset:51200
	ds_read_b128 v[220:223], v162 offset:52224
	ds_read_b128 v[154:157], v175 offset:32768
	ds_read_b128 v[158:161], v175 offset:33792
	ds_read_b128 v[178:181], v175 offset:34816
	ds_read_b128 v[182:185], v175 offset:35840
	ds_read_b128 v[186:189], v175 offset:36864
	ds_read_b128 v[190:193], v175 offset:37888
	ds_read_b128 v[194:197], v175 offset:38912
	ds_read_b128 v[198:201], v175 offset:39936
	s_mov_b32 m0, s77
	s_nop 0
	global_load_lds_dwordx4 v230, s[98:99]
	s_mov_b32 m0, s78
	s_nop 0
	global_load_lds_dwordx4 v231, s[98:99]
	s_waitcnt vmcnt(8) lgkmcnt(0)
	s_setprio 1
	s_barrier
	v_mfma_f32_16x16x32_bf16 v[2:5], v[154:157], v[138:141], v[2:5]
	v_mfma_f32_16x16x32_bf16 v[6:9], v[154:157], v[146:149], v[6:9]
	v_mfma_f32_16x16x32_bf16 v[10:13], v[178:181], v[138:141], v[10:13]
	v_mfma_f32_16x16x32_bf16 v[18:21], v[178:181], v[146:149], v[18:21]
	v_mfma_f32_16x16x32_bf16 v[30:33], v[186:189], v[138:141], v[30:33]
	v_mfma_f32_16x16x32_bf16 v[42:45], v[186:189], v[146:149], v[42:45]
	v_mfma_f32_16x16x32_bf16 v[54:57], v[194:197], v[138:141], v[54:57]
	v_mfma_f32_16x16x32_bf16 v[66:69], v[194:197], v[146:149], v[66:69]
	v_mfma_f32_16x16x32_bf16 v[2:5], v[158:161], v[142:145], v[2:5]
	v_mfma_f32_16x16x32_bf16 v[6:9], v[158:161], v[150:153], v[6:9]
	v_mfma_f32_16x16x32_bf16 v[10:13], v[182:185], v[142:145], v[10:13]
	v_mfma_f32_16x16x32_bf16 v[18:21], v[182:185], v[150:153], v[18:21]
	v_mfma_f32_16x16x32_bf16 v[30:33], v[190:193], v[142:145], v[30:33]
	v_mfma_f32_16x16x32_bf16 v[42:45], v[190:193], v[150:153], v[42:45]
	v_mfma_f32_16x16x32_bf16 v[54:57], v[198:201], v[142:145], v[54:57]
	v_mfma_f32_16x16x32_bf16 v[66:69], v[198:201], v[150:153], v[66:69]
	v_mfma_f32_16x16x32_bf16 v[14:17], v[154:157], v[208:211], v[14:17]
	v_mfma_f32_16x16x32_bf16 v[22:25], v[154:157], v[216:219], v[22:25]
	v_mfma_f32_16x16x32_bf16 v[34:37], v[178:181], v[208:211], v[34:37]
	v_mfma_f32_16x16x32_bf16 v[46:49], v[178:181], v[216:219], v[46:49]
	v_mfma_f32_16x16x32_bf16 v[58:61], v[186:189], v[208:211], v[58:61]
	v_mfma_f32_16x16x32_bf16 v[70:73], v[186:189], v[216:219], v[70:73]
	v_mfma_f32_16x16x32_bf16 v[78:81], v[194:197], v[208:211], v[78:81]
	v_mfma_f32_16x16x32_bf16 v[86:89], v[194:197], v[216:219], v[86:89]
	v_mfma_f32_16x16x32_bf16 v[14:17], v[158:161], v[212:215], v[14:17]
	v_mfma_f32_16x16x32_bf16 v[22:25], v[158:161], v[220:223], v[22:25]
	v_mfma_f32_16x16x32_bf16 v[34:37], v[182:185], v[212:215], v[34:37]
	v_mfma_f32_16x16x32_bf16 v[46:49], v[182:185], v[220:223], v[46:49]
	v_mfma_f32_16x16x32_bf16 v[58:61], v[190:193], v[212:215], v[58:61]
	v_mfma_f32_16x16x32_bf16 v[70:73], v[190:193], v[220:223], v[70:73]
	v_mfma_f32_16x16x32_bf16 v[78:81], v[198:201], v[212:215], v[78:81]
	v_mfma_f32_16x16x32_bf16 v[86:89], v[198:201], v[220:223], v[86:89]
	s_barrier
	s_setprio 0
	ds_read_b128 v[154:157], v175 offset:49152
	ds_read_b128 v[158:161], v175 offset:50176
	ds_read_b128 v[178:181], v175 offset:51200
	ds_read_b128 v[182:185], v175 offset:52224
	ds_read_b128 v[186:189], v175 offset:53248
	ds_read_b128 v[190:193], v175 offset:54272
	ds_read_b128 v[194:197], v175 offset:55296
	ds_read_b128 v[198:201], v175 offset:56320
	s_mov_b32 m0, s35
	s_nop 0
	global_load_lds_dwordx4 v232, s[100:101]
	s_mov_b32 m0, s53
	s_nop 0
	global_load_lds_dwordx4 v233, s[100:101]
	s_mov_b32 m0, s56
	s_nop 0
	global_load_lds_dwordx4 v234, s[98:99]
	s_mov_b32 m0, s57
	s_nop 0
	global_load_lds_dwordx4 v235, s[98:99]
	s_mov_b32 m0, s54
	s_nop 0
	global_load_lds_dwordx4 v236, s[100:101]
	s_mov_b32 m0, s55
	s_nop 0
	global_load_lds_dwordx4 v237, s[100:101]
	s_add_i32 s58, s58, 2
	s_add_u32 s10, s10, 0x100
	s_addc_u32 s11, s11, 0
	s_add_u32 s98, s98, 0x100
	s_addc_u32 s99, s99, 0
	s_add_u32 s100, s100, 0x100
	s_addc_u32 s101, s101, 0
	s_cmp_gt_u32 s58, 27
	s_waitcnt vmcnt(8) lgkmcnt(0)
	s_setprio 1
	s_barrier
	v_mfma_f32_16x16x32_bf16 v[26:29], v[154:157], v[138:141], v[26:29]
	v_mfma_f32_16x16x32_bf16 v[38:41], v[154:157], v[146:149], v[38:41]
	v_mfma_f32_16x16x32_bf16 v[50:53], v[178:181], v[138:141], v[50:53]
	v_mfma_f32_16x16x32_bf16 v[62:65], v[178:181], v[146:149], v[62:65]
	v_mfma_f32_16x16x32_bf16 v[74:77], v[186:189], v[138:141], v[74:77]
	v_mfma_f32_16x16x32_bf16 v[82:85], v[186:189], v[146:149], v[82:85]
	v_mfma_f32_16x16x32_bf16 v[90:93], v[194:197], v[138:141], v[90:93]
	v_mfma_f32_16x16x32_bf16 v[94:97], v[194:197], v[146:149], v[94:97]
	v_mfma_f32_16x16x32_bf16 v[26:29], v[158:161], v[142:145], v[26:29]
	v_mfma_f32_16x16x32_bf16 v[38:41], v[158:161], v[150:153], v[38:41]
	v_mfma_f32_16x16x32_bf16 v[50:53], v[182:185], v[142:145], v[50:53]
	v_mfma_f32_16x16x32_bf16 v[62:65], v[182:185], v[150:153], v[62:65]
	v_mfma_f32_16x16x32_bf16 v[74:77], v[190:193], v[142:145], v[74:77]
	v_mfma_f32_16x16x32_bf16 v[82:85], v[190:193], v[150:153], v[82:85]
	v_mfma_f32_16x16x32_bf16 v[90:93], v[198:201], v[142:145], v[90:93]
	v_mfma_f32_16x16x32_bf16 v[94:97], v[198:201], v[150:153], v[94:97]
	v_mfma_f32_16x16x32_bf16 v[98:101], v[154:157], v[208:211], v[98:101]
	v_mfma_f32_16x16x32_bf16 v[102:105], v[154:157], v[216:219], v[102:105]
	v_mfma_f32_16x16x32_bf16 v[106:109], v[178:181], v[208:211], v[106:109]
	v_mfma_f32_16x16x32_bf16 v[110:113], v[178:181], v[216:219], v[110:113]
	v_mfma_f32_16x16x32_bf16 v[114:117], v[186:189], v[208:211], v[114:117]
	v_mfma_f32_16x16x32_bf16 v[118:121], v[186:189], v[216:219], v[118:121]
	v_mfma_f32_16x16x32_bf16 v[122:125], v[194:197], v[208:211], v[122:125]
	v_mfma_f32_16x16x32_bf16 v[126:129], v[194:197], v[216:219], v[126:129]
	v_mfma_f32_16x16x32_bf16 v[98:101], v[158:161], v[212:215], v[98:101]
	v_mfma_f32_16x16x32_bf16 v[102:105], v[158:161], v[220:223], v[102:105]
	v_mfma_f32_16x16x32_bf16 v[106:109], v[182:185], v[212:215], v[106:109]
	v_mfma_f32_16x16x32_bf16 v[110:113], v[182:185], v[220:223], v[110:113]
	v_mfma_f32_16x16x32_bf16 v[114:117], v[190:193], v[212:215], v[114:117]
	v_mfma_f32_16x16x32_bf16 v[118:121], v[190:193], v[220:223], v[118:121]
	v_mfma_f32_16x16x32_bf16 v[122:125], v[198:201], v[212:215], v[122:125]
	v_mfma_f32_16x16x32_bf16 v[126:129], v[198:201], v[220:223], v[126:129]
	s_barrier
; #define LDA(dst, b, h)                                                                                     \
;   _Pragma("unroll") for (int m = 0; m < 4; ++m) _Pragma("unroll") for (int k = 0; k < 2; ++k) dst[m][k] = \
;       *reinterpret_cast<const bf16x8*>(shmc + aL + (((b) * 2 + (h)) * 16384 + (m * 2 + k) * 1024))
; #define LDB(dst, b, h)                                                                                     \
;   _Pragma("unroll") for (int n = 0; n < 2; ++n) _Pragma("unroll") for (int k = 0; k < 2; ++k) dst[n][k] = \
;       *reinterpret_cast<const bf16x8*>(shmc + bL + (((b) * 2 + (h)) * 16384 + (n * 2 + k) * 1024))
; #define OPAQ asm volatile("" : "+v"(aL), "+v"(bL))
; #define WAIT_V(n) asm volatile("s_waitcnt vmcnt(" #n ")" ::: "memory")
; #define WAIT_L(n) asm volatile("s_waitcnt lgkmcnt(" #n ")" ::: "memory")
; #define BAR __builtin_amdgcn_s_barrier()
; template <int EPI>
; __device__ __forceinline__ void phase_gemm(const Params& p, const GemmDesc& d, char* shmc) {
;     ...
;     {
;       OPAQ;
;       LDB(B0, 0, 0); LDA(At, 0, 0); STAGE_A(SA(1, 1), 1, nt - 1);
;       BAR; WAIT_L(0); MMA(0, 0, At, B0); BAR;
;       LDB(B1, 0, 1); BAR; WAIT_L(0); MMA(0, 1, At, B1); BAR;
;       LDA(At, 0, 1); WAIT_V(4); BAR; WAIT_L(0); MMA(1, 0, At, B0); MMA(1, 1, At, B1); BAR;
;     }
	s_cbranch_scc0 .LBB0_1153
	s_setprio 0
	s_add_u32 s8, s8, 0x80f80
	s_addc_u32 s9, s9, 0
	v_add_u32_e32 v162, 0, v205
	v_add_u32_e32 v175, 0, v204
	s_mov_b32 m0, s59
	ds_read_b128 v[130:133], v162
	ds_read_b128 v[134:137], v162 offset:1024
	ds_read_b128 v[138:141], v162 offset:2048
	ds_read_b128 v[142:145], v162 offset:3072
	ds_read_b128 v[146:149], v175
	ds_read_b128 v[150:153], v175 offset:1024
	ds_read_b128 v[154:157], v175 offset:2048
	ds_read_b128 v[158:161], v175 offset:3072
	ds_read_b128 v[178:181], v175 offset:4096
	ds_read_b128 v[182:185], v175 offset:5120
	ds_read_b128 v[186:189], v175 offset:6144
	ds_read_b128 v[190:193], v175 offset:7168
	global_load_lds_dwordx4 v174, s[8:9]
	s_mov_b32 m0, s68
	s_nop 0
	global_load_lds_dwordx4 v176, s[8:9]
	s_waitcnt vmcnt(8)
	s_barrier
	s_waitcnt lgkmcnt(0)
	s_setprio 1
	s_waitcnt lgkmcnt(0)
	v_mfma_f32_16x16x32_bf16 v[2:5], v[146:149], v[130:133], v[2:5]
	v_mfma_f32_16x16x32_bf16 v[6:9], v[146:149], v[138:141], v[6:9]
	v_mfma_f32_16x16x32_bf16 v[10:13], v[154:157], v[130:133], v[10:13]
	v_mfma_f32_16x16x32_bf16 v[18:21], v[154:157], v[138:141], v[18:21]
	v_mfma_f32_16x16x32_bf16 v[66:69], v[186:189], v[138:141], v[66:69]
	v_mfma_f32_16x16x32_bf16 v[2:5], v[150:153], v[134:137], v[2:5]
	v_mfma_f32_16x16x32_bf16 v[6:9], v[150:153], v[142:145], v[6:9]
	v_mfma_f32_16x16x32_bf16 v[10:13], v[158:161], v[134:137], v[10:13]
	v_mfma_f32_16x16x32_bf16 v[18:21], v[158:161], v[142:145], v[18:21]
	v_mfma_f32_16x16x32_bf16 v[30:33], v[178:181], v[130:133], v[30:33]
	v_mfma_f32_16x16x32_bf16 v[42:45], v[178:181], v[138:141], v[42:45]
	v_mfma_f32_16x16x32_bf16 v[54:57], v[186:189], v[130:133], v[54:57]
	v_mfma_f32_16x16x32_bf16 v[66:69], v[190:193], v[142:145], v[66:69]
	v_mfma_f32_16x16x32_bf16 v[30:33], v[182:185], v[134:137], v[30:33]
	v_mfma_f32_16x16x32_bf16 v[42:45], v[182:185], v[142:145], v[42:45]
	v_mfma_f32_16x16x32_bf16 v[54:57], v[190:193], v[134:137], v[54:57]
	s_setprio 0
	s_barrier
	ds_read_b128 v[194:197], v162 offset:16384
	ds_read_b128 v[198:201], v162 offset:17408
	ds_read_b128 v[208:211], v162 offset:18432
	ds_read_b128 v[212:215], v162 offset:19456
	s_barrier
	s_waitcnt lgkmcnt(0)
	s_setprio 1
	s_waitcnt lgkmcnt(0)
	v_mfma_f32_16x16x32_bf16 v[14:17], v[146:149], v[194:197], v[14:17]
	v_mfma_f32_16x16x32_bf16 v[22:25], v[146:149], v[208:211], v[22:25]
	v_mfma_f32_16x16x32_bf16 v[58:61], v[178:181], v[194:197], v[58:61]
	v_mfma_f32_16x16x32_bf16 v[14:17], v[150:153], v[198:201], v[14:17]
	v_mfma_f32_16x16x32_bf16 v[22:25], v[150:153], v[212:215], v[22:25]
	v_mfma_f32_16x16x32_bf16 v[150:153], v[182:185], v[198:201], v[58:61]
	v_mfma_f32_16x16x32_bf16 v[58:61], v[178:181], v[208:211], v[70:73]
	v_mfma_f32_16x16x32_bf16 v[34:37], v[154:157], v[194:197], v[34:37]
	v_mfma_f32_16x16x32_bf16 v[46:49], v[154:157], v[208:211], v[46:49]
	v_mfma_f32_16x16x32_bf16 v[154:157], v[182:185], v[212:215], v[58:61]
	v_mfma_f32_16x16x32_bf16 v[58:61], v[186:189], v[194:197], v[78:81]
	v_mfma_f32_16x16x32_bf16 v[78:81], v[190:193], v[198:201], v[58:61]
	v_mfma_f32_16x16x32_bf16 v[58:61], v[186:189], v[208:211], v[86:89]
	v_mfma_f32_16x16x32_bf16 v[86:89], v[190:193], v[212:215], v[58:61]
	v_mfma_f32_16x16x32_bf16 v[34:37], v[158:161], v[198:201], v[34:37]
	v_mfma_f32_16x16x32_bf16 v[46:49], v[158:161], v[212:215], v[46:49]
	s_setprio 0
	s_barrier
	s_nop 2
	ds_read_b128 v[58:61], v175 offset:16384
	ds_read_b128 v[70:73], v175 offset:17408
	ds_read_b128 v[146:149], v175 offset:18432
	ds_read_b128 v[158:161], v175 offset:19456
	ds_read_b128 v[178:181], v175 offset:20480
	ds_read_b128 v[182:185], v175 offset:21504
	ds_read_b128 v[186:189], v175 offset:22528
	ds_read_b128 v[190:193], v175 offset:23552
	s_waitcnt vmcnt(4)
	s_barrier
	s_waitcnt lgkmcnt(0)
	s_setprio 1
	s_waitcnt lgkmcnt(0)
	v_mfma_f32_16x16x32_bf16 v[74:77], v[178:181], v[130:133], v[74:77]
	v_mfma_f32_16x16x32_bf16 v[216:219], v[182:185], v[134:137], v[74:77]
	v_mfma_f32_16x16x32_bf16 v[74:77], v[178:181], v[138:141], v[82:85]
	v_mfma_f32_16x16x32_bf16 v[26:29], v[58:61], v[130:133], v[26:29]
	v_mfma_f32_16x16x32_bf16 v[82:85], v[182:185], v[142:145], v[74:77]
	v_mfma_f32_16x16x32_bf16 v[74:77], v[186:189], v[130:133], v[90:93]
	v_mfma_f32_16x16x32_bf16 v[26:29], v[70:73], v[134:137], v[26:29]
	v_mfma_f32_16x16x32_bf16 v[38:41], v[58:61], v[138:141], v[38:41]
	v_mfma_f32_16x16x32_bf16 v[50:53], v[146:149], v[130:133], v[50:53]
	v_mfma_f32_16x16x32_bf16 v[62:65], v[146:149], v[138:141], v[62:65]
	v_mfma_f32_16x16x32_bf16 v[90:93], v[190:193], v[134:137], v[74:77]
	v_mfma_f32_16x16x32_bf16 v[74:77], v[186:189], v[138:141], v[94:97]
	v_mfma_f32_16x16x32_bf16 v[38:41], v[70:73], v[142:145], v[38:41]
	v_mfma_f32_16x16x32_bf16 v[50:53], v[158:161], v[134:137], v[50:53]
	v_mfma_f32_16x16x32_bf16 v[62:65], v[158:161], v[142:145], v[62:65]
	v_mfma_f32_16x16x32_bf16 v[220:223], v[190:193], v[142:145], v[74:77]
	s_setprio 0
	s_setprio 1
	v_mfma_f32_16x16x32_bf16 v[74:77], v[58:61], v[194:197], v[98:101]
	v_mfma_f32_16x16x32_bf16 v[58:61], v[58:61], v[208:211], v[102:105]
	v_mfma_f32_16x16x32_bf16 v[228:231], v[70:73], v[212:215], v[58:61]
	v_mfma_f32_16x16x32_bf16 v[58:61], v[146:149], v[194:197], v[106:109]
	v_mfma_f32_16x16x32_bf16 v[232:235], v[158:161], v[198:201], v[58:61]
	v_mfma_f32_16x16x32_bf16 v[58:61], v[146:149], v[208:211], v[110:113]
	v_mfma_f32_16x16x32_bf16 v[236:239], v[158:161], v[212:215], v[58:61]
	v_mfma_f32_16x16x32_bf16 v[58:61], v[178:181], v[194:197], v[114:117]
	v_mfma_f32_16x16x32_bf16 v[240:243], v[182:185], v[198:201], v[58:61]
	v_mfma_f32_16x16x32_bf16 v[58:61], v[178:181], v[208:211], v[118:121]
	v_mfma_f32_16x16x32_bf16 v[178:181], v[182:185], v[212:215], v[58:61]
	v_mfma_f32_16x16x32_bf16 v[58:61], v[186:189], v[194:197], v[122:125]
	v_mfma_f32_16x16x32_bf16 v[182:185], v[190:193], v[198:201], v[58:61]
	v_mfma_f32_16x16x32_bf16 v[58:61], v[186:189], v[208:211], v[126:129]
	v_mfma_f32_16x16x32_bf16 v[224:227], v[70:73], v[198:201], v[74:77]
	v_mfma_f32_16x16x32_bf16 v[186:189], v[190:193], v[212:215], v[58:61]
	s_setprio 0
	s_barrier
; #define LDA(dst, b, h)                                                                                     \
;   _Pragma("unroll") for (int m = 0; m < 4; ++m) _Pragma("unroll") for (int k = 0; k < 2; ++k) dst[m][k] = \
;       *reinterpret_cast<const bf16x8*>(shmc + aL + (((b) * 2 + (h)) * 16384 + (m * 2 + k) * 1024))
; #define LDB(dst, b, h)                                                                                     \
;   _Pragma("unroll") for (int n = 0; n < 2; ++n) _Pragma("unroll") for (int k = 0; k < 2; ++k) dst[n][k] = \
;       *reinterpret_cast<const bf16x8*>(shmc + bL + (((b) * 2 + (h)) * 16384 + (n * 2 + k) * 1024))
; #define WAIT_V(n) asm volatile("s_waitcnt vmcnt(" #n ")" ::: "memory")
; #define WAIT_L(n) asm volatile("s_waitcnt lgkmcnt(" #n ")" ::: "memory")
; #define BAR __builtin_amdgcn_s_barrier()
; template <int EPI>
; __device__ __forceinline__ void phase_gemm(const Params& p, const GemmDesc& d, char* shmc) {
;     ...
;     {
;       LDB(B0, 1, 0); LDA(At, 1, 0); WAIT_V(2); BAR; WAIT_L(0); MMA(0, 0, At, B0); BAR;
;       LDB(B1, 1, 1); WAIT_V(0); BAR; WAIT_L(0); MMA(0, 1, At, B1); BAR;
;       LDA(At, 1, 1); BAR; WAIT_L(0); MMA(1, 0, At, B0); MMA(1, 1, At, B1); BAR;
;     }
;     if (wr == 0) BAR;
	ds_read_b128 v[98:101], v162 offset:32768
	ds_read_b128 v[106:109], v162 offset:33792
	ds_read_b128 v[190:193], v162 offset:34816
	ds_read_b128 v[194:197], v162 offset:35840
	ds_read_b128 v[58:61], v175 offset:32768
	ds_read_b128 v[70:73], v175 offset:33792
	ds_read_b128 v[114:117], v175 offset:34816
	ds_read_b128 v[122:125], v175 offset:35840
	ds_read_b128 v[130:133], v175 offset:36864
	ds_read_b128 v[138:141], v175 offset:37888
	ds_read_b128 v[198:201], v175 offset:38912
	ds_read_b128 v[208:211], v175 offset:39936
	s_waitcnt vmcnt(2)
	s_barrier
	s_waitcnt lgkmcnt(0)
	s_setprio 1
	s_waitcnt lgkmcnt(0)
	v_mfma_f32_16x16x32_bf16 v[2:5], v[58:61], v[98:101], v[2:5]
	v_mfma_f32_16x16x32_bf16 v[158:161], v[70:73], v[106:109], v[2:5]
	v_mfma_f32_16x16x32_bf16 v[2:5], v[58:61], v[190:193], v[6:9]
	v_mfma_f32_16x16x32_bf16 v[146:149], v[70:73], v[194:197], v[2:5]
	v_mfma_f32_16x16x32_bf16 v[2:5], v[114:117], v[98:101], v[10:13]
	v_mfma_f32_16x16x32_bf16 v[142:145], v[122:125], v[106:109], v[2:5]
	v_mfma_f32_16x16x32_bf16 v[2:5], v[114:117], v[190:193], v[18:21]
	v_mfma_f32_16x16x32_bf16 v[134:137], v[122:125], v[194:197], v[2:5]
	v_mfma_f32_16x16x32_bf16 v[2:5], v[130:133], v[98:101], v[30:33]
	v_mfma_f32_16x16x32_bf16 v[126:129], v[138:141], v[106:109], v[2:5]
	v_mfma_f32_16x16x32_bf16 v[2:5], v[130:133], v[190:193], v[42:45]
	v_mfma_f32_16x16x32_bf16 v[118:121], v[138:141], v[194:197], v[2:5]
	v_mfma_f32_16x16x32_bf16 v[2:5], v[198:201], v[98:101], v[54:57]
	v_mfma_f32_16x16x32_bf16 v[110:113], v[208:211], v[106:109], v[2:5]
	v_mfma_f32_16x16x32_bf16 v[2:5], v[198:201], v[190:193], v[66:69]
	v_mfma_f32_16x16x32_bf16 v[102:105], v[208:211], v[194:197], v[2:5]
	s_setprio 0
	s_barrier
	ds_read_b128 v[30:33], v162 offset:49152
	ds_read_b128 v[42:45], v162 offset:50176
	ds_read_b128 v[54:57], v162 offset:51200
	ds_read_b128 v[212:215], v162 offset:52224
	s_waitcnt vmcnt(0)
	s_barrier
	s_waitcnt lgkmcnt(0)
	s_setprio 1
	s_waitcnt lgkmcnt(0)
	v_mfma_f32_16x16x32_bf16 v[2:5], v[58:61], v[30:33], v[14:17]
	v_mfma_f32_16x16x32_bf16 v[94:97], v[70:73], v[42:45], v[2:5]
	v_mfma_f32_16x16x32_bf16 v[2:5], v[58:61], v[54:57], v[22:25]
	v_mfma_f32_16x16x32_bf16 v[58:61], v[70:73], v[212:215], v[2:5]
	v_mfma_f32_16x16x32_bf16 v[2:5], v[114:117], v[30:33], v[34:37]
	v_mfma_f32_16x16x32_bf16 v[74:77], v[122:125], v[42:45], v[2:5]
	v_mfma_f32_16x16x32_bf16 v[2:5], v[114:117], v[54:57], v[46:49]
	v_mfma_f32_16x16x32_bf16 v[10:13], v[122:125], v[212:215], v[2:5]
	v_mfma_f32_16x16x32_bf16 v[2:5], v[130:133], v[30:33], v[150:153]
	v_mfma_f32_16x16x32_bf16 v[70:73], v[138:141], v[42:45], v[2:5]
	v_mfma_f32_16x16x32_bf16 v[2:5], v[130:133], v[54:57], v[154:157]
	v_mfma_f32_16x16x32_bf16 v[6:9], v[138:141], v[212:215], v[2:5]
	v_mfma_f32_16x16x32_bf16 v[2:5], v[198:201], v[30:33], v[78:81]
	v_mfma_f32_16x16x32_bf16 v[66:69], v[208:211], v[42:45], v[2:5]
	v_mfma_f32_16x16x32_bf16 v[2:5], v[198:201], v[54:57], v[86:89]
	v_mfma_f32_16x16x32_bf16 v[2:5], v[208:211], v[212:215], v[2:5]
	s_setprio 0
	s_barrier
	ds_read_b128 v[14:17], v175 offset:49152
	ds_read_b128 v[18:21], v175 offset:50176
	ds_read_b128 v[22:25], v175 offset:51200
	ds_read_b128 v[34:37], v175 offset:52224
	ds_read_b128 v[46:49], v175 offset:53248
	ds_read_b128 v[78:81], v175 offset:54272
	ds_read_b128 v[198:201], v175 offset:55296
	ds_read_b128 v[208:211], v175 offset:56320
	s_barrier
	s_waitcnt lgkmcnt(0)
	s_setprio 1
	s_waitcnt lgkmcnt(0)
	v_mfma_f32_16x16x32_bf16 v[26:29], v[14:17], v[98:101], v[26:29]
	v_mfma_f32_16x16x32_bf16 v[154:157], v[18:21], v[106:109], v[26:29]
	v_mfma_f32_16x16x32_bf16 v[26:29], v[14:17], v[190:193], v[38:41]
	v_mfma_f32_16x16x32_bf16 v[150:153], v[18:21], v[194:197], v[26:29]
	v_mfma_f32_16x16x32_bf16 v[26:29], v[22:25], v[98:101], v[50:53]
	v_mfma_f32_16x16x32_bf16 v[138:141], v[34:37], v[106:109], v[26:29]
	v_mfma_f32_16x16x32_bf16 v[26:29], v[22:25], v[190:193], v[62:65]
	v_mfma_f32_16x16x32_bf16 v[130:133], v[34:37], v[194:197], v[26:29]
	v_mfma_f32_16x16x32_bf16 v[26:29], v[46:49], v[98:101], v[216:219]
	v_mfma_f32_16x16x32_bf16 v[122:125], v[78:81], v[106:109], v[26:29]
	v_mfma_f32_16x16x32_bf16 v[26:29], v[46:49], v[190:193], v[82:85]
	v_mfma_f32_16x16x32_bf16 v[114:117], v[78:81], v[194:197], v[26:29]
	v_mfma_f32_16x16x32_bf16 v[26:29], v[198:201], v[98:101], v[90:93]
	v_mfma_f32_16x16x32_bf16 v[106:109], v[208:211], v[106:109], v[26:29]
	v_mfma_f32_16x16x32_bf16 v[26:29], v[198:201], v[190:193], v[220:223]
	v_mfma_f32_16x16x32_bf16 v[98:101], v[208:211], v[194:197], v[26:29]
	s_setprio 0
	s_setprio 1
	v_mfma_f32_16x16x32_bf16 v[26:29], v[14:17], v[30:33], v[224:227]
	v_mfma_f32_16x16x32_bf16 v[14:17], v[14:17], v[54:57], v[228:231]
	v_mfma_f32_16x16x32_bf16 v[90:93], v[18:21], v[42:45], v[26:29]
	v_mfma_f32_16x16x32_bf16 v[26:29], v[18:21], v[212:215], v[14:17]
	v_mfma_f32_16x16x32_bf16 v[14:17], v[22:25], v[30:33], v[232:235]
	v_mfma_f32_16x16x32_bf16 v[86:89], v[34:37], v[42:45], v[14:17]
	v_mfma_f32_16x16x32_bf16 v[14:17], v[22:25], v[54:57], v[236:239]
	v_mfma_f32_16x16x32_bf16 v[22:25], v[34:37], v[212:215], v[14:17]
	v_mfma_f32_16x16x32_bf16 v[14:17], v[46:49], v[30:33], v[240:243]
	v_mfma_f32_16x16x32_bf16 v[82:85], v[78:81], v[42:45], v[14:17]
	v_mfma_f32_16x16x32_bf16 v[14:17], v[46:49], v[54:57], v[178:181]
	v_mfma_f32_16x16x32_bf16 v[18:21], v[78:81], v[212:215], v[14:17]
	v_mfma_f32_16x16x32_bf16 v[14:17], v[198:201], v[30:33], v[182:185]
	v_mfma_f32_16x16x32_bf16 v[78:81], v[208:211], v[42:45], v[14:17]
	v_mfma_f32_16x16x32_bf16 v[14:17], v[198:201], v[54:57], v[186:189]
	v_mfma_f32_16x16x32_bf16 v[14:17], v[208:211], v[212:215], v[14:17]
	s_setprio 0
	s_barrier
	s_and_saveexec_b64 s[8:9], s[6:7]
	s_cbranch_execz .LBB0_1156
	s_barrier

; #define LDA(dst, b, h)                                                                                     \
;   _Pragma("unroll") for (int m = 0; m < 4; ++m) _Pragma("unroll") for (int k = 0; k < 2; ++k) dst[m][k] = \
;       *reinterpret_cast<const bf16x8*>(shmc + aL + (((b) * 2 + (h)) * 16384 + (m * 2 + k) * 1024))
; #define LDB(dst, b, h)                                                                                     \
;   _Pragma("unroll") for (int n = 0; n < 2; ++n) _Pragma("unroll") for (int k = 0; k < 2; ++k) dst[n][k] = \
;       *reinterpret_cast<const bf16x8*>(shmc + bL + (((b) * 2 + (h)) * 16384 + (n * 2 + k) * 1024))
; #define OPAQ asm volatile("" : "+v"(aL), "+v"(bL))
; #define WAIT_V(n) asm volatile("s_waitcnt vmcnt(" #n ")" ::: "memory")
; #define WAIT_L(n) asm volatile("s_waitcnt lgkmcnt(" #n ")" ::: "memory")
; #define BAR __builtin_amdgcn_s_barrier()
; #define SCHED __builtin_amdgcn_sched_barrier(0)
; template <int EPI>
; __device__ __forceinline__ void phase_gemm(const Params& p, const GemmDesc& d, char* shmc) {
;     ...
;     for (int t = 0; t < nt - 2; t += 2) {
;       OPAQ;
;       LDB(B0, 0, 0); SCHED; LDA(At, 0, 0); STAGE_A(SA(1, 1), 1, t + 1);
;       WAIT_L(8); BAR; WAIT_L(0); MMA(0, 0, At, B0); BAR; SCHED;
;       LDB(B1, 0, 1); STAGE_B(SB(0, 0), 0, t + 2);
;       BAR; WAIT_L(0); MMA(0, 1, At, B1); BAR;
;       LDA(At, 0, 1); STAGE_A(SA(0, 0), 0, t + 2);
;       BAR; WAIT_L(0); MMA(1, 0, At, B0); BAR; SCHED;
;       STAGE_B(SB(0, 1), 1, t + 2);
;       WAIT_V(6); BAR; MMA(1, 1, At, B1); BAR;
.LBB0_1312:
	s_nop 0
	v_add_u32_e32 v130, 0, v153
	v_add_u32_e32 v141, 0, v152
	s_setprio 0
	ds_read_b128 v[156:159], v130
	ds_read_b128 v[160:163], v130 offset:1024
	ds_read_b128 v[164:167], v130 offset:2048
	ds_read_b128 v[168:171], v130 offset:3072
	ds_read_b128 v[204:207], v130 offset:16384
	ds_read_b128 v[208:211], v130 offset:17408
	ds_read_b128 v[212:215], v130 offset:18432
	ds_read_b128 v[216:219], v130 offset:19456
	ds_read_b128 v[172:175], v141
	ds_read_b128 v[176:179], v141 offset:1024
	ds_read_b128 v[180:183], v141 offset:2048
	ds_read_b128 v[184:187], v141 offset:3072
	ds_read_b128 v[188:191], v141 offset:4096
	ds_read_b128 v[192:195], v141 offset:5120
	ds_read_b128 v[196:199], v141 offset:6144
	ds_read_b128 v[200:203], v141 offset:7168
	s_mov_b32 m0, s59
	s_nop 0
	global_load_lds_dwordx4 v220, s[98:99]
	s_mov_b32 m0, s60
	s_nop 0
	global_load_lds_dwordx4 v221, s[98:99]
	s_waitcnt vmcnt(8) lgkmcnt(0)
	s_setprio 1
	s_barrier
	v_mfma_f32_16x16x32_bf16 v[126:129], v[156:159], v[172:175], v[126:129]
	v_mfma_f32_16x16x32_bf16 v[122:125], v[164:167], v[172:175], v[122:125]
	v_mfma_f32_16x16x32_bf16 v[118:121], v[156:159], v[180:183], v[118:121]
	v_mfma_f32_16x16x32_bf16 v[114:117], v[164:167], v[180:183], v[114:117]
	v_mfma_f32_16x16x32_bf16 v[110:113], v[156:159], v[188:191], v[110:113]
	v_mfma_f32_16x16x32_bf16 v[106:109], v[164:167], v[188:191], v[106:109]
	v_mfma_f32_16x16x32_bf16 v[102:105], v[156:159], v[196:199], v[102:105]
	v_mfma_f32_16x16x32_bf16 v[98:101], v[164:167], v[196:199], v[98:101]
	v_mfma_f32_16x16x32_bf16 v[126:129], v[160:163], v[176:179], v[126:129]
	v_mfma_f32_16x16x32_bf16 v[122:125], v[168:171], v[176:179], v[122:125]
	v_mfma_f32_16x16x32_bf16 v[118:121], v[160:163], v[184:187], v[118:121]
	v_mfma_f32_16x16x32_bf16 v[114:117], v[168:171], v[184:187], v[114:117]
	v_mfma_f32_16x16x32_bf16 v[110:113], v[160:163], v[192:195], v[110:113]
	v_mfma_f32_16x16x32_bf16 v[106:109], v[168:171], v[192:195], v[106:109]
	v_mfma_f32_16x16x32_bf16 v[102:105], v[160:163], v[200:203], v[102:105]
	v_mfma_f32_16x16x32_bf16 v[98:101], v[168:171], v[200:203], v[98:101]
	v_mfma_f32_16x16x32_bf16 v[86:89], v[204:207], v[172:175], v[86:89]
	v_mfma_f32_16x16x32_bf16 v[70:73], v[212:215], v[172:175], v[70:73]
	v_mfma_f32_16x16x32_bf16 v[54:57], v[204:207], v[180:183], v[54:57]
	v_mfma_f32_16x16x32_bf16 v[50:53], v[212:215], v[180:183], v[50:53]
	v_mfma_f32_16x16x32_bf16 v[46:49], v[204:207], v[188:191], v[46:49]
	v_mfma_f32_16x16x32_bf16 v[42:45], v[212:215], v[188:191], v[42:45]
	v_mfma_f32_16x16x32_bf16 v[38:41], v[204:207], v[196:199], v[38:41]
	v_mfma_f32_16x16x32_bf16 v[34:37], v[212:215], v[196:199], v[34:37]
	v_mfma_f32_16x16x32_bf16 v[86:89], v[208:211], v[176:179], v[86:89]
	v_mfma_f32_16x16x32_bf16 v[70:73], v[216:219], v[176:179], v[70:73]
	v_mfma_f32_16x16x32_bf16 v[54:57], v[208:211], v[184:187], v[54:57]
	v_mfma_f32_16x16x32_bf16 v[50:53], v[216:219], v[184:187], v[50:53]
	v_mfma_f32_16x16x32_bf16 v[46:49], v[208:211], v[192:195], v[46:49]
	v_mfma_f32_16x16x32_bf16 v[42:45], v[216:219], v[192:195], v[42:45]
	v_mfma_f32_16x16x32_bf16 v[38:41], v[208:211], v[200:203], v[38:41]
	v_mfma_f32_16x16x32_bf16 v[34:37], v[216:219], v[200:203], v[34:37]
	s_barrier
	s_setprio 0
	ds_read_b128 v[172:175], v141 offset:16384
	ds_read_b128 v[176:179], v141 offset:17408
	ds_read_b128 v[180:183], v141 offset:18432
	ds_read_b128 v[184:187], v141 offset:19456
	ds_read_b128 v[188:191], v141 offset:20480
	ds_read_b128 v[192:195], v141 offset:21504
	ds_read_b128 v[196:199], v141 offset:22528
	ds_read_b128 v[200:203], v141 offset:23552
	s_mov_b32 m0, s34
	s_nop 0
	global_load_lds_dwordx4 v222, s[100:101]
	s_mov_b32 m0, s35
	s_nop 0
	global_load_lds_dwordx4 v223, s[100:101]
	s_mov_b32 m0, s33
	s_nop 0
	global_load_lds_dwordx4 v224, s[98:99]
	s_mov_b32 m0, s46
	s_nop 0
	global_load_lds_dwordx4 v225, s[98:99]
	s_mov_b32 m0, s47
	s_nop 0
	global_load_lds_dwordx4 v226, s[100:101]
	s_mov_b32 m0, s48
	s_nop 0
	global_load_lds_dwordx4 v227, s[100:101]
	s_waitcnt vmcnt(8) lgkmcnt(0)
	s_setprio 1
	s_barrier
	v_mfma_f32_16x16x32_bf16 v[30:33], v[156:159], v[172:175], v[30:33]
	v_mfma_f32_16x16x32_bf16 v[26:29], v[164:167], v[172:175], v[26:29]
	v_mfma_f32_16x16x32_bf16 v[22:25], v[156:159], v[180:183], v[22:25]
	v_mfma_f32_16x16x32_bf16 v[18:21], v[164:167], v[180:183], v[18:21]
	v_mfma_f32_16x16x32_bf16 v[14:17], v[156:159], v[188:191], v[14:17]
	v_mfma_f32_16x16x32_bf16 v[10:13], v[164:167], v[188:191], v[10:13]
	v_mfma_f32_16x16x32_bf16 v[6:9], v[156:159], v[196:199], v[6:9]
	v_mfma_f32_16x16x32_bf16 v[2:5], v[164:167], v[196:199], v[2:5]
	v_mfma_f32_16x16x32_bf16 v[30:33], v[160:163], v[176:179], v[30:33]
	v_mfma_f32_16x16x32_bf16 v[26:29], v[168:171], v[176:179], v[26:29]
	v_mfma_f32_16x16x32_bf16 v[22:25], v[160:163], v[184:187], v[22:25]
	v_mfma_f32_16x16x32_bf16 v[18:21], v[168:171], v[184:187], v[18:21]
	v_mfma_f32_16x16x32_bf16 v[14:17], v[160:163], v[192:195], v[14:17]
	v_mfma_f32_16x16x32_bf16 v[10:13], v[168:171], v[192:195], v[10:13]
	v_mfma_f32_16x16x32_bf16 v[6:9], v[160:163], v[200:203], v[6:9]
	v_mfma_f32_16x16x32_bf16 v[2:5], v[168:171], v[200:203], v[2:5]
	v_mfma_f32_16x16x32_bf16 v[58:61], v[204:207], v[172:175], v[58:61]
	v_mfma_f32_16x16x32_bf16 v[62:65], v[212:215], v[172:175], v[62:65]
	v_mfma_f32_16x16x32_bf16 v[66:69], v[204:207], v[180:183], v[66:69]
	v_mfma_f32_16x16x32_bf16 v[74:77], v[212:215], v[180:183], v[74:77]
	v_mfma_f32_16x16x32_bf16 v[78:81], v[204:207], v[188:191], v[78:81]
	v_mfma_f32_16x16x32_bf16 v[82:85], v[212:215], v[188:191], v[82:85]
	v_mfma_f32_16x16x32_bf16 v[90:93], v[204:207], v[196:199], v[90:93]
	v_mfma_f32_16x16x32_bf16 v[94:97], v[212:215], v[196:199], v[94:97]
	v_mfma_f32_16x16x32_bf16 v[58:61], v[208:211], v[176:179], v[58:61]
	v_mfma_f32_16x16x32_bf16 v[62:65], v[216:219], v[176:179], v[62:65]
	v_mfma_f32_16x16x32_bf16 v[66:69], v[208:211], v[184:187], v[66:69]
	v_mfma_f32_16x16x32_bf16 v[74:77], v[216:219], v[184:187], v[74:77]
	v_mfma_f32_16x16x32_bf16 v[78:81], v[208:211], v[192:195], v[78:81]
	v_mfma_f32_16x16x32_bf16 v[82:85], v[216:219], v[192:195], v[82:85]
	v_mfma_f32_16x16x32_bf16 v[90:93], v[208:211], v[200:203], v[90:93]
	v_mfma_f32_16x16x32_bf16 v[94:97], v[216:219], v[200:203], v[94:97]
	s_barrier
; #define LDA(dst, b, h)                                                                                     \
;   _Pragma("unroll") for (int m = 0; m < 4; ++m) _Pragma("unroll") for (int k = 0; k < 2; ++k) dst[m][k] = \
;       *reinterpret_cast<const bf16x8*>(shmc + aL + (((b) * 2 + (h)) * 16384 + (m * 2 + k) * 1024))
; #define LDB(dst, b, h)                                                                                     \
;   _Pragma("unroll") for (int n = 0; n < 2; ++n) _Pragma("unroll") for (int k = 0; k < 2; ++k) dst[n][k] = \
;       *reinterpret_cast<const bf16x8*>(shmc + bL + (((b) * 2 + (h)) * 16384 + (n * 2 + k) * 1024))
; #define WAIT_V(n) asm volatile("s_waitcnt vmcnt(" #n ")" ::: "memory")
; #define WAIT_L(n) asm volatile("s_waitcnt lgkmcnt(" #n ")" ::: "memory")
; #define BAR __builtin_amdgcn_s_barrier()
; #define SCHED __builtin_amdgcn_sched_barrier(0)
; template <int EPI>
; __device__ __forceinline__ void phase_gemm(const Params& p, const GemmDesc& d, char* shmc) {
;     ...
;       LDB(B0, 1, 0); SCHED; LDA(At, 1, 0); STAGE_A(SA(0, 1), 1, t + 2);
;       WAIT_L(8); BAR; WAIT_L(0); MMA(0, 0, At, B0); BAR; SCHED;
;       LDB(B1, 1, 1); STAGE_B(SB(1, 0), 0, t + 3);
;       BAR; WAIT_L(0); MMA(0, 1, At, B1); BAR;
;       LDA(At, 1, 1); STAGE_A(SA(1, 0), 0, t + 3);
;       BAR; WAIT_L(0); MMA(1, 0, At, B0); BAR; SCHED;
;       STAGE_B(SB(1, 1), 1, t + 3);
;       WAIT_V(6); BAR; MMA(1, 1, At, B1); BAR;
;     }
	s_setprio 0
	ds_read_b128 v[156:159], v130 offset:32768
	ds_read_b128 v[160:163], v130 offset:33792
	ds_read_b128 v[164:167], v130 offset:34816
	ds_read_b128 v[168:171], v130 offset:35840
	ds_read_b128 v[204:207], v130 offset:49152
	ds_read_b128 v[208:211], v130 offset:50176
	ds_read_b128 v[212:215], v130 offset:51200
	ds_read_b128 v[216:219], v130 offset:52224
	ds_read_b128 v[172:175], v141 offset:32768
	ds_read_b128 v[176:179], v141 offset:33792
	ds_read_b128 v[180:183], v141 offset:34816
	ds_read_b128 v[184:187], v141 offset:35840
	ds_read_b128 v[188:191], v141 offset:36864
	ds_read_b128 v[192:195], v141 offset:37888
	ds_read_b128 v[196:199], v141 offset:38912
	ds_read_b128 v[200:203], v141 offset:39936
	s_mov_b32 m0, s49
	s_nop 0
	global_load_lds_dwordx4 v228, s[98:99]
	s_mov_b32 m0, s52
	s_nop 0
	global_load_lds_dwordx4 v229, s[98:99]
	s_waitcnt vmcnt(8) lgkmcnt(0)
	s_setprio 1
	s_barrier
	v_mfma_f32_16x16x32_bf16 v[126:129], v[156:159], v[172:175], v[126:129]
	v_mfma_f32_16x16x32_bf16 v[122:125], v[164:167], v[172:175], v[122:125]
	v_mfma_f32_16x16x32_bf16 v[118:121], v[156:159], v[180:183], v[118:121]
	v_mfma_f32_16x16x32_bf16 v[114:117], v[164:167], v[180:183], v[114:117]
	v_mfma_f32_16x16x32_bf16 v[110:113], v[156:159], v[188:191], v[110:113]
	v_mfma_f32_16x16x32_bf16 v[106:109], v[164:167], v[188:191], v[106:109]
	v_mfma_f32_16x16x32_bf16 v[102:105], v[156:159], v[196:199], v[102:105]
	v_mfma_f32_16x16x32_bf16 v[98:101], v[164:167], v[196:199], v[98:101]
	v_mfma_f32_16x16x32_bf16 v[126:129], v[160:163], v[176:179], v[126:129]
	v_mfma_f32_16x16x32_bf16 v[122:125], v[168:171], v[176:179], v[122:125]
	v_mfma_f32_16x16x32_bf16 v[118:121], v[160:163], v[184:187], v[118:121]
	v_mfma_f32_16x16x32_bf16 v[114:117], v[168:171], v[184:187], v[114:117]
	v_mfma_f32_16x16x32_bf16 v[110:113], v[160:163], v[192:195], v[110:113]
	v_mfma_f32_16x16x32_bf16 v[106:109], v[168:171], v[192:195], v[106:109]
	v_mfma_f32_16x16x32_bf16 v[102:105], v[160:163], v[200:203], v[102:105]
	v_mfma_f32_16x16x32_bf16 v[98:101], v[168:171], v[200:203], v[98:101]
	v_mfma_f32_16x16x32_bf16 v[86:89], v[204:207], v[172:175], v[86:89]
	v_mfma_f32_16x16x32_bf16 v[70:73], v[212:215], v[172:175], v[70:73]
	v_mfma_f32_16x16x32_bf16 v[54:57], v[204:207], v[180:183], v[54:57]
	v_mfma_f32_16x16x32_bf16 v[50:53], v[212:215], v[180:183], v[50:53]
	v_mfma_f32_16x16x32_bf16 v[46:49], v[204:207], v[188:191], v[46:49]
	v_mfma_f32_16x16x32_bf16 v[42:45], v[212:215], v[188:191], v[42:45]
	v_mfma_f32_16x16x32_bf16 v[38:41], v[204:207], v[196:199], v[38:41]
	v_mfma_f32_16x16x32_bf16 v[34:37], v[212:215], v[196:199], v[34:37]
	v_mfma_f32_16x16x32_bf16 v[86:89], v[208:211], v[176:179], v[86:89]
	v_mfma_f32_16x16x32_bf16 v[70:73], v[216:219], v[176:179], v[70:73]
	v_mfma_f32_16x16x32_bf16 v[54:57], v[208:211], v[184:187], v[54:57]
	v_mfma_f32_16x16x32_bf16 v[50:53], v[216:219], v[184:187], v[50:53]
	v_mfma_f32_16x16x32_bf16 v[46:49], v[208:211], v[192:195], v[46:49]
	v_mfma_f32_16x16x32_bf16 v[42:45], v[216:219], v[192:195], v[42:45]
	v_mfma_f32_16x16x32_bf16 v[38:41], v[208:211], v[200:203], v[38:41]
	v_mfma_f32_16x16x32_bf16 v[34:37], v[216:219], v[200:203], v[34:37]
	s_barrier
	s_setprio 0
	ds_read_b128 v[172:175], v141 offset:49152
	ds_read_b128 v[176:179], v141 offset:50176
	ds_read_b128 v[180:183], v141 offset:51200
	ds_read_b128 v[184:187], v141 offset:52224
	ds_read_b128 v[188:191], v141 offset:53248
	ds_read_b128 v[192:195], v141 offset:54272
	ds_read_b128 v[196:199], v141 offset:55296
	ds_read_b128 v[200:203], v141 offset:56320
	s_mov_b32 m0, s53
	s_nop 0
	global_load_lds_dwordx4 v232, s[100:101]
	s_mov_b32 m0, s54
	s_nop 0
	global_load_lds_dwordx4 v233, s[100:101]
	s_mov_b32 m0, s55
	s_nop 0
	global_load_lds_dwordx4 v234, s[98:99]
	s_mov_b32 m0, s56
	s_nop 0
	global_load_lds_dwordx4 v235, s[98:99]
	s_mov_b32 m0, s57
	s_nop 0
	global_load_lds_dwordx4 v236, s[100:101]
	s_mov_b32 m0, s58
	s_nop 0
	global_load_lds_dwordx4 v237, s[100:101]
	s_add_i32 s42, s42, 2
	s_add_u32 s40, s40, 0x100
	s_addc_u32 s41, s41, 0
	s_add_u32 s98, s98, 0x100
	s_addc_u32 s99, s99, 0
	s_add_u32 s100, s100, 0x100
	s_addc_u32 s101, s101, 0
	s_cmpk_gt_u32 s42, 0x53
	s_waitcnt vmcnt(8) lgkmcnt(0)
	s_setprio 1
	s_barrier
	v_mfma_f32_16x16x32_bf16 v[30:33], v[156:159], v[172:175], v[30:33]
	v_mfma_f32_16x16x32_bf16 v[26:29], v[164:167], v[172:175], v[26:29]
	v_mfma_f32_16x16x32_bf16 v[22:25], v[156:159], v[180:183], v[22:25]
	v_mfma_f32_16x16x32_bf16 v[18:21], v[164:167], v[180:183], v[18:21]
	v_mfma_f32_16x16x32_bf16 v[14:17], v[156:159], v[188:191], v[14:17]
	v_mfma_f32_16x16x32_bf16 v[10:13], v[164:167], v[188:191], v[10:13]
	v_mfma_f32_16x16x32_bf16 v[6:9], v[156:159], v[196:199], v[6:9]
	v_mfma_f32_16x16x32_bf16 v[2:5], v[164:167], v[196:199], v[2:5]
	v_mfma_f32_16x16x32_bf16 v[30:33], v[160:163], v[176:179], v[30:33]
	v_mfma_f32_16x16x32_bf16 v[26:29], v[168:171], v[176:179], v[26:29]
	v_mfma_f32_16x16x32_bf16 v[22:25], v[160:163], v[184:187], v[22:25]
	v_mfma_f32_16x16x32_bf16 v[18:21], v[168:171], v[184:187], v[18:21]
	v_mfma_f32_16x16x32_bf16 v[14:17], v[160:163], v[192:195], v[14:17]
	v_mfma_f32_16x16x32_bf16 v[10:13], v[168:171], v[192:195], v[10:13]
	v_mfma_f32_16x16x32_bf16 v[6:9], v[160:163], v[200:203], v[6:9]
	v_mfma_f32_16x16x32_bf16 v[2:5], v[168:171], v[200:203], v[2:5]
	v_mfma_f32_16x16x32_bf16 v[58:61], v[204:207], v[172:175], v[58:61]
	v_mfma_f32_16x16x32_bf16 v[62:65], v[212:215], v[172:175], v[62:65]
	v_mfma_f32_16x16x32_bf16 v[66:69], v[204:207], v[180:183], v[66:69]
	v_mfma_f32_16x16x32_bf16 v[74:77], v[212:215], v[180:183], v[74:77]
	v_mfma_f32_16x16x32_bf16 v[78:81], v[204:207], v[188:191], v[78:81]
	v_mfma_f32_16x16x32_bf16 v[82:85], v[212:215], v[188:191], v[82:85]
	v_mfma_f32_16x16x32_bf16 v[90:93], v[204:207], v[196:199], v[90:93]
	v_mfma_f32_16x16x32_bf16 v[94:97], v[212:215], v[196:199], v[94:97]
	v_mfma_f32_16x16x32_bf16 v[58:61], v[208:211], v[176:179], v[58:61]
	v_mfma_f32_16x16x32_bf16 v[62:65], v[216:219], v[176:179], v[62:65]
	v_mfma_f32_16x16x32_bf16 v[66:69], v[208:211], v[184:187], v[66:69]
	v_mfma_f32_16x16x32_bf16 v[74:77], v[216:219], v[184:187], v[74:77]
	v_mfma_f32_16x16x32_bf16 v[78:81], v[208:211], v[192:195], v[78:81]
	v_mfma_f32_16x16x32_bf16 v[82:85], v[216:219], v[192:195], v[82:85]
	v_mfma_f32_16x16x32_bf16 v[90:93], v[208:211], v[200:203], v[90:93]
	v_mfma_f32_16x16x32_bf16 v[94:97], v[216:219], v[200:203], v[94:97]
	s_barrier
; #define LDA(dst, b, h)                                                                                     \
;   _Pragma("unroll") for (int m = 0; m < 4; ++m) _Pragma("unroll") for (int k = 0; k < 2; ++k) dst[m][k] = \
;       *reinterpret_cast<const bf16x8*>(shmc + aL + (((b) * 2 + (h)) * 16384 + (m * 2 + k) * 1024))
; #define LDB(dst, b, h)                                                                                     \
;   _Pragma("unroll") for (int n = 0; n < 2; ++n) _Pragma("unroll") for (int k = 0; k < 2; ++k) dst[n][k] = \
;       *reinterpret_cast<const bf16x8*>(shmc + bL + (((b) * 2 + (h)) * 16384 + (n * 2 + k) * 1024))
; #define OPAQ asm volatile("" : "+v"(aL), "+v"(bL))
; #define WAIT_V(n) asm volatile("s_waitcnt vmcnt(" #n ")" ::: "memory")
; #define WAIT_L(n) asm volatile("s_waitcnt lgkmcnt(" #n ")" ::: "memory")
; #define BAR __builtin_amdgcn_s_barrier()
; template <int EPI>
; __device__ __forceinline__ void phase_gemm(const Params& p, const GemmDesc& d, char* shmc) {
;     ...
;     {
;       OPAQ;
;       LDB(B0, 0, 0); LDA(At, 0, 0); STAGE_A(SA(1, 1), 1, nt - 1);
;       BAR; WAIT_L(0); MMA(0, 0, At, B0); BAR;
;       LDB(B1, 0, 1); BAR; WAIT_L(0); MMA(0, 1, At, B1); BAR;
;       LDA(At, 0, 1); WAIT_V(4); BAR; WAIT_L(0); MMA(1, 0, At, B0); MMA(1, 1, At, B1); BAR;
;     }
	s_cbranch_scc0 .LBB0_1312
	s_setprio 0
	s_add_u32 s38, s38, 0x162b80
	s_addc_u32 s39, s39, 0
	v_add_u32_e32 v130, 0, v153
	v_add_u32_e32 v141, 0, v152
	s_mov_b32 m0, s59
	ds_read_b128 v[144:147], v130
	ds_read_b128 v[148:151], v130 offset:1024
	ds_read_b128 v[156:159], v130 offset:2048
	ds_read_b128 v[160:163], v130 offset:3072
	ds_read_b128 v[164:167], v141
	ds_read_b128 v[168:171], v141 offset:1024
	ds_read_b128 v[172:175], v141 offset:2048
	ds_read_b128 v[176:179], v141 offset:3072
	ds_read_b128 v[180:183], v141 offset:4096
	ds_read_b128 v[184:187], v141 offset:5120
	ds_read_b128 v[188:191], v141 offset:6144
	ds_read_b128 v[192:195], v141 offset:7168
	global_load_lds_dwordx4 v140, s[38:39]
	s_mov_b32 m0, s60
	s_nop 0
	global_load_lds_dwordx4 v142, s[38:39]
	s_waitcnt vmcnt(8)
	s_barrier
	s_waitcnt lgkmcnt(0)
	s_setprio 1
	s_waitcnt lgkmcnt(0)
	v_mfma_f32_16x16x32_bf16 v[126:129], v[144:147], v[164:167], v[126:129]
	v_mfma_f32_16x16x32_bf16 v[122:125], v[156:159], v[164:167], v[122:125]
	v_mfma_f32_16x16x32_bf16 v[114:117], v[156:159], v[172:175], v[114:117]
	v_mfma_f32_16x16x32_bf16 v[110:113], v[144:147], v[180:183], v[110:113]
	v_mfma_f32_16x16x32_bf16 v[102:105], v[144:147], v[188:191], v[102:105]
	v_mfma_f32_16x16x32_bf16 v[126:129], v[148:151], v[168:171], v[126:129]
	v_mfma_f32_16x16x32_bf16 v[122:125], v[160:163], v[168:171], v[122:125]
	v_mfma_f32_16x16x32_bf16 v[118:121], v[144:147], v[172:175], v[118:121]
	v_mfma_f32_16x16x32_bf16 v[114:117], v[160:163], v[176:179], v[114:117]
	v_mfma_f32_16x16x32_bf16 v[110:113], v[148:151], v[184:187], v[110:113]
	v_mfma_f32_16x16x32_bf16 v[106:109], v[156:159], v[180:183], v[106:109]
	v_mfma_f32_16x16x32_bf16 v[102:105], v[148:151], v[192:195], v[102:105]
	v_mfma_f32_16x16x32_bf16 v[98:101], v[156:159], v[188:191], v[98:101]
	v_mfma_f32_16x16x32_bf16 v[196:199], v[148:151], v[176:179], v[118:121]
	v_mfma_f32_16x16x32_bf16 v[200:203], v[160:163], v[184:187], v[106:109]
	v_mfma_f32_16x16x32_bf16 v[204:207], v[160:163], v[192:195], v[98:101]
	s_setprio 0
	s_barrier
	s_nop 2
	ds_read_b128 v[98:101], v130 offset:16384
	ds_read_b128 v[106:109], v130 offset:17408
	ds_read_b128 v[118:121], v130 offset:18432
	ds_read_b128 v[208:211], v130 offset:19456
	s_barrier
	s_waitcnt lgkmcnt(0)
	s_setprio 1
	s_waitcnt lgkmcnt(0)
	v_mfma_f32_16x16x32_bf16 v[86:89], v[98:101], v[164:167], v[86:89]
	v_mfma_f32_16x16x32_bf16 v[70:73], v[118:121], v[164:167], v[70:73]
	v_mfma_f32_16x16x32_bf16 v[54:57], v[98:101], v[172:175], v[54:57]
	v_mfma_f32_16x16x32_bf16 v[50:53], v[118:121], v[172:175], v[50:53]
	v_mfma_f32_16x16x32_bf16 v[46:49], v[98:101], v[180:183], v[46:49]
	v_mfma_f32_16x16x32_bf16 v[42:45], v[118:121], v[180:183], v[42:45]
	v_mfma_f32_16x16x32_bf16 v[38:41], v[98:101], v[188:191], v[38:41]
	v_mfma_f32_16x16x32_bf16 v[34:37], v[118:121], v[188:191], v[34:37]
	v_mfma_f32_16x16x32_bf16 v[86:89], v[106:109], v[168:171], v[86:89]
	v_mfma_f32_16x16x32_bf16 v[70:73], v[208:211], v[168:171], v[70:73]
	v_mfma_f32_16x16x32_bf16 v[54:57], v[106:109], v[176:179], v[54:57]
	v_mfma_f32_16x16x32_bf16 v[50:53], v[208:211], v[176:179], v[50:53]
	v_mfma_f32_16x16x32_bf16 v[46:49], v[106:109], v[184:187], v[46:49]
	v_mfma_f32_16x16x32_bf16 v[42:45], v[208:211], v[184:187], v[42:45]
	v_mfma_f32_16x16x32_bf16 v[38:41], v[106:109], v[192:195], v[38:41]
	v_mfma_f32_16x16x32_bf16 v[34:37], v[208:211], v[192:195], v[34:37]
	s_setprio 0
	s_barrier
	ds_read_b128 v[164:167], v141 offset:16384
	ds_read_b128 v[168:171], v141 offset:17408
	ds_read_b128 v[172:175], v141 offset:18432
	ds_read_b128 v[176:179], v141 offset:19456
	ds_read_b128 v[180:183], v141 offset:20480
	ds_read_b128 v[184:187], v141 offset:21504
	ds_read_b128 v[188:191], v141 offset:22528
	ds_read_b128 v[192:195], v141 offset:23552
	s_waitcnt vmcnt(4)
	s_barrier
	s_waitcnt lgkmcnt(0)
	s_setprio 1
	s_waitcnt lgkmcnt(0)
	v_mfma_f32_16x16x32_bf16 v[30:33], v[144:147], v[164:167], v[30:33]
	v_mfma_f32_16x16x32_bf16 v[26:29], v[156:159], v[164:167], v[26:29]
	v_mfma_f32_16x16x32_bf16 v[22:25], v[144:147], v[172:175], v[22:25]
	v_mfma_f32_16x16x32_bf16 v[18:21], v[156:159], v[172:175], v[18:21]
	v_mfma_f32_16x16x32_bf16 v[14:17], v[144:147], v[180:183], v[14:17]
	v_mfma_f32_16x16x32_bf16 v[10:13], v[156:159], v[180:183], v[10:13]
	v_mfma_f32_16x16x32_bf16 v[6:9], v[144:147], v[188:191], v[6:9]
	v_mfma_f32_16x16x32_bf16 v[2:5], v[156:159], v[188:191], v[2:5]
	v_mfma_f32_16x16x32_bf16 v[30:33], v[148:151], v[168:171], v[30:33]
	v_mfma_f32_16x16x32_bf16 v[26:29], v[160:163], v[168:171], v[26:29]
	v_mfma_f32_16x16x32_bf16 v[22:25], v[148:151], v[176:179], v[22:25]
	v_mfma_f32_16x16x32_bf16 v[18:21], v[160:163], v[176:179], v[18:21]
	v_mfma_f32_16x16x32_bf16 v[14:17], v[148:151], v[184:187], v[14:17]
	v_mfma_f32_16x16x32_bf16 v[10:13], v[160:163], v[184:187], v[10:13]
	v_mfma_f32_16x16x32_bf16 v[6:9], v[148:151], v[192:195], v[6:9]
	v_mfma_f32_16x16x32_bf16 v[2:5], v[160:163], v[192:195], v[2:5]
	s_setprio 0
	s_setprio 1
	v_mfma_f32_16x16x32_bf16 v[62:65], v[118:121], v[164:167], v[62:65]
	v_mfma_f32_16x16x32_bf16 v[144:147], v[208:211], v[168:171], v[62:65]
	v_mfma_f32_16x16x32_bf16 v[62:65], v[98:101], v[172:175], v[66:69]
	v_mfma_f32_16x16x32_bf16 v[148:151], v[106:109], v[176:179], v[62:65]
	v_mfma_f32_16x16x32_bf16 v[62:65], v[118:121], v[172:175], v[74:77]
	v_mfma_f32_16x16x32_bf16 v[156:159], v[208:211], v[176:179], v[62:65]
	v_mfma_f32_16x16x32_bf16 v[62:65], v[98:101], v[180:183], v[78:81]
	v_mfma_f32_16x16x32_bf16 v[160:163], v[106:109], v[184:187], v[62:65]
	v_mfma_f32_16x16x32_bf16 v[62:65], v[118:121], v[180:183], v[82:85]
	v_mfma_f32_16x16x32_bf16 v[58:61], v[98:101], v[164:167], v[58:61]
	v_mfma_f32_16x16x32_bf16 v[164:167], v[208:211], v[184:187], v[62:65]
	v_mfma_f32_16x16x32_bf16 v[62:65], v[98:101], v[188:191], v[90:93]
	v_mfma_f32_16x16x32_bf16 v[58:61], v[106:109], v[168:171], v[58:61]
	v_mfma_f32_16x16x32_bf16 v[168:171], v[106:109], v[192:195], v[62:65]
	v_mfma_f32_16x16x32_bf16 v[62:65], v[118:121], v[188:191], v[94:97]
	v_mfma_f32_16x16x32_bf16 v[172:175], v[208:211], v[192:195], v[62:65]
	s_setprio 0
	s_barrier
; #define LDA(dst, b, h)                                                                                     \
;   _Pragma("unroll") for (int m = 0; m < 4; ++m) _Pragma("unroll") for (int k = 0; k < 2; ++k) dst[m][k] = \
;       *reinterpret_cast<const bf16x8*>(shmc + aL + (((b) * 2 + (h)) * 16384 + (m * 2 + k) * 1024))
; #define LDB(dst, b, h)                                                                                     \
;   _Pragma("unroll") for (int n = 0; n < 2; ++n) _Pragma("unroll") for (int k = 0; k < 2; ++k) dst[n][k] = \
;       *reinterpret_cast<const bf16x8*>(shmc + bL + (((b) * 2 + (h)) * 16384 + (n * 2 + k) * 1024))
; #define WAIT_V(n) asm volatile("s_waitcnt vmcnt(" #n ")" ::: "memory")
; #define WAIT_L(n) asm volatile("s_waitcnt lgkmcnt(" #n ")" ::: "memory")
; #define BAR __builtin_amdgcn_s_barrier()
; template <int EPI>
; __device__ __forceinline__ void phase_gemm(const Params& p, const GemmDesc& d, char* shmc) {
;     ...
;     {
;       LDB(B0, 1, 0); LDA(At, 1, 0); WAIT_V(2); BAR; WAIT_L(0); MMA(0, 0, At, B0); BAR;
;       LDB(B1, 1, 1); WAIT_V(0); BAR; WAIT_L(0); MMA(0, 1, At, B1); BAR;
;       LDA(At, 1, 1); BAR; WAIT_L(0); MMA(1, 0, At, B0); MMA(1, 1, At, B1); BAR;
;     }
;     if (wr == 0) BAR;
	ds_read_b128 v[176:179], v130 offset:32768
	ds_read_b128 v[180:183], v130 offset:33792
	ds_read_b128 v[184:187], v130 offset:34816
	ds_read_b128 v[188:191], v130 offset:35840
	s_nop 0
	ds_read_b128 v[62:65], v141 offset:32768
	ds_read_b128 v[78:81], v141 offset:33792
	ds_read_b128 v[94:97], v141 offset:34816
	ds_read_b128 v[192:195], v141 offset:35840
	ds_read_b128 v[208:211], v141 offset:36864
	ds_read_b128 v[212:215], v141 offset:37888
	ds_read_b128 v[216:219], v141 offset:38912
	ds_read_b128 v[220:223], v141 offset:39936
	s_waitcnt vmcnt(2)
	s_barrier
	s_waitcnt lgkmcnt(0)
	s_setprio 1
	s_waitcnt lgkmcnt(0)
	v_mfma_f32_16x16x32_bf16 v[66:69], v[176:179], v[62:65], v[126:129]
	v_mfma_f32_16x16x32_bf16 v[126:129], v[180:183], v[78:81], v[66:69]
	v_mfma_f32_16x16x32_bf16 v[66:69], v[184:187], v[62:65], v[122:125]
	v_mfma_f32_16x16x32_bf16 v[118:121], v[188:191], v[78:81], v[66:69]
	v_mfma_f32_16x16x32_bf16 v[66:69], v[176:179], v[94:97], v[196:199]
	v_mfma_f32_16x16x32_bf16 v[106:109], v[180:183], v[192:195], v[66:69]
	v_mfma_f32_16x16x32_bf16 v[66:69], v[184:187], v[94:97], v[114:117]
	v_mfma_f32_16x16x32_bf16 v[98:101], v[188:191], v[192:195], v[66:69]
	v_mfma_f32_16x16x32_bf16 v[66:69], v[176:179], v[208:211], v[110:113]
	v_mfma_f32_16x16x32_bf16 v[90:93], v[180:183], v[212:215], v[66:69]
	v_mfma_f32_16x16x32_bf16 v[66:69], v[184:187], v[208:211], v[200:203]
	v_mfma_f32_16x16x32_bf16 v[82:85], v[188:191], v[212:215], v[66:69]
	v_mfma_f32_16x16x32_bf16 v[66:69], v[176:179], v[216:219], v[102:105]
	v_mfma_f32_16x16x32_bf16 v[74:77], v[180:183], v[220:223], v[66:69]
	v_mfma_f32_16x16x32_bf16 v[66:69], v[184:187], v[216:219], v[204:207]
	v_mfma_f32_16x16x32_bf16 v[66:69], v[188:191], v[220:223], v[66:69]
	s_setprio 0
	s_barrier
	ds_read_b128 v[196:199], v130 offset:49152
	ds_read_b128 v[200:203], v130 offset:50176
	ds_read_b128 v[204:207], v130 offset:51200
	ds_read_b128 v[224:227], v130 offset:52224
	s_waitcnt vmcnt(0)
	s_barrier
	s_waitcnt lgkmcnt(0)
	s_setprio 1
	s_waitcnt lgkmcnt(0)
	v_mfma_f32_16x16x32_bf16 v[86:89], v[196:199], v[62:65], v[86:89]
	v_mfma_f32_16x16x32_bf16 v[62:65], v[204:207], v[62:65], v[70:73]
	v_mfma_f32_16x16x32_bf16 v[54:57], v[196:199], v[94:97], v[54:57]
	v_mfma_f32_16x16x32_bf16 v[50:53], v[204:207], v[94:97], v[50:53]
	v_mfma_f32_16x16x32_bf16 v[46:49], v[196:199], v[208:211], v[46:49]
	v_mfma_f32_16x16x32_bf16 v[42:45], v[204:207], v[208:211], v[42:45]
	v_mfma_f32_16x16x32_bf16 v[38:41], v[196:199], v[216:219], v[38:41]
	v_mfma_f32_16x16x32_bf16 v[34:37], v[204:207], v[216:219], v[34:37]
	v_mfma_f32_16x16x32_bf16 v[122:125], v[200:203], v[78:81], v[86:89]
	v_mfma_f32_16x16x32_bf16 v[114:117], v[224:227], v[78:81], v[62:65]
	v_mfma_f32_16x16x32_bf16 v[110:113], v[200:203], v[192:195], v[54:57]
	v_mfma_f32_16x16x32_bf16 v[102:105], v[224:227], v[192:195], v[50:53]
	v_mfma_f32_16x16x32_bf16 v[94:97], v[200:203], v[212:215], v[46:49]
	v_mfma_f32_16x16x32_bf16 v[86:89], v[224:227], v[212:215], v[42:45]
	v_mfma_f32_16x16x32_bf16 v[78:81], v[200:203], v[220:223], v[38:41]
	v_mfma_f32_16x16x32_bf16 v[70:73], v[224:227], v[220:223], v[34:37]
	s_setprio 0
	s_barrier
	s_nop 0
	ds_read_b128 v[34:37], v141 offset:49152
	ds_read_b128 v[42:45], v141 offset:50176
	ds_read_b128 v[192:195], v141 offset:51200
	ds_read_b128 v[208:211], v141 offset:52224
	ds_read_b128 v[212:215], v141 offset:53248
	ds_read_b128 v[216:219], v141 offset:54272
	ds_read_b128 v[220:223], v141 offset:55296
	ds_read_b128 v[228:231], v141 offset:56320
	s_barrier
	s_waitcnt lgkmcnt(0)
	s_setprio 1
	s_waitcnt lgkmcnt(0)
	v_mfma_f32_16x16x32_bf16 v[30:33], v[176:179], v[34:37], v[30:33]
	v_mfma_f32_16x16x32_bf16 v[26:29], v[184:187], v[34:37], v[26:29]
	v_mfma_f32_16x16x32_bf16 v[22:25], v[176:179], v[192:195], v[22:25]
	v_mfma_f32_16x16x32_bf16 v[18:21], v[184:187], v[192:195], v[18:21]
	v_mfma_f32_16x16x32_bf16 v[14:17], v[176:179], v[212:215], v[14:17]
	v_mfma_f32_16x16x32_bf16 v[10:13], v[184:187], v[212:215], v[10:13]
	v_mfma_f32_16x16x32_bf16 v[6:9], v[176:179], v[220:223], v[6:9]
	v_mfma_f32_16x16x32_bf16 v[2:5], v[184:187], v[220:223], v[2:5]
	v_mfma_f32_16x16x32_bf16 v[62:65], v[180:183], v[42:45], v[30:33]
	v_mfma_f32_16x16x32_bf16 v[54:57], v[188:191], v[42:45], v[26:29]
	v_mfma_f32_16x16x32_bf16 v[46:49], v[180:183], v[208:211], v[22:25]
	v_mfma_f32_16x16x32_bf16 v[38:41], v[188:191], v[208:211], v[18:21]
	v_mfma_f32_16x16x32_bf16 v[30:33], v[180:183], v[216:219], v[14:17]
	v_mfma_f32_16x16x32_bf16 v[22:25], v[188:191], v[216:219], v[10:13]
	v_mfma_f32_16x16x32_bf16 v[14:17], v[180:183], v[228:231], v[6:9]
	v_mfma_f32_16x16x32_bf16 v[6:9], v[188:191], v[228:231], v[2:5]
	s_setprio 0
	s_setprio 1
	v_mfma_f32_16x16x32_bf16 v[2:5], v[196:199], v[34:37], v[58:61]
	v_mfma_f32_16x16x32_bf16 v[58:61], v[200:203], v[42:45], v[2:5]
	v_mfma_f32_16x16x32_bf16 v[2:5], v[204:207], v[34:37], v[144:147]
	v_mfma_f32_16x16x32_bf16 v[50:53], v[224:227], v[42:45], v[2:5]
	v_mfma_f32_16x16x32_bf16 v[2:5], v[196:199], v[192:195], v[148:151]
	v_mfma_f32_16x16x32_bf16 v[42:45], v[200:203], v[208:211], v[2:5]
	v_mfma_f32_16x16x32_bf16 v[2:5], v[204:207], v[192:195], v[156:159]
	v_mfma_f32_16x16x32_bf16 v[34:37], v[224:227], v[208:211], v[2:5]
	v_mfma_f32_16x16x32_bf16 v[2:5], v[196:199], v[212:215], v[160:163]
	v_mfma_f32_16x16x32_bf16 v[26:29], v[200:203], v[216:219], v[2:5]
	v_mfma_f32_16x16x32_bf16 v[2:5], v[204:207], v[212:215], v[164:167]
	v_mfma_f32_16x16x32_bf16 v[18:21], v[224:227], v[216:219], v[2:5]
	v_mfma_f32_16x16x32_bf16 v[2:5], v[196:199], v[220:223], v[168:171]
	v_mfma_f32_16x16x32_bf16 v[10:13], v[200:203], v[228:231], v[2:5]
	v_mfma_f32_16x16x32_bf16 v[2:5], v[204:207], v[220:223], v[172:175]
	v_mfma_f32_16x16x32_bf16 v[2:5], v[224:227], v[228:231], v[2:5]
	s_setprio 0
	s_barrier
	s_and_saveexec_b64 s[38:39], s[4:5]
	s_cbranch_execz .LBB0_1315
	s_barrier
